# GEMM loop edges: s_setprio 1 hoisted before the barrier, duplicate lgkmcnt(0) dropped, barrier moved directly after the last MFMA of each segment
# speedup vs baseline: 1.0164x; 1.0108x over previous
.LBB0_37:
	s_add_u32 s7, s46, 0xffea0080
	s_addc_u32 s78, s47, -1
	s_add_i32 s87, 0, 0x10000
	v_add_u32_e32 v132, s87, v135
	ds_read_b128 v[138:141], v132
	ds_read_b128 v[142:145], v132 offset:1024
	ds_read_b128 v[148:151], v132 offset:2048
	ds_read_b128 v[152:155], v132 offset:3072
	s_cmpk_eq_i32 s6, 0x54
	s_cselect_b32 s79, s43, s78
	s_cselect_b32 s78, s42, s7
	s_cselect_b32 s89, s45, s9
	s_cselect_b32 s88, s44, s8
	v_lshl_add_u64 v[132:133], s[46:47], 0, v[130:131]
	s_add_i32 m0, s54, 0xc000
	ds_read_b128 v[156:159], v136
	ds_read_b128 v[160:163], v136 offset:1024
	ds_read_b128 v[164:167], v136 offset:2048
	ds_read_b128 v[168:171], v136 offset:3072
	ds_read_b128 v[172:175], v136 offset:4096
	ds_read_b128 v[176:179], v136 offset:5120
	ds_read_b128 v[180:183], v136 offset:6144
	ds_read_b128 v[184:187], v136 offset:7168
	global_load_lds_dwordx4 v[132:133], off
	v_lshl_add_u64 v[132:133], v[132:133], 0, s[26:27]
	s_add_i32 m0, s54, 0xe000
	s_nop 0
	global_load_lds_dwordx4 v[132:133], off
	s_waitcnt lgkmcnt(8)
	s_setprio 1
	s_barrier
	s_waitcnt lgkmcnt(0)
	v_mfma_f32_16x16x32_bf16 v[126:129], v[138:141], v[156:159], v[126:129]
	v_mfma_f32_16x16x32_bf16 v[122:125], v[148:151], v[156:159], v[122:125]
	v_mfma_f32_16x16x32_bf16 v[118:121], v[138:141], v[164:167], v[118:121]
	v_mfma_f32_16x16x32_bf16 v[110:113], v[148:151], v[164:167], v[110:113]
	v_mfma_f32_16x16x32_bf16 v[102:105], v[138:141], v[172:175], v[102:105]
	v_mfma_f32_16x16x32_bf16 v[94:97], v[148:151], v[172:175], v[94:97]
	v_mfma_f32_16x16x32_bf16 v[86:89], v[138:141], v[180:183], v[86:89]
	v_mfma_f32_16x16x32_bf16 v[78:81], v[148:151], v[180:183], v[78:81]
	v_mfma_f32_16x16x32_bf16 v[126:129], v[142:145], v[160:163], v[126:129]
	v_mfma_f32_16x16x32_bf16 v[122:125], v[152:155], v[160:163], v[122:125]
	v_mfma_f32_16x16x32_bf16 v[118:121], v[142:145], v[168:171], v[118:121]
	v_mfma_f32_16x16x32_bf16 v[110:113], v[152:155], v[168:171], v[110:113]
	v_mfma_f32_16x16x32_bf16 v[102:105], v[142:145], v[176:179], v[102:105]
	v_mfma_f32_16x16x32_bf16 v[94:97], v[152:155], v[176:179], v[94:97]
	v_mfma_f32_16x16x32_bf16 v[86:89], v[142:145], v[184:187], v[86:89]
	v_mfma_f32_16x16x32_bf16 v[78:81], v[152:155], v[184:187], v[78:81]
	s_barrier
	s_setprio 0
	s_add_i32 s7, 0, 0x14000
	v_add_u32_e32 v132, s7, v135
	s_add_i32 s87, s87, s53
	ds_read_b128 v[188:191], v132
	ds_read_b128 v[192:195], v132 offset:1024
	ds_read_b128 v[196:199], v132 offset:2048
	ds_read_b128 v[200:203], v132 offset:3072
	v_lshl_add_u64 v[132:133], s[88:89], 0, v[0:1]
	s_mov_b32 m0, s87
	v_lshl_add_u64 v[204:205], v[132:133], 0, s[26:27]
	global_load_lds_dwordx4 v[132:133], off
	s_add_i32 m0, s87, 0x2000
	s_nop 0
	global_load_lds_dwordx4 v[204:205], off
	s_setprio 1
	s_barrier
	s_waitcnt lgkmcnt(0)
	v_mfma_f32_16x16x32_bf16 v[114:117], v[188:191], v[156:159], v[114:117]
	v_mfma_f32_16x16x32_bf16 v[106:109], v[196:199], v[156:159], v[106:109]
	v_mfma_f32_16x16x32_bf16 v[98:101], v[188:191], v[164:167], v[98:101]
	v_mfma_f32_16x16x32_bf16 v[90:93], v[196:199], v[164:167], v[90:93]
	v_mfma_f32_16x16x32_bf16 v[82:85], v[188:191], v[172:175], v[82:85]
	v_mfma_f32_16x16x32_bf16 v[74:77], v[196:199], v[172:175], v[74:77]
	v_mfma_f32_16x16x32_bf16 v[70:73], v[188:191], v[180:183], v[70:73]
	v_mfma_f32_16x16x32_bf16 v[66:69], v[196:199], v[180:183], v[66:69]
	v_mfma_f32_16x16x32_bf16 v[114:117], v[192:195], v[160:163], v[114:117]
	v_mfma_f32_16x16x32_bf16 v[106:109], v[200:203], v[160:163], v[106:109]
	v_mfma_f32_16x16x32_bf16 v[98:101], v[192:195], v[168:171], v[98:101]
	v_mfma_f32_16x16x32_bf16 v[90:93], v[200:203], v[168:171], v[90:93]
	v_mfma_f32_16x16x32_bf16 v[82:85], v[192:195], v[176:179], v[82:85]
	v_mfma_f32_16x16x32_bf16 v[74:77], v[200:203], v[176:179], v[74:77]
	v_mfma_f32_16x16x32_bf16 v[70:73], v[192:195], v[184:187], v[70:73]
	v_mfma_f32_16x16x32_bf16 v[66:69], v[200:203], v[184:187], v[66:69]
	s_barrier
	s_setprio 0
	s_mov_b32 m0, s54
	v_lshl_add_u64 v[204:205], s[78:79], 0, v[0:1]
	ds_read_b128 v[156:159], v136 offset:16384
	ds_read_b128 v[160:163], v136 offset:17408
	ds_read_b128 v[164:167], v136 offset:18432
	ds_read_b128 v[168:171], v136 offset:19456
	ds_read_b128 v[172:175], v136 offset:20480
	ds_read_b128 v[176:179], v136 offset:21504
	ds_read_b128 v[180:183], v136 offset:22528
	ds_read_b128 v[184:187], v136 offset:23552
	global_load_lds_dwordx4 v[204:205], off
	v_lshl_add_u64 v[206:207], v[204:205], 0, s[26:27]
	s_mov_b32 m0, s55
	s_nop 0
	global_load_lds_dwordx4 v[206:207], off
	s_setprio 1
	s_barrier
	s_waitcnt lgkmcnt(0)
	v_mfma_f32_16x16x32_bf16 v[62:65], v[138:141], v[156:159], v[62:65]
	v_mfma_f32_16x16x32_bf16 v[58:61], v[148:151], v[156:159], v[58:61]
	v_mfma_f32_16x16x32_bf16 v[54:57], v[138:141], v[164:167], v[54:57]
	v_mfma_f32_16x16x32_bf16 v[46:49], v[148:151], v[164:167], v[46:49]
	v_mfma_f32_16x16x32_bf16 v[38:41], v[138:141], v[172:175], v[38:41]
	v_mfma_f32_16x16x32_bf16 v[30:33], v[148:151], v[172:175], v[30:33]
	v_mfma_f32_16x16x32_bf16 v[22:25], v[138:141], v[180:183], v[22:25]
	v_mfma_f32_16x16x32_bf16 v[14:17], v[148:151], v[180:183], v[14:17]
	v_mfma_f32_16x16x32_bf16 v[62:65], v[142:145], v[160:163], v[62:65]
	v_mfma_f32_16x16x32_bf16 v[58:61], v[152:155], v[160:163], v[58:61]
	v_mfma_f32_16x16x32_bf16 v[54:57], v[142:145], v[168:171], v[54:57]
	v_mfma_f32_16x16x32_bf16 v[46:49], v[152:155], v[168:171], v[46:49]
	v_mfma_f32_16x16x32_bf16 v[38:41], v[142:145], v[176:179], v[38:41]
	v_mfma_f32_16x16x32_bf16 v[30:33], v[152:155], v[176:179], v[30:33]
	v_mfma_f32_16x16x32_bf16 v[22:25], v[142:145], v[184:187], v[22:25]
	v_mfma_f32_16x16x32_bf16 v[14:17], v[152:155], v[184:187], v[14:17]
	s_barrier
	s_setprio 0
	s_add_i32 s7, s7, s53
	v_lshl_add_u64 v[138:139], v[132:133], 0, s[28:29]
	s_mov_b32 m0, s7
	s_nop 0
	global_load_lds_dwordx4 v[138:139], off
	v_lshl_add_u64 v[138:139], v[132:133], 0, s[30:31]
	s_add_i32 m0, s7, 0x2000
	s_nop 0
	global_load_lds_dwordx4 v[138:139], off
	s_waitcnt vmcnt(6)
	s_setprio 1
	s_barrier
	v_mfma_f32_16x16x32_bf16 v[50:53], v[188:191], v[156:159], v[50:53]
	v_mfma_f32_16x16x32_bf16 v[42:45], v[196:199], v[156:159], v[42:45]
	v_mfma_f32_16x16x32_bf16 v[34:37], v[188:191], v[164:167], v[34:37]
	v_mfma_f32_16x16x32_bf16 v[26:29], v[196:199], v[164:167], v[26:29]
	v_mfma_f32_16x16x32_bf16 v[18:21], v[188:191], v[172:175], v[18:21]
	v_mfma_f32_16x16x32_bf16 v[10:13], v[196:199], v[172:175], v[10:13]
	v_mfma_f32_16x16x32_bf16 v[6:9], v[188:191], v[180:183], v[6:9]
	v_mfma_f32_16x16x32_bf16 v[2:5], v[196:199], v[180:183], v[2:5]
	v_mfma_f32_16x16x32_bf16 v[50:53], v[192:195], v[160:163], v[50:53]
	v_mfma_f32_16x16x32_bf16 v[42:45], v[200:203], v[160:163], v[42:45]
	v_mfma_f32_16x16x32_bf16 v[34:37], v[192:195], v[168:171], v[34:37]
	v_mfma_f32_16x16x32_bf16 v[26:29], v[200:203], v[168:171], v[26:29]
	v_mfma_f32_16x16x32_bf16 v[18:21], v[192:195], v[176:179], v[18:21]
	v_mfma_f32_16x16x32_bf16 v[10:13], v[200:203], v[176:179], v[10:13]
	v_mfma_f32_16x16x32_bf16 v[6:9], v[192:195], v[184:187], v[6:9]
	v_mfma_f32_16x16x32_bf16 v[2:5], v[200:203], v[184:187], v[2:5]
	s_barrier
	s_setprio 0
	s_add_i32 s7, 0, 0x18000
	v_add_u32_e32 v137, s7, v135
	ds_read_b128 v[138:141], v137
	ds_read_b128 v[142:145], v137 offset:1024
	ds_read_b128 v[148:151], v137 offset:2048
	ds_read_b128 v[152:155], v137 offset:3072
	s_mov_b32 m0, s56
	v_lshl_add_u64 v[188:189], v[204:205], 0, s[28:29]
	ds_read_b128 v[156:159], v136 offset:32768
	ds_read_b128 v[160:163], v136 offset:33792
	ds_read_b128 v[164:167], v136 offset:34816
	ds_read_b128 v[168:171], v136 offset:35840
	ds_read_b128 v[172:175], v136 offset:36864
	ds_read_b128 v[176:179], v136 offset:37888
	ds_read_b128 v[180:183], v136 offset:38912
	ds_read_b128 v[184:187], v136 offset:39936
	global_load_lds_dwordx4 v[188:189], off
	v_lshl_add_u64 v[188:189], v[204:205], 0, s[30:31]
	s_mov_b32 m0, s57
	s_nop 0
	global_load_lds_dwordx4 v[188:189], off
	s_waitcnt lgkmcnt(8)
	s_setprio 1
	s_barrier
	s_waitcnt lgkmcnt(0)
	v_mfma_f32_16x16x32_bf16 v[126:129], v[138:141], v[156:159], v[126:129]
	v_mfma_f32_16x16x32_bf16 v[122:125], v[148:151], v[156:159], v[122:125]
	v_mfma_f32_16x16x32_bf16 v[118:121], v[138:141], v[164:167], v[118:121]
	v_mfma_f32_16x16x32_bf16 v[110:113], v[148:151], v[164:167], v[110:113]
	v_mfma_f32_16x16x32_bf16 v[102:105], v[138:141], v[172:175], v[102:105]
	v_mfma_f32_16x16x32_bf16 v[94:97], v[148:151], v[172:175], v[94:97]
	v_mfma_f32_16x16x32_bf16 v[86:89], v[138:141], v[180:183], v[86:89]
	v_mfma_f32_16x16x32_bf16 v[78:81], v[148:151], v[180:183], v[78:81]
	v_mfma_f32_16x16x32_bf16 v[126:129], v[142:145], v[160:163], v[126:129]
	v_mfma_f32_16x16x32_bf16 v[122:125], v[152:155], v[160:163], v[122:125]
	v_mfma_f32_16x16x32_bf16 v[118:121], v[142:145], v[168:171], v[118:121]
	v_mfma_f32_16x16x32_bf16 v[110:113], v[152:155], v[168:171], v[110:113]
	v_mfma_f32_16x16x32_bf16 v[102:105], v[142:145], v[176:179], v[102:105]
	v_mfma_f32_16x16x32_bf16 v[94:97], v[152:155], v[176:179], v[94:97]
	v_mfma_f32_16x16x32_bf16 v[86:89], v[142:145], v[184:187], v[86:89]
	v_mfma_f32_16x16x32_bf16 v[78:81], v[152:155], v[184:187], v[78:81]
	s_barrier
	s_setprio 0
	s_add_i32 s78, 0, 0x1c000
	s_add_i32 s7, s7, s53
	v_add_u32_e32 v137, s78, v135
	v_lshl_add_u64 v[206:207], v[132:133], 0, s[34:35]
	s_mov_b32 m0, s7
	ds_read_b128 v[188:191], v137
	ds_read_b128 v[192:195], v137 offset:1024
	ds_read_b128 v[196:199], v137 offset:2048
	ds_read_b128 v[200:203], v137 offset:3072
	global_load_lds_dwordx4 v[206:207], off
	v_lshl_add_u64 v[206:207], v[132:133], 0, s[36:37]
	s_add_i32 m0, s7, 0x2000
	s_nop 0
	global_load_lds_dwordx4 v[206:207], off
	s_setprio 1
	s_barrier
	s_waitcnt lgkmcnt(0)
	v_mfma_f32_16x16x32_bf16 v[114:117], v[188:191], v[156:159], v[114:117]
	v_mfma_f32_16x16x32_bf16 v[106:109], v[196:199], v[156:159], v[106:109]
	v_mfma_f32_16x16x32_bf16 v[98:101], v[188:191], v[164:167], v[98:101]
	v_mfma_f32_16x16x32_bf16 v[90:93], v[196:199], v[164:167], v[90:93]
	v_mfma_f32_16x16x32_bf16 v[82:85], v[188:191], v[172:175], v[82:85]
	v_mfma_f32_16x16x32_bf16 v[74:77], v[196:199], v[172:175], v[74:77]
	v_mfma_f32_16x16x32_bf16 v[70:73], v[188:191], v[180:183], v[70:73]
	v_mfma_f32_16x16x32_bf16 v[66:69], v[196:199], v[180:183], v[66:69]
	v_mfma_f32_16x16x32_bf16 v[114:117], v[192:195], v[160:163], v[114:117]
	v_mfma_f32_16x16x32_bf16 v[106:109], v[200:203], v[160:163], v[106:109]
	v_mfma_f32_16x16x32_bf16 v[98:101], v[192:195], v[168:171], v[98:101]
	v_mfma_f32_16x16x32_bf16 v[90:93], v[200:203], v[168:171], v[90:93]
	v_mfma_f32_16x16x32_bf16 v[82:85], v[192:195], v[176:179], v[82:85]
	v_mfma_f32_16x16x32_bf16 v[74:77], v[200:203], v[176:179], v[74:77]
	v_mfma_f32_16x16x32_bf16 v[70:73], v[192:195], v[184:187], v[70:73]
	v_mfma_f32_16x16x32_bf16 v[66:69], v[200:203], v[184:187], v[66:69]
	s_barrier
	s_setprio 0
	s_mov_b32 m0, s62
	v_lshl_add_u64 v[206:207], v[204:205], 0, s[34:35]
	ds_read_b128 v[156:159], v136 offset:49152
	ds_read_b128 v[160:163], v136 offset:50176
	ds_read_b128 v[164:167], v136 offset:51200
	ds_read_b128 v[168:171], v136 offset:52224
	ds_read_b128 v[172:175], v136 offset:53248
	ds_read_b128 v[176:179], v136 offset:54272
	ds_read_b128 v[180:183], v136 offset:55296
	ds_read_b128 v[184:187], v136 offset:56320
	global_load_lds_dwordx4 v[206:207], off
	v_lshl_add_u64 v[204:205], v[204:205], 0, s[36:37]
	s_mov_b32 m0, s63
	s_nop 0
	global_load_lds_dwordx4 v[204:205], off
	s_setprio 1
	s_barrier
	s_waitcnt lgkmcnt(0)
	v_mfma_f32_16x16x32_bf16 v[62:65], v[138:141], v[156:159], v[62:65]
	v_mfma_f32_16x16x32_bf16 v[58:61], v[148:151], v[156:159], v[58:61]
	v_mfma_f32_16x16x32_bf16 v[54:57], v[138:141], v[164:167], v[54:57]
	v_mfma_f32_16x16x32_bf16 v[46:49], v[148:151], v[164:167], v[46:49]
	v_mfma_f32_16x16x32_bf16 v[38:41], v[138:141], v[172:175], v[38:41]
	v_mfma_f32_16x16x32_bf16 v[30:33], v[148:151], v[172:175], v[30:33]
	v_mfma_f32_16x16x32_bf16 v[22:25], v[138:141], v[180:183], v[22:25]
	v_mfma_f32_16x16x32_bf16 v[14:17], v[148:151], v[180:183], v[14:17]
	v_mfma_f32_16x16x32_bf16 v[62:65], v[142:145], v[160:163], v[62:65]
	v_mfma_f32_16x16x32_bf16 v[58:61], v[152:155], v[160:163], v[58:61]
	v_mfma_f32_16x16x32_bf16 v[54:57], v[142:145], v[168:171], v[54:57]
	v_mfma_f32_16x16x32_bf16 v[46:49], v[152:155], v[168:171], v[46:49]
	v_mfma_f32_16x16x32_bf16 v[38:41], v[142:145], v[176:179], v[38:41]
	v_mfma_f32_16x16x32_bf16 v[30:33], v[152:155], v[176:179], v[30:33]
	v_mfma_f32_16x16x32_bf16 v[22:25], v[142:145], v[184:187], v[22:25]
	v_mfma_f32_16x16x32_bf16 v[14:17], v[152:155], v[184:187], v[14:17]
	s_barrier
	s_setprio 0
	s_add_i32 s7, s78, s53
	v_lshl_add_u64 v[138:139], v[132:133], 0, s[18:19]
	s_mov_b32 m0, s7
	v_lshl_add_u64 v[132:133], v[132:133], 0, s[14:15]
	global_load_lds_dwordx4 v[138:139], off
	s_add_i32 m0, s7, 0x2000
	s_nop 0
	global_load_lds_dwordx4 v[132:133], off
	s_waitcnt vmcnt(6)
	s_setprio 1
	s_barrier
	v_mfma_f32_16x16x32_bf16 v[50:53], v[188:191], v[156:159], v[50:53]
	v_mfma_f32_16x16x32_bf16 v[42:45], v[196:199], v[156:159], v[42:45]
	v_mfma_f32_16x16x32_bf16 v[34:37], v[188:191], v[164:167], v[34:37]
	v_mfma_f32_16x16x32_bf16 v[26:29], v[196:199], v[164:167], v[26:29]
	v_mfma_f32_16x16x32_bf16 v[18:21], v[188:191], v[172:175], v[18:21]
	v_mfma_f32_16x16x32_bf16 v[10:13], v[196:199], v[172:175], v[10:13]
	v_mfma_f32_16x16x32_bf16 v[6:9], v[188:191], v[180:183], v[6:9]
	v_mfma_f32_16x16x32_bf16 v[2:5], v[196:199], v[180:183], v[2:5]
	v_mfma_f32_16x16x32_bf16 v[50:53], v[192:195], v[160:163], v[50:53]
	v_mfma_f32_16x16x32_bf16 v[42:45], v[200:203], v[160:163], v[42:45]
	v_mfma_f32_16x16x32_bf16 v[34:37], v[192:195], v[168:171], v[34:37]
	v_mfma_f32_16x16x32_bf16 v[26:29], v[200:203], v[168:171], v[26:29]
	v_mfma_f32_16x16x32_bf16 v[18:21], v[192:195], v[176:179], v[18:21]
	v_mfma_f32_16x16x32_bf16 v[10:13], v[200:203], v[176:179], v[10:13]
	v_mfma_f32_16x16x32_bf16 v[6:9], v[192:195], v[184:187], v[6:9]
	v_mfma_f32_16x16x32_bf16 v[2:5], v[200:203], v[184:187], v[2:5]
	s_barrier
	s_setprio 0
	s_add_i32 s6, s6, 2
	s_add_u32 s8, s8, 0x100
	s_addc_u32 s9, s9, 0
	s_add_u32 s46, s46, 0x100
	s_addc_u32 s47, s47, 0
	s_cmpk_gt_u32 s6, 0x55
	s_cbranch_scc0 .LBB0_37
	v_mov_b32_e32 v137, v134
	s_lshl_b32 s6, s86, 8
	v_ashrrev_i32_e32 v132, 2, v137
	s_or_b32 s6, s6, s59
	v_and_b32_e32 v132, -4, v132
	v_add_u32_e32 v132, s6, v132
	s_lshl_b32 s6, s85, 8
	s_add_i32 s6, s6, s58
	v_and_or_b32 v188, v137, 15, s6
	v_ashrrev_i32_e32 v189, 31, v188
	v_ashrrev_i32_e32 v133, 31, v132
	v_lshlrev_b64 v[206:207], 13, v[188:189]
	v_or_b32_e32 v156, 16, v188
	v_or_b32_e32 v172, 32, v188
	v_or_b32_e32 v188, 48, v188
	v_lshlrev_b64 v[132:133], 2, v[132:133]
	v_ashrrev_i32_e32 v157, 31, v156
	v_ashrrev_i32_e32 v173, 31, v172
	v_ashrrev_i32_e32 v189, 31, v188
	v_lshl_add_u64 v[204:205], s[4:5], 0, v[132:133]
	v_lshlrev_b64 v[208:209], 13, v[156:157]
	v_lshlrev_b64 v[210:211], 13, v[172:173]
	v_lshlrev_b64 v[212:213], 13, v[188:189]
	v_lshl_add_u64 v[152:153], v[204:205], 0, v[206:207]
	v_lshl_add_u64 v[168:169], v[204:205], 0, v[208:209]
	v_lshl_add_u64 v[184:185], v[204:205], 0, v[210:211]
	v_lshl_add_u64 v[200:201], v[204:205], 0, v[212:213]
	global_load_dwordx4 v[138:141], v[152:153], off
	global_load_dwordx4 v[142:145], v[152:153], off offset:64
	global_load_dwordx4 v[148:151], v[152:153], off offset:512
	s_nop 0
	global_load_dwordx4 v[152:155], v[152:153], off offset:576
	s_nop 0
	global_load_dwordx4 v[156:159], v[168:169], off
	global_load_dwordx4 v[160:163], v[168:169], off offset:64
	global_load_dwordx4 v[164:167], v[168:169], off offset:512
	s_nop 0
	global_load_dwordx4 v[168:171], v[168:169], off offset:576
	s_nop 0
	global_load_dwordx4 v[172:175], v[184:185], off
	global_load_dwordx4 v[176:179], v[184:185], off offset:64
	global_load_dwordx4 v[180:183], v[184:185], off offset:512
	s_nop 0
	global_load_dwordx4 v[184:187], v[184:185], off offset:576
	s_nop 0
	global_load_dwordx4 v[188:191], v[200:201], off
	global_load_dwordx4 v[192:195], v[200:201], off offset:64
	global_load_dwordx4 v[196:199], v[200:201], off offset:512
	s_nop 0
	global_load_dwordx4 v[200:203], v[200:201], off offset:576
	s_waitcnt vmcnt(0) lgkmcnt(0)
	v_pk_fma_f32 v[126:127], v[126:127], 0.5, v[138:139] op_sel_hi:[1,0,1]
	v_lshl_add_u64 v[138:139], s[4:5], 0, v[206:207]
	v_lshl_add_u64 v[138:139], v[138:139], 0, v[132:133]
	v_pk_fma_f32 v[116:117], v[116:117], 0.5, v[150:151] op_sel_hi:[1,0,1]
	v_pk_fma_f32 v[114:115], v[114:115], 0.5, v[148:149] op_sel_hi:[1,0,1]
	global_store_dwordx4 v[138:139], v[114:117], off offset:512
	v_pk_fma_f32 v[100:101], v[100:101], 0.5, v[166:167] op_sel_hi:[1,0,1]
	v_pk_fma_f32 v[98:99], v[98:99], 0.5, v[164:165] op_sel_hi:[1,0,1]
	v_lshl_add_u64 v[114:115], s[4:5], 0, v[208:209]
	v_lshl_add_u64 v[114:115], v[114:115], 0, v[132:133]
	global_store_dwordx4 v[114:115], v[98:101], off offset:512
	v_pk_fma_f32 v[84:85], v[84:85], 0.5, v[182:183] op_sel_hi:[1,0,1]
	v_pk_fma_f32 v[82:83], v[82:83], 0.5, v[180:181] op_sel_hi:[1,0,1]
	v_lshl_add_u64 v[98:99], s[4:5], 0, v[210:211]
	v_lshl_add_u64 v[98:99], v[98:99], 0, v[132:133]
	v_pk_fma_f32 v[108:109], v[108:109], 0.5, v[154:155] op_sel_hi:[1,0,1]
	v_pk_fma_f32 v[106:107], v[106:107], 0.5, v[152:153] op_sel_hi:[1,0,1]
	v_pk_fma_f32 v[92:93], v[92:93], 0.5, v[170:171] op_sel_hi:[1,0,1]
	v_pk_fma_f32 v[90:91], v[90:91], 0.5, v[168:169] op_sel_hi:[1,0,1]
	global_store_dwordx4 v[98:99], v[82:85], off offset:512
	v_pk_fma_f32 v[76:77], v[76:77], 0.5, v[186:187] op_sel_hi:[1,0,1]
	v_pk_fma_f32 v[74:75], v[74:75], 0.5, v[184:185] op_sel_hi:[1,0,1]
	v_lshl_add_u64 v[82:83], s[4:5], 0, v[212:213]
	global_store_dwordx4 v[138:139], v[106:109], off offset:576
	global_store_dwordx4 v[114:115], v[90:93], off offset:576
	global_store_dwordx4 v[98:99], v[74:77], off offset:576
	v_pk_fma_f32 v[108:109], v[120:121], 0.5, v[158:159] op_sel_hi:[1,0,1]
	v_pk_fma_f32 v[106:107], v[118:119], 0.5, v[156:157] op_sel_hi:[1,0,1]
	v_pk_fma_f32 v[92:93], v[104:105], 0.5, v[174:175] op_sel_hi:[1,0,1]
	v_pk_fma_f32 v[90:91], v[102:103], 0.5, v[172:173] op_sel_hi:[1,0,1]
	v_pk_fma_f32 v[76:77], v[88:89], 0.5, v[190:191] op_sel_hi:[1,0,1]
	v_pk_fma_f32 v[74:75], v[86:87], 0.5, v[188:189] op_sel_hi:[1,0,1]
	v_lshl_add_u64 v[82:83], v[82:83], 0, v[132:133]
	v_pk_fma_f32 v[128:129], v[128:129], 0.5, v[140:141] op_sel_hi:[1,0,1]
	v_pk_fma_f32 v[124:125], v[124:125], 0.5, v[144:145] op_sel_hi:[1,0,1]
	v_pk_fma_f32 v[122:123], v[122:123], 0.5, v[142:143] op_sel_hi:[1,0,1]
	global_store_dwordx4 v[114:115], v[106:109], off
	global_store_dwordx4 v[98:99], v[90:93], off
	global_store_dwordx4 v[82:83], v[74:77], off
	v_pk_fma_f32 v[108:109], v[112:113], 0.5, v[162:163] op_sel_hi:[1,0,1]
	v_pk_fma_f32 v[106:107], v[110:111], 0.5, v[160:161] op_sel_hi:[1,0,1]
	v_pk_fma_f32 v[92:93], v[96:97], 0.5, v[178:179] op_sel_hi:[1,0,1]
	v_pk_fma_f32 v[90:91], v[94:95], 0.5, v[176:177] op_sel_hi:[1,0,1]
	v_pk_fma_f32 v[76:77], v[80:81], 0.5, v[194:195] op_sel_hi:[1,0,1]
	v_pk_fma_f32 v[74:75], v[78:79], 0.5, v[192:193] op_sel_hi:[1,0,1]
	v_pk_fma_f32 v[72:73], v[72:73], 0.5, v[198:199] op_sel_hi:[1,0,1]
	v_pk_fma_f32 v[70:71], v[70:71], 0.5, v[196:197] op_sel_hi:[1,0,1]
	v_pk_fma_f32 v[68:69], v[68:69], 0.5, v[202:203] op_sel_hi:[1,0,1]
	v_pk_fma_f32 v[66:67], v[66:67], 0.5, v[200:201] op_sel_hi:[1,0,1]
	global_store_dwordx4 v[138:139], v[126:129], off
	global_store_dwordx4 v[138:139], v[122:125], off offset:64
	global_store_dwordx4 v[114:115], v[106:109], off offset:64
	global_store_dwordx4 v[98:99], v[90:93], off offset:64
	global_store_dwordx4 v[82:83], v[74:77], off offset:64
	global_store_dwordx4 v[82:83], v[70:73], off offset:512
	global_store_dwordx4 v[82:83], v[66:69], off offset:576
	s_mov_b64 s[6:7], 0x120000
	v_lshl_add_u64 v[140:141], v[206:207], 0, s[6:7]
	s_mov_b64 s[6:7], 0x140000
	v_lshl_add_u64 v[138:139], v[206:207], 0, s[0:1]
	v_lshl_add_u64 v[142:143], v[206:207], 0, s[6:7]
	v_lshl_add_u64 v[144:145], v[206:207], 0, s[28:29]
	v_lshl_add_u64 v[78:79], v[204:205], 0, v[138:139]
	v_lshl_add_u64 v[94:95], v[204:205], 0, v[140:141]
	v_lshl_add_u64 v[110:111], v[204:205], 0, v[142:143]
	v_lshl_add_u64 v[126:127], v[204:205], 0, v[144:145]
	global_load_dwordx4 v[66:69], v[78:79], off
	global_load_dwordx4 v[70:73], v[78:79], off offset:64
	global_load_dwordx4 v[74:77], v[78:79], off offset:512
	s_nop 0
	global_load_dwordx4 v[78:81], v[78:79], off offset:576
	s_nop 0
	global_load_dwordx4 v[82:85], v[94:95], off
	global_load_dwordx4 v[86:89], v[94:95], off offset:64
	global_load_dwordx4 v[90:93], v[94:95], off offset:512
	s_nop 0
	global_load_dwordx4 v[94:97], v[94:95], off offset:576
	s_nop 0
	global_load_dwordx4 v[98:101], v[110:111], off
	global_load_dwordx4 v[102:105], v[110:111], off offset:64
	global_load_dwordx4 v[106:109], v[110:111], off offset:512
	s_nop 0
	global_load_dwordx4 v[110:113], v[110:111], off offset:576
	s_nop 0
	global_load_dwordx4 v[114:117], v[126:127], off
	global_load_dwordx4 v[118:121], v[126:127], off offset:64
	global_load_dwordx4 v[122:125], v[126:127], off offset:512
	s_nop 0
	global_load_dwordx4 v[126:129], v[126:127], off offset:576
	s_waitcnt vmcnt(0) lgkmcnt(0)
	v_pk_fma_f32 v[62:63], v[62:63], 0.5, v[66:67] op_sel_hi:[1,0,1]
	v_lshl_add_u64 v[66:67], s[4:5], 0, v[138:139]
	v_lshl_add_u64 v[66:67], v[66:67], 0, v[132:133]
	v_pk_fma_f32 v[52:53], v[52:53], 0.5, v[76:77] op_sel_hi:[1,0,1]
	v_pk_fma_f32 v[50:51], v[50:51], 0.5, v[74:75] op_sel_hi:[1,0,1]
	global_store_dwordx4 v[66:67], v[50:53], off offset:512
	v_pk_fma_f32 v[36:37], v[36:37], 0.5, v[92:93] op_sel_hi:[1,0,1]
	v_pk_fma_f32 v[34:35], v[34:35], 0.5, v[90:91] op_sel_hi:[1,0,1]
	v_lshl_add_u64 v[50:51], s[4:5], 0, v[140:141]
	v_lshl_add_u64 v[50:51], v[50:51], 0, v[132:133]
	global_store_dwordx4 v[50:51], v[34:37], off offset:512
	v_pk_fma_f32 v[20:21], v[20:21], 0.5, v[108:109] op_sel_hi:[1,0,1]
	v_pk_fma_f32 v[18:19], v[18:19], 0.5, v[106:107] op_sel_hi:[1,0,1]
	v_lshl_add_u64 v[34:35], s[4:5], 0, v[142:143]
	v_lshl_add_u64 v[34:35], v[34:35], 0, v[132:133]
	v_pk_fma_f32 v[44:45], v[44:45], 0.5, v[80:81] op_sel_hi:[1,0,1]
	v_pk_fma_f32 v[42:43], v[42:43], 0.5, v[78:79] op_sel_hi:[1,0,1]
	v_pk_fma_f32 v[28:29], v[28:29], 0.5, v[96:97] op_sel_hi:[1,0,1]
	v_pk_fma_f32 v[26:27], v[26:27], 0.5, v[94:95] op_sel_hi:[1,0,1]
	global_store_dwordx4 v[34:35], v[18:21], off offset:512
	v_pk_fma_f32 v[12:13], v[12:13], 0.5, v[112:113] op_sel_hi:[1,0,1]
	v_pk_fma_f32 v[10:11], v[10:11], 0.5, v[110:111] op_sel_hi:[1,0,1]
	v_lshl_add_u64 v[18:19], s[4:5], 0, v[144:145]
	global_store_dwordx4 v[66:67], v[42:45], off offset:576
	global_store_dwordx4 v[50:51], v[26:29], off offset:576
	global_store_dwordx4 v[34:35], v[10:13], off offset:576
	v_pk_fma_f32 v[44:45], v[56:57], 0.5, v[84:85] op_sel_hi:[1,0,1]
	v_pk_fma_f32 v[42:43], v[54:55], 0.5, v[82:83] op_sel_hi:[1,0,1]
	v_pk_fma_f32 v[28:29], v[40:41], 0.5, v[100:101] op_sel_hi:[1,0,1]
	v_pk_fma_f32 v[26:27], v[38:39], 0.5, v[98:99] op_sel_hi:[1,0,1]
	v_pk_fma_f32 v[12:13], v[24:25], 0.5, v[116:117] op_sel_hi:[1,0,1]
	v_pk_fma_f32 v[10:11], v[22:23], 0.5, v[114:115] op_sel_hi:[1,0,1]
	v_lshl_add_u64 v[18:19], v[18:19], 0, v[132:133]
	v_pk_fma_f32 v[64:65], v[64:65], 0.5, v[68:69] op_sel_hi:[1,0,1]
	v_pk_fma_f32 v[60:61], v[60:61], 0.5, v[72:73] op_sel_hi:[1,0,1]
	v_pk_fma_f32 v[58:59], v[58:59], 0.5, v[70:71] op_sel_hi:[1,0,1]
	global_store_dwordx4 v[50:51], v[42:45], off
	global_store_dwordx4 v[34:35], v[26:29], off
	global_store_dwordx4 v[18:19], v[10:13], off
	v_pk_fma_f32 v[44:45], v[48:49], 0.5, v[88:89] op_sel_hi:[1,0,1]
	v_pk_fma_f32 v[42:43], v[46:47], 0.5, v[86:87] op_sel_hi:[1,0,1]
	v_pk_fma_f32 v[28:29], v[32:33], 0.5, v[104:105] op_sel_hi:[1,0,1]
	v_pk_fma_f32 v[26:27], v[30:31], 0.5, v[102:103] op_sel_hi:[1,0,1]
	v_pk_fma_f32 v[12:13], v[16:17], 0.5, v[120:121] op_sel_hi:[1,0,1]
	v_pk_fma_f32 v[10:11], v[14:15], 0.5, v[118:119] op_sel_hi:[1,0,1]
	v_pk_fma_f32 v[8:9], v[8:9], 0.5, v[124:125] op_sel_hi:[1,0,1]
	v_pk_fma_f32 v[6:7], v[6:7], 0.5, v[122:123] op_sel_hi:[1,0,1]
	v_pk_fma_f32 v[4:5], v[4:5], 0.5, v[128:129] op_sel_hi:[1,0,1]
	v_pk_fma_f32 v[2:3], v[2:3], 0.5, v[126:127] op_sel_hi:[1,0,1]
	global_store_dwordx4 v[66:67], v[62:65], off
	global_store_dwordx4 v[66:67], v[58:61], off offset:64
	global_store_dwordx4 v[50:51], v[42:45], off offset:64
	global_store_dwordx4 v[34:35], v[26:29], off offset:64
	global_store_dwordx4 v[18:19], v[10:13], off offset:64
	global_store_dwordx4 v[18:19], v[6:9], off offset:512
	global_store_dwordx4 v[18:19], v[2:5], off offset:576
	s_and_b64 vcc, exec, s[40:41]
	s_mov_b32 s85, s10
	s_mov_b32 s86, s11
	s_mov_b64 s[8:9], s[44:45]
	s_mov_b64 s[6:7], s[42:43]
	s_movk_i32 s89, 0x37ff
	s_mov_b32 s88, 0x16000
	s_cbranch_vccz .LBB0_30
	s_waitcnt vmcnt(0)
	s_cmpk_gt_u32 s48, 0xff
	s_cbranch_scc1 .LBB0_41
	s_barrier

.LBB0_51:
	s_add_u32 s8, s6, 0x100
	s_addc_u32 s9, s7, 0
	s_add_i32 s90, 0, 0x10000
	v_add_u32_e32 v134, s90, v137
	ds_read_b128 v[140:143], v134
	ds_read_b128 v[148:151], v134 offset:1024
	ds_read_b128 v[152:155], v134 offset:2048
	ds_read_b128 v[156:159], v134 offset:3072
	s_cmp_eq_u32 s87, 28
	s_cselect_b32 s79, s43, s9
	s_cselect_b32 s78, s42, s8
	s_cselect_b32 s89, s47, s86
	s_cselect_b32 s88, s46, s41
	v_lshl_add_u64 v[134:135], s[6:7], 0, v[132:133]
	v_lshl_add_u64 v[144:145], v[134:135], 0, s[16:17]
	s_add_i32 m0, s49, 0xc000
	ds_read_b128 v[160:163], v138
	ds_read_b128 v[164:167], v138 offset:1024
	ds_read_b128 v[168:171], v138 offset:2048
	ds_read_b128 v[172:175], v138 offset:3072
	ds_read_b128 v[176:179], v138 offset:4096
	ds_read_b128 v[180:183], v138 offset:5120
	ds_read_b128 v[184:187], v138 offset:6144
	ds_read_b128 v[188:191], v138 offset:7168
	global_load_lds_dwordx4 v[144:145], off
	v_lshl_add_u64 v[134:135], v[134:135], 0, s[80:81]
	s_add_i32 m0, s49, 0xe000
	s_nop 0
	global_load_lds_dwordx4 v[134:135], off
	s_waitcnt lgkmcnt(8)
	s_setprio 1
	s_barrier
	s_waitcnt lgkmcnt(0)
	v_mfma_f32_16x16x32_bf16 v[126:129], v[140:143], v[160:163], v[126:129]
	v_mfma_f32_16x16x32_bf16 v[118:121], v[152:155], v[160:163], v[118:121]
	v_mfma_f32_16x16x32_bf16 v[110:113], v[140:143], v[168:171], v[110:113]
	v_mfma_f32_16x16x32_bf16 v[102:105], v[152:155], v[168:171], v[102:105]
	v_mfma_f32_16x16x32_bf16 v[94:97], v[140:143], v[176:179], v[94:97]
	v_mfma_f32_16x16x32_bf16 v[86:89], v[152:155], v[176:179], v[86:89]
	v_mfma_f32_16x16x32_bf16 v[78:81], v[140:143], v[184:187], v[78:81]
	v_mfma_f32_16x16x32_bf16 v[70:73], v[152:155], v[184:187], v[70:73]
	v_mfma_f32_16x16x32_bf16 v[126:129], v[148:151], v[164:167], v[126:129]
	v_mfma_f32_16x16x32_bf16 v[118:121], v[156:159], v[164:167], v[118:121]
	v_mfma_f32_16x16x32_bf16 v[110:113], v[148:151], v[172:175], v[110:113]
	v_mfma_f32_16x16x32_bf16 v[102:105], v[156:159], v[172:175], v[102:105]
	v_mfma_f32_16x16x32_bf16 v[94:97], v[148:151], v[180:183], v[94:97]
	v_mfma_f32_16x16x32_bf16 v[86:89], v[156:159], v[180:183], v[86:89]
	v_mfma_f32_16x16x32_bf16 v[78:81], v[148:151], v[188:191], v[78:81]
	v_mfma_f32_16x16x32_bf16 v[70:73], v[156:159], v[188:191], v[70:73]
	s_barrier
	s_setprio 0
	s_add_i32 s6, 0, 0x14000
	v_add_u32_e32 v134, s6, v137
	s_add_i32 s7, s90, s54
	ds_read_b128 v[192:195], v134
	ds_read_b128 v[196:199], v134 offset:1024
	ds_read_b128 v[200:203], v134 offset:2048
	ds_read_b128 v[204:207], v134 offset:3072
	v_lshl_add_u64 v[134:135], s[88:89], 0, v[0:1]
	s_mov_b32 m0, s7
	v_lshl_add_u64 v[144:145], v[134:135], 0, s[60:61]
	global_load_lds_dwordx4 v[134:135], off
	s_add_i32 m0, s7, 0x2000
	s_nop 0
	global_load_lds_dwordx4 v[144:145], off
	s_setprio 1
	s_barrier
	s_waitcnt lgkmcnt(0)
	v_mfma_f32_16x16x32_bf16 v[122:125], v[192:195], v[160:163], v[122:125]
	v_mfma_f32_16x16x32_bf16 v[114:117], v[200:203], v[160:163], v[114:117]
	v_mfma_f32_16x16x32_bf16 v[106:109], v[192:195], v[168:171], v[106:109]
	v_mfma_f32_16x16x32_bf16 v[98:101], v[200:203], v[168:171], v[98:101]
	v_mfma_f32_16x16x32_bf16 v[90:93], v[192:195], v[176:179], v[90:93]
	v_mfma_f32_16x16x32_bf16 v[82:85], v[200:203], v[176:179], v[82:85]
	v_mfma_f32_16x16x32_bf16 v[74:77], v[192:195], v[184:187], v[74:77]
	v_mfma_f32_16x16x32_bf16 v[66:69], v[200:203], v[184:187], v[66:69]
	v_mfma_f32_16x16x32_bf16 v[122:125], v[196:199], v[164:167], v[122:125]
	v_mfma_f32_16x16x32_bf16 v[114:117], v[204:207], v[164:167], v[114:117]
	v_mfma_f32_16x16x32_bf16 v[106:109], v[196:199], v[172:175], v[106:109]
	v_mfma_f32_16x16x32_bf16 v[98:101], v[204:207], v[172:175], v[98:101]
	v_mfma_f32_16x16x32_bf16 v[90:93], v[196:199], v[180:183], v[90:93]
	v_mfma_f32_16x16x32_bf16 v[82:85], v[204:207], v[180:183], v[82:85]
	v_mfma_f32_16x16x32_bf16 v[74:77], v[196:199], v[188:191], v[74:77]
	v_mfma_f32_16x16x32_bf16 v[66:69], v[204:207], v[188:191], v[66:69]
	s_barrier
	s_setprio 0
	s_mov_b32 m0, s49
	v_lshl_add_u64 v[144:145], s[78:79], 0, v[130:131]
	ds_read_b128 v[160:163], v138 offset:16384
	ds_read_b128 v[164:167], v138 offset:17408
	ds_read_b128 v[168:171], v138 offset:18432
	ds_read_b128 v[172:175], v138 offset:19456
	ds_read_b128 v[176:179], v138 offset:20480
	ds_read_b128 v[180:183], v138 offset:21504
	ds_read_b128 v[184:187], v138 offset:22528
	ds_read_b128 v[188:191], v138 offset:23552
	global_load_lds_dwordx4 v[144:145], off
	v_lshl_add_u64 v[208:209], v[144:145], 0, s[60:61]
	s_mov_b32 m0, s55
	s_nop 0
	global_load_lds_dwordx4 v[208:209], off
	s_setprio 1
	s_barrier
	s_waitcnt lgkmcnt(0)
	v_mfma_f32_16x16x32_bf16 v[62:65], v[140:143], v[160:163], v[62:65]
	v_mfma_f32_16x16x32_bf16 v[54:57], v[152:155], v[160:163], v[54:57]
	v_mfma_f32_16x16x32_bf16 v[46:49], v[140:143], v[168:171], v[46:49]
	v_mfma_f32_16x16x32_bf16 v[38:41], v[152:155], v[168:171], v[38:41]
	v_mfma_f32_16x16x32_bf16 v[30:33], v[140:143], v[176:179], v[30:33]
	v_mfma_f32_16x16x32_bf16 v[22:25], v[152:155], v[176:179], v[22:25]
	v_mfma_f32_16x16x32_bf16 v[14:17], v[140:143], v[184:187], v[14:17]
	v_mfma_f32_16x16x32_bf16 v[6:9], v[152:155], v[184:187], v[6:9]
	v_mfma_f32_16x16x32_bf16 v[62:65], v[148:151], v[164:167], v[62:65]
	v_mfma_f32_16x16x32_bf16 v[54:57], v[156:159], v[164:167], v[54:57]
	v_mfma_f32_16x16x32_bf16 v[46:49], v[148:151], v[172:175], v[46:49]
	v_mfma_f32_16x16x32_bf16 v[38:41], v[156:159], v[172:175], v[38:41]
	v_mfma_f32_16x16x32_bf16 v[30:33], v[148:151], v[180:183], v[30:33]
	v_mfma_f32_16x16x32_bf16 v[22:25], v[156:159], v[180:183], v[22:25]
	v_mfma_f32_16x16x32_bf16 v[14:17], v[148:151], v[188:191], v[14:17]
	v_mfma_f32_16x16x32_bf16 v[6:9], v[156:159], v[188:191], v[6:9]
	s_barrier
	s_setprio 0
	s_add_i32 s6, s6, s54
	v_lshl_add_u64 v[140:141], v[134:135], 0, s[20:21]
	s_mov_b32 m0, s6
	s_nop 0
	global_load_lds_dwordx4 v[140:141], off
	v_lshl_add_u64 v[140:141], v[134:135], 0, s[64:65]
	s_add_i32 m0, s6, 0x2000
	s_nop 0
	global_load_lds_dwordx4 v[140:141], off
	s_waitcnt vmcnt(6)
	s_setprio 1
	s_barrier
	v_mfma_f32_16x16x32_bf16 v[58:61], v[192:195], v[160:163], v[58:61]
	v_mfma_f32_16x16x32_bf16 v[50:53], v[200:203], v[160:163], v[50:53]
	v_mfma_f32_16x16x32_bf16 v[42:45], v[192:195], v[168:171], v[42:45]
	v_mfma_f32_16x16x32_bf16 v[34:37], v[200:203], v[168:171], v[34:37]
	v_mfma_f32_16x16x32_bf16 v[26:29], v[192:195], v[176:179], v[26:29]
	v_mfma_f32_16x16x32_bf16 v[18:21], v[200:203], v[176:179], v[18:21]
	v_mfma_f32_16x16x32_bf16 v[10:13], v[192:195], v[184:187], v[10:13]
	v_mfma_f32_16x16x32_bf16 v[2:5], v[200:203], v[184:187], v[2:5]
	v_mfma_f32_16x16x32_bf16 v[58:61], v[196:199], v[164:167], v[58:61]
	v_mfma_f32_16x16x32_bf16 v[50:53], v[204:207], v[164:167], v[50:53]
	v_mfma_f32_16x16x32_bf16 v[42:45], v[196:199], v[172:175], v[42:45]
	v_mfma_f32_16x16x32_bf16 v[34:37], v[204:207], v[172:175], v[34:37]
	v_mfma_f32_16x16x32_bf16 v[26:29], v[196:199], v[180:183], v[26:29]
	v_mfma_f32_16x16x32_bf16 v[18:21], v[204:207], v[180:183], v[18:21]
	v_mfma_f32_16x16x32_bf16 v[10:13], v[196:199], v[188:191], v[10:13]
	v_mfma_f32_16x16x32_bf16 v[2:5], v[204:207], v[188:191], v[2:5]
	s_barrier
	s_setprio 0
	s_add_i32 s6, 0, 0x18000
	v_add_u32_e32 v139, s6, v137
	ds_read_b128 v[140:143], v139
	ds_read_b128 v[148:151], v139 offset:1024
	ds_read_b128 v[152:155], v139 offset:2048
	ds_read_b128 v[156:159], v139 offset:3072
	s_mov_b32 m0, s56
	v_lshl_add_u64 v[192:193], v[144:145], 0, s[20:21]
	ds_read_b128 v[160:163], v138 offset:32768
	ds_read_b128 v[164:167], v138 offset:33792
	ds_read_b128 v[168:171], v138 offset:34816
	ds_read_b128 v[172:175], v138 offset:35840
	ds_read_b128 v[176:179], v138 offset:36864
	ds_read_b128 v[180:183], v138 offset:37888
	ds_read_b128 v[184:187], v138 offset:38912
	ds_read_b128 v[188:191], v138 offset:39936
	global_load_lds_dwordx4 v[192:193], off
	v_lshl_add_u64 v[192:193], v[144:145], 0, s[64:65]
	s_mov_b32 m0, s57
	s_nop 0
	global_load_lds_dwordx4 v[192:193], off
	s_waitcnt lgkmcnt(8)
	s_setprio 1
	s_barrier
	s_waitcnt lgkmcnt(0)
	v_mfma_f32_16x16x32_bf16 v[126:129], v[140:143], v[160:163], v[126:129]
	v_mfma_f32_16x16x32_bf16 v[118:121], v[152:155], v[160:163], v[118:121]
	v_mfma_f32_16x16x32_bf16 v[110:113], v[140:143], v[168:171], v[110:113]
	v_mfma_f32_16x16x32_bf16 v[102:105], v[152:155], v[168:171], v[102:105]
	v_mfma_f32_16x16x32_bf16 v[94:97], v[140:143], v[176:179], v[94:97]
	v_mfma_f32_16x16x32_bf16 v[86:89], v[152:155], v[176:179], v[86:89]
	v_mfma_f32_16x16x32_bf16 v[78:81], v[140:143], v[184:187], v[78:81]
	v_mfma_f32_16x16x32_bf16 v[70:73], v[152:155], v[184:187], v[70:73]
	v_mfma_f32_16x16x32_bf16 v[126:129], v[148:151], v[164:167], v[126:129]
	v_mfma_f32_16x16x32_bf16 v[118:121], v[156:159], v[164:167], v[118:121]
	v_mfma_f32_16x16x32_bf16 v[110:113], v[148:151], v[172:175], v[110:113]
	v_mfma_f32_16x16x32_bf16 v[102:105], v[156:159], v[172:175], v[102:105]
	v_mfma_f32_16x16x32_bf16 v[94:97], v[148:151], v[180:183], v[94:97]
	v_mfma_f32_16x16x32_bf16 v[86:89], v[156:159], v[180:183], v[86:89]
	v_mfma_f32_16x16x32_bf16 v[78:81], v[148:151], v[188:191], v[78:81]
	v_mfma_f32_16x16x32_bf16 v[70:73], v[156:159], v[188:191], v[70:73]
	s_barrier
	s_setprio 0
	s_add_i32 s7, 0, 0x1c000
	s_add_i32 s6, s6, s54
	v_add_u32_e32 v139, s7, v137
	v_lshl_add_u64 v[208:209], v[134:135], 0, s[34:35]
	s_mov_b32 m0, s6
	ds_read_b128 v[192:195], v139
	ds_read_b128 v[196:199], v139 offset:1024
	ds_read_b128 v[200:203], v139 offset:2048
	ds_read_b128 v[204:207], v139 offset:3072
	global_load_lds_dwordx4 v[208:209], off
	v_lshl_add_u64 v[208:209], v[134:135], 0, s[66:67]
	s_add_i32 m0, s6, 0x2000
	s_nop 0
	global_load_lds_dwordx4 v[208:209], off
	s_setprio 1
	s_barrier
	s_waitcnt lgkmcnt(0)
	v_mfma_f32_16x16x32_bf16 v[122:125], v[192:195], v[160:163], v[122:125]
	v_mfma_f32_16x16x32_bf16 v[114:117], v[200:203], v[160:163], v[114:117]
	v_mfma_f32_16x16x32_bf16 v[106:109], v[192:195], v[168:171], v[106:109]
	v_mfma_f32_16x16x32_bf16 v[98:101], v[200:203], v[168:171], v[98:101]
	v_mfma_f32_16x16x32_bf16 v[90:93], v[192:195], v[176:179], v[90:93]
	v_mfma_f32_16x16x32_bf16 v[82:85], v[200:203], v[176:179], v[82:85]
	v_mfma_f32_16x16x32_bf16 v[74:77], v[192:195], v[184:187], v[74:77]
	v_mfma_f32_16x16x32_bf16 v[66:69], v[200:203], v[184:187], v[66:69]
	v_mfma_f32_16x16x32_bf16 v[122:125], v[196:199], v[164:167], v[122:125]
	v_mfma_f32_16x16x32_bf16 v[114:117], v[204:207], v[164:167], v[114:117]
	v_mfma_f32_16x16x32_bf16 v[106:109], v[196:199], v[172:175], v[106:109]
	v_mfma_f32_16x16x32_bf16 v[98:101], v[204:207], v[172:175], v[98:101]
	v_mfma_f32_16x16x32_bf16 v[90:93], v[196:199], v[180:183], v[90:93]
	v_mfma_f32_16x16x32_bf16 v[82:85], v[204:207], v[180:183], v[82:85]
	v_mfma_f32_16x16x32_bf16 v[74:77], v[196:199], v[188:191], v[74:77]
	v_mfma_f32_16x16x32_bf16 v[66:69], v[204:207], v[188:191], v[66:69]
	s_barrier
	s_setprio 0
	s_mov_b32 m0, s59
	v_lshl_add_u64 v[208:209], v[144:145], 0, s[34:35]
	ds_read_b128 v[160:163], v138 offset:49152
	ds_read_b128 v[164:167], v138 offset:50176
	ds_read_b128 v[168:171], v138 offset:51200
	ds_read_b128 v[172:175], v138 offset:52224
	ds_read_b128 v[176:179], v138 offset:53248
	ds_read_b128 v[180:183], v138 offset:54272
	ds_read_b128 v[184:187], v138 offset:55296
	ds_read_b128 v[188:191], v138 offset:56320
	global_load_lds_dwordx4 v[208:209], off
	v_lshl_add_u64 v[144:145], v[144:145], 0, s[66:67]
	s_mov_b32 m0, s62
	s_nop 0
	global_load_lds_dwordx4 v[144:145], off
	s_setprio 1
	s_barrier
	s_waitcnt lgkmcnt(0)
	v_mfma_f32_16x16x32_bf16 v[62:65], v[140:143], v[160:163], v[62:65]
	v_mfma_f32_16x16x32_bf16 v[54:57], v[152:155], v[160:163], v[54:57]
	v_mfma_f32_16x16x32_bf16 v[46:49], v[140:143], v[168:171], v[46:49]
	v_mfma_f32_16x16x32_bf16 v[38:41], v[152:155], v[168:171], v[38:41]
	v_mfma_f32_16x16x32_bf16 v[30:33], v[140:143], v[176:179], v[30:33]
	v_mfma_f32_16x16x32_bf16 v[22:25], v[152:155], v[176:179], v[22:25]
	v_mfma_f32_16x16x32_bf16 v[14:17], v[140:143], v[184:187], v[14:17]
	v_mfma_f32_16x16x32_bf16 v[6:9], v[152:155], v[184:187], v[6:9]
	v_mfma_f32_16x16x32_bf16 v[62:65], v[148:151], v[164:167], v[62:65]
	v_mfma_f32_16x16x32_bf16 v[54:57], v[156:159], v[164:167], v[54:57]
	v_mfma_f32_16x16x32_bf16 v[46:49], v[148:151], v[172:175], v[46:49]
	v_mfma_f32_16x16x32_bf16 v[38:41], v[156:159], v[172:175], v[38:41]
	v_mfma_f32_16x16x32_bf16 v[30:33], v[148:151], v[180:183], v[30:33]
	v_mfma_f32_16x16x32_bf16 v[22:25], v[156:159], v[180:183], v[22:25]
	v_mfma_f32_16x16x32_bf16 v[14:17], v[148:151], v[188:191], v[14:17]
	v_mfma_f32_16x16x32_bf16 v[6:9], v[156:159], v[188:191], v[6:9]
	s_barrier
	s_setprio 0
	s_add_i32 s6, s7, s54
	v_lshl_add_u64 v[140:141], v[134:135], 0, s[16:17]
	s_mov_b32 m0, s6
	v_lshl_add_u64 v[134:135], v[134:135], 0, s[80:81]
	global_load_lds_dwordx4 v[140:141], off
	s_add_i32 m0, s6, 0x2000
	s_nop 0
	global_load_lds_dwordx4 v[134:135], off
	s_waitcnt vmcnt(6)
	s_setprio 1
	s_barrier
	v_mfma_f32_16x16x32_bf16 v[58:61], v[192:195], v[160:163], v[58:61]
	v_mfma_f32_16x16x32_bf16 v[50:53], v[200:203], v[160:163], v[50:53]
	v_mfma_f32_16x16x32_bf16 v[42:45], v[192:195], v[168:171], v[42:45]
	v_mfma_f32_16x16x32_bf16 v[34:37], v[200:203], v[168:171], v[34:37]
	v_mfma_f32_16x16x32_bf16 v[26:29], v[192:195], v[176:179], v[26:29]
	v_mfma_f32_16x16x32_bf16 v[18:21], v[200:203], v[176:179], v[18:21]
	v_mfma_f32_16x16x32_bf16 v[10:13], v[192:195], v[184:187], v[10:13]
	v_mfma_f32_16x16x32_bf16 v[2:5], v[200:203], v[184:187], v[2:5]
	v_mfma_f32_16x16x32_bf16 v[58:61], v[196:199], v[164:167], v[58:61]
	v_mfma_f32_16x16x32_bf16 v[50:53], v[204:207], v[164:167], v[50:53]
	v_mfma_f32_16x16x32_bf16 v[42:45], v[196:199], v[172:175], v[42:45]
	v_mfma_f32_16x16x32_bf16 v[34:37], v[204:207], v[172:175], v[34:37]
	v_mfma_f32_16x16x32_bf16 v[26:29], v[196:199], v[180:183], v[26:29]
	v_mfma_f32_16x16x32_bf16 v[18:21], v[204:207], v[180:183], v[18:21]
	v_mfma_f32_16x16x32_bf16 v[10:13], v[196:199], v[188:191], v[10:13]
	v_mfma_f32_16x16x32_bf16 v[2:5], v[204:207], v[188:191], v[2:5]
	s_barrier
	s_setprio 0
	s_add_i32 s87, s87, 2
	s_add_u32 s41, s41, 0x100
	s_addc_u32 s86, s86, 0
	s_cmp_gt_u32 s87, 29
	s_mov_b64 s[6:7], s[8:9]
	s_cbranch_scc0 .LBB0_51
	v_mul_f32_e32 v144, 0xbfb8aa3b, v126
	v_exp_f32_e32 v144, v144
	v_mov_b32_e32 v134, v136
	s_lshl_b32 s6, s48, 8
	v_add_f32_e32 v144, 1.0, v144
	v_rcp_f32_e32 v144, v144
	s_add_i32 s6, s6, s10
	v_and_or_b32 v139, v134, 15, s6
	s_lshl_b32 s6, s85, 7
	v_mul_f32_e32 v126, v126, v144
	v_mul_f32_e32 v122, v126, v122
	v_mul_f32_e32 v126, 0xbfb8aa3b, v127
	v_exp_f32_e32 v126, v126
	v_ashrrev_i32_e32 v134, 1, v134
	s_or_b32 s6, s6, s58
	v_and_b32_e32 v134, -8, v134
	v_add_f32_e32 v126, 1.0, v126
	v_rcp_f32_e32 v126, v126
	v_add_u32_e32 v140, s6, v134
	v_ashrrev_i32_e32 v141, 31, v140
	v_mov_b64_e32 v[134:135], s[4:5]
	v_mul_f32_e32 v126, v127, v126
	v_mul_f32_e32 v123, v126, v123
	v_mul_f32_e32 v126, 0xbfb8aa3b, v128
	v_exp_f32_e32 v126, v126
	v_mad_i64_i32 v[142:143], s[6:7], v139, s74, v[134:135]
	s_and_b64 vcc, exec, s[44:45]
	v_add_f32_e32 v126, 1.0, v126
	v_rcp_f32_e32 v126, v126
	s_mov_b32 s48, s40
	s_mov_b32 s85, s84
	s_mov_b64 s[8:9], s[46:47]
	v_mul_f32_e32 v126, v128, v126
	v_mul_f32_e32 v124, v126, v124
	v_mul_f32_e32 v126, 0xbfb8aa3b, v129
	v_exp_f32_e32 v126, v126
	s_nop 0
	v_add_f32_e32 v126, 1.0, v126
	v_rcp_f32_e32 v126, v126
	s_nop 0
	v_mul_f32_e32 v126, v129, v126
	v_mul_f32_e32 v125, v126, v125
	v_mul_f32_e32 v126, 0xbfb8aa3b, v118
	v_exp_f32_e32 v126, v126
	s_nop 0
	v_add_f32_e32 v126, 1.0, v126
	v_rcp_f32_e32 v126, v126
	s_nop 0
	v_mul_f32_e32 v118, v118, v126
	v_mul_f32_e32 v118, v118, v114
	v_mul_f32_e32 v114, 0xbfb8aa3b, v119
	v_exp_f32_e32 v114, v114
	s_nop 0
	v_add_f32_e32 v114, 1.0, v114
	v_rcp_f32_e32 v114, v114
	s_nop 0
	v_mul_f32_e32 v114, v119, v114
	v_mul_f32_e32 v119, v114, v115
	v_mul_f32_e32 v114, 0xbfb8aa3b, v120
	v_exp_f32_e32 v114, v114
	s_nop 0
	v_add_f32_e32 v114, 1.0, v114
	v_rcp_f32_e32 v114, v114
	s_nop 0
	v_mul_f32_e32 v114, v120, v114
	v_mul_f32_e32 v126, v114, v116
	v_mul_f32_e32 v114, 0xbfb8aa3b, v121
	v_exp_f32_e32 v114, v114
	v_cvt_pk_bf16_f32 v116, v122, v123
	s_nop 0
	v_add_f32_e32 v114, 1.0, v114
	v_rcp_f32_e32 v114, v114
	s_nop 0
	v_mul_f32_e32 v114, v121, v114
	v_mul_f32_e32 v127, v114, v117
	v_lshlrev_b64 v[114:115], 1, v[140:141]
	v_lshl_add_u64 v[120:121], v[142:143], 0, v[114:115]
	v_cvt_pk_bf16_f32 v117, v124, v125
	v_cvt_pk_bf16_f32 v118, v118, v119
	v_cvt_pk_bf16_f32 v119, v126, v127
	global_store_dwordx4 v[120:121], v[116:119], off
	s_nop 1
	v_mul_f32_e32 v118, 0xbfb8aa3b, v110
	v_exp_f32_e32 v118, v118
	v_or_b32_e32 v116, 16, v139
	v_mad_i64_i32 v[116:117], s[6:7], v116, s74, v[134:135]
	v_add_f32_e32 v118, 1.0, v118
	v_rcp_f32_e32 v118, v118
	s_nop 0
	v_mul_f32_e32 v110, v110, v118
	v_mul_f32_e32 v106, v110, v106
	v_mul_f32_e32 v110, 0xbfb8aa3b, v111
	v_exp_f32_e32 v110, v110
	s_nop 0
	v_add_f32_e32 v110, 1.0, v110
	v_rcp_f32_e32 v110, v110
	s_nop 0
	v_mul_f32_e32 v110, v111, v110
	v_mul_f32_e32 v107, v110, v107
	v_mul_f32_e32 v110, 0xbfb8aa3b, v112
	v_exp_f32_e32 v110, v110
	s_nop 0
	v_add_f32_e32 v110, 1.0, v110
	v_rcp_f32_e32 v110, v110
	s_nop 0
	v_mul_f32_e32 v110, v112, v110
	v_mul_f32_e32 v108, v110, v108
	v_mul_f32_e32 v110, 0xbfb8aa3b, v113
	v_exp_f32_e32 v110, v110
	s_nop 0
	v_add_f32_e32 v110, 1.0, v110
	v_rcp_f32_e32 v110, v110
	s_nop 0
	v_mul_f32_e32 v110, v113, v110
	v_mul_f32_e32 v109, v110, v109
	v_mul_f32_e32 v110, 0xbfb8aa3b, v102
	v_exp_f32_e32 v110, v110
	s_nop 0
	v_add_f32_e32 v110, 1.0, v110
	v_rcp_f32_e32 v110, v110
	s_nop 0
	v_mul_f32_e32 v102, v102, v110
	v_mul_f32_e32 v110, v102, v98
	v_mul_f32_e32 v98, 0xbfb8aa3b, v103
	v_exp_f32_e32 v98, v98
	s_nop 0
	v_add_f32_e32 v98, 1.0, v98
	v_rcp_f32_e32 v98, v98
	s_nop 0
	v_mul_f32_e32 v98, v103, v98
	v_mul_f32_e32 v111, v98, v99
	v_mul_f32_e32 v98, 0xbfb8aa3b, v104
	v_exp_f32_e32 v98, v98
	v_lshl_add_u64 v[102:103], v[116:117], 0, v[114:115]
	v_add_f32_e32 v98, 1.0, v98
	v_rcp_f32_e32 v98, v98
	s_nop 0
	v_mul_f32_e32 v98, v104, v98
	v_mul_f32_e32 v104, v98, v100
	v_mul_f32_e32 v98, 0xbfb8aa3b, v105
	v_exp_f32_e32 v98, v98
	s_nop 0
	v_add_f32_e32 v98, 1.0, v98
	v_rcp_f32_e32 v98, v98
	s_nop 0
	v_mul_f32_e32 v98, v105, v98
	v_mul_f32_e32 v101, v98, v101
	v_cvt_pk_bf16_f32 v98, v106, v107
	v_cvt_pk_bf16_f32 v99, v108, v109
	v_cvt_pk_bf16_f32 v100, v110, v111
	v_cvt_pk_bf16_f32 v101, v104, v101
	global_store_dwordx4 v[102:103], v[98:101], off
	s_nop 1
	v_mul_f32_e32 v100, 0xbfb8aa3b, v94
	v_exp_f32_e32 v100, v100
	v_or_b32_e32 v98, 32, v139
	v_mad_i64_i32 v[98:99], s[6:7], v98, s74, v[134:135]
	v_add_f32_e32 v100, 1.0, v100
	v_rcp_f32_e32 v100, v100
	s_nop 0
	v_mul_f32_e32 v94, v94, v100
	v_mul_f32_e32 v90, v94, v90
	v_mul_f32_e32 v94, 0xbfb8aa3b, v95
	v_exp_f32_e32 v94, v94
	s_nop 0
	v_add_f32_e32 v94, 1.0, v94
	v_rcp_f32_e32 v94, v94
	s_nop 0
	v_mul_f32_e32 v94, v95, v94
	v_mul_f32_e32 v91, v94, v91
	v_mul_f32_e32 v94, 0xbfb8aa3b, v96
	v_exp_f32_e32 v94, v94
	s_nop 0
	v_add_f32_e32 v94, 1.0, v94
	v_rcp_f32_e32 v94, v94
	s_nop 0
	v_mul_f32_e32 v94, v96, v94
	v_mul_f32_e32 v92, v94, v92
	v_mul_f32_e32 v94, 0xbfb8aa3b, v97
	v_exp_f32_e32 v94, v94
	s_nop 0
	v_add_f32_e32 v94, 1.0, v94
	v_rcp_f32_e32 v94, v94
	s_nop 0
	v_mul_f32_e32 v94, v97, v94
	v_mul_f32_e32 v93, v94, v93
	v_mul_f32_e32 v94, 0xbfb8aa3b, v86
	v_exp_f32_e32 v94, v94
	s_nop 0
	v_add_f32_e32 v94, 1.0, v94
	v_rcp_f32_e32 v94, v94
	s_nop 0
	v_mul_f32_e32 v86, v86, v94
	v_mul_f32_e32 v94, v86, v82
	v_mul_f32_e32 v82, 0xbfb8aa3b, v87
	v_exp_f32_e32 v82, v82
	s_nop 0
	v_add_f32_e32 v82, 1.0, v82
	v_rcp_f32_e32 v82, v82
	s_nop 0
	v_mul_f32_e32 v82, v87, v82
	v_mul_f32_e32 v95, v82, v83
	v_mul_f32_e32 v82, 0xbfb8aa3b, v88
	v_exp_f32_e32 v82, v82
	v_lshl_add_u64 v[86:87], v[98:99], 0, v[114:115]
	v_add_f32_e32 v82, 1.0, v82
	v_rcp_f32_e32 v82, v82
	s_nop 0
	v_mul_f32_e32 v82, v88, v82
	v_mul_f32_e32 v88, v82, v84
	v_mul_f32_e32 v82, 0xbfb8aa3b, v89
	v_exp_f32_e32 v82, v82
	s_nop 0
	v_add_f32_e32 v82, 1.0, v82
	v_rcp_f32_e32 v82, v82
	s_nop 0
	v_mul_f32_e32 v82, v89, v82
	v_mul_f32_e32 v85, v82, v85
	v_cvt_pk_bf16_f32 v82, v90, v91
	v_cvt_pk_bf16_f32 v83, v92, v93
	v_cvt_pk_bf16_f32 v84, v94, v95
	v_cvt_pk_bf16_f32 v85, v88, v85
	global_store_dwordx4 v[86:87], v[82:85], off
	s_nop 1
	v_mul_f32_e32 v84, 0xbfb8aa3b, v78
	v_exp_f32_e32 v84, v84
	v_or_b32_e32 v82, 48, v139
	v_mad_i64_i32 v[82:83], s[6:7], v82, s74, v[134:135]
	v_add_f32_e32 v84, 1.0, v84
	v_rcp_f32_e32 v84, v84
	s_nop 0
	v_mul_f32_e32 v78, v78, v84
	v_mul_f32_e32 v74, v78, v74
	v_mul_f32_e32 v78, 0xbfb8aa3b, v79
	v_exp_f32_e32 v78, v78
	s_nop 0
	v_add_f32_e32 v78, 1.0, v78
	v_rcp_f32_e32 v78, v78
	s_nop 0
	v_mul_f32_e32 v78, v79, v78
	v_mul_f32_e32 v75, v78, v75
	v_mul_f32_e32 v78, 0xbfb8aa3b, v80
	v_exp_f32_e32 v78, v78
	s_nop 0
	v_add_f32_e32 v78, 1.0, v78
	v_rcp_f32_e32 v78, v78
	s_nop 0
	v_mul_f32_e32 v78, v80, v78
	v_mul_f32_e32 v76, v78, v76
	v_mul_f32_e32 v78, 0xbfb8aa3b, v81
	v_exp_f32_e32 v78, v78
	s_nop 0
	v_add_f32_e32 v78, 1.0, v78
	v_rcp_f32_e32 v78, v78
	s_nop 0
	v_mul_f32_e32 v78, v81, v78
	v_mul_f32_e32 v77, v78, v77
	v_mul_f32_e32 v78, 0xbfb8aa3b, v70
	v_exp_f32_e32 v78, v78
	s_nop 0
	v_add_f32_e32 v78, 1.0, v78
	v_rcp_f32_e32 v78, v78
	s_nop 0
	v_mul_f32_e32 v70, v70, v78
	v_mul_f32_e32 v78, v70, v66
	v_mul_f32_e32 v66, 0xbfb8aa3b, v71
	v_exp_f32_e32 v66, v66
	s_nop 0
	v_add_f32_e32 v66, 1.0, v66
	v_rcp_f32_e32 v66, v66
	s_nop 0
	v_mul_f32_e32 v66, v71, v66
	v_mul_f32_e32 v79, v66, v67
	v_mul_f32_e32 v66, 0xbfb8aa3b, v72
	v_exp_f32_e32 v66, v66
	v_lshl_add_u64 v[70:71], v[82:83], 0, v[114:115]
	v_add_f32_e32 v66, 1.0, v66
	v_rcp_f32_e32 v66, v66
	s_nop 0
	v_mul_f32_e32 v66, v72, v66
	v_mul_f32_e32 v72, v66, v68
	v_mul_f32_e32 v66, 0xbfb8aa3b, v73
	v_exp_f32_e32 v66, v66
	s_nop 0
	v_add_f32_e32 v66, 1.0, v66
	v_rcp_f32_e32 v66, v66
	s_nop 0
	v_mul_f32_e32 v66, v73, v66
	v_mul_f32_e32 v69, v66, v69
	v_cvt_pk_bf16_f32 v66, v74, v75
	v_cvt_pk_bf16_f32 v67, v76, v77
	v_cvt_pk_bf16_f32 v68, v78, v79
	v_cvt_pk_bf16_f32 v69, v72, v69
	global_store_dwordx4 v[70:71], v[66:69], off
	s_nop 1
	v_mul_f32_e32 v68, 0xbfb8aa3b, v62
	v_exp_f32_e32 v68, v68
	v_add_u32_e32 v66, 0x80, v139
	v_mad_i64_i32 v[66:67], s[6:7], v66, s74, v[134:135]
	v_add_f32_e32 v68, 1.0, v68
	v_rcp_f32_e32 v68, v68
	s_nop 0
	v_mul_f32_e32 v62, v62, v68
	v_mul_f32_e32 v58, v62, v58
	v_mul_f32_e32 v62, 0xbfb8aa3b, v63
	v_exp_f32_e32 v62, v62
	s_nop 0
	v_add_f32_e32 v62, 1.0, v62
	v_rcp_f32_e32 v62, v62
	s_nop 0
	v_mul_f32_e32 v62, v63, v62
	v_mul_f32_e32 v59, v62, v59
	v_mul_f32_e32 v62, 0xbfb8aa3b, v64
	v_exp_f32_e32 v62, v62
	s_nop 0
	v_add_f32_e32 v62, 1.0, v62
	v_rcp_f32_e32 v62, v62
	s_nop 0
	v_mul_f32_e32 v62, v64, v62
	v_mul_f32_e32 v60, v62, v60
	v_mul_f32_e32 v62, 0xbfb8aa3b, v65
	v_exp_f32_e32 v62, v62
	s_nop 0
	v_add_f32_e32 v62, 1.0, v62
	v_rcp_f32_e32 v62, v62
	s_nop 0
	v_mul_f32_e32 v62, v65, v62
	v_mul_f32_e32 v61, v62, v61
	v_mul_f32_e32 v62, 0xbfb8aa3b, v54
	v_exp_f32_e32 v62, v62
	s_nop 0
	v_add_f32_e32 v62, 1.0, v62
	v_rcp_f32_e32 v62, v62
	s_nop 0
	v_mul_f32_e32 v54, v54, v62
	v_mul_f32_e32 v62, v54, v50
	v_mul_f32_e32 v50, 0xbfb8aa3b, v55
	v_exp_f32_e32 v50, v50
	s_nop 0
	v_add_f32_e32 v50, 1.0, v50
	v_rcp_f32_e32 v50, v50
	s_nop 0
	v_mul_f32_e32 v50, v55, v50
	v_mul_f32_e32 v63, v50, v51
	v_mul_f32_e32 v50, 0xbfb8aa3b, v56
	v_exp_f32_e32 v50, v50
	v_lshl_add_u64 v[54:55], v[66:67], 0, v[114:115]
	v_add_f32_e32 v50, 1.0, v50
	v_rcp_f32_e32 v50, v50
	s_nop 0
	v_mul_f32_e32 v50, v56, v50
	v_mul_f32_e32 v56, v50, v52
	v_mul_f32_e32 v50, 0xbfb8aa3b, v57
	v_exp_f32_e32 v50, v50
	s_nop 0
	v_add_f32_e32 v50, 1.0, v50
	v_rcp_f32_e32 v50, v50
	s_nop 0
	v_mul_f32_e32 v50, v57, v50
	v_mul_f32_e32 v53, v50, v53
	v_cvt_pk_bf16_f32 v50, v58, v59
	v_cvt_pk_bf16_f32 v51, v60, v61
	v_cvt_pk_bf16_f32 v52, v62, v63
	v_cvt_pk_bf16_f32 v53, v56, v53
	global_store_dwordx4 v[54:55], v[50:53], off
	s_nop 1
	v_mul_f32_e32 v52, 0xbfb8aa3b, v46
	v_exp_f32_e32 v52, v52
	v_add_u32_e32 v50, 0x90, v139
	v_mad_i64_i32 v[50:51], s[6:7], v50, s74, v[134:135]
	v_add_f32_e32 v52, 1.0, v52
	v_rcp_f32_e32 v52, v52
	s_nop 0
	v_mul_f32_e32 v46, v46, v52
	v_mul_f32_e32 v42, v46, v42
	v_mul_f32_e32 v46, 0xbfb8aa3b, v47
	v_exp_f32_e32 v46, v46
	s_nop 0
	v_add_f32_e32 v46, 1.0, v46
	v_rcp_f32_e32 v46, v46
	s_nop 0
	v_mul_f32_e32 v46, v47, v46
	v_mul_f32_e32 v43, v46, v43
	v_mul_f32_e32 v46, 0xbfb8aa3b, v48
	v_exp_f32_e32 v46, v46
	s_nop 0
	v_add_f32_e32 v46, 1.0, v46
	v_rcp_f32_e32 v46, v46
	s_nop 0
	v_mul_f32_e32 v46, v48, v46
	v_mul_f32_e32 v44, v46, v44
	v_mul_f32_e32 v46, 0xbfb8aa3b, v49
	v_exp_f32_e32 v46, v46
	s_nop 0
	v_add_f32_e32 v46, 1.0, v46
	v_rcp_f32_e32 v46, v46
	s_nop 0
	v_mul_f32_e32 v46, v49, v46
	v_mul_f32_e32 v45, v46, v45
	v_mul_f32_e32 v46, 0xbfb8aa3b, v38
	v_exp_f32_e32 v46, v46
	s_nop 0
	v_add_f32_e32 v46, 1.0, v46
	v_rcp_f32_e32 v46, v46
	s_nop 0
	v_mul_f32_e32 v38, v38, v46
	v_mul_f32_e32 v46, v38, v34
	v_mul_f32_e32 v34, 0xbfb8aa3b, v39
	v_exp_f32_e32 v34, v34
	s_nop 0
	v_add_f32_e32 v34, 1.0, v34
	v_rcp_f32_e32 v34, v34
	s_nop 0
	v_mul_f32_e32 v34, v39, v34
	v_mul_f32_e32 v47, v34, v35
	v_mul_f32_e32 v34, 0xbfb8aa3b, v40
	v_exp_f32_e32 v34, v34
	v_lshl_add_u64 v[38:39], v[50:51], 0, v[114:115]
	v_add_f32_e32 v34, 1.0, v34
	v_rcp_f32_e32 v34, v34
	s_nop 0
	v_mul_f32_e32 v34, v40, v34
	v_mul_f32_e32 v40, v34, v36
	v_mul_f32_e32 v34, 0xbfb8aa3b, v41
	v_exp_f32_e32 v34, v34
	s_nop 0
	v_add_f32_e32 v34, 1.0, v34
	v_rcp_f32_e32 v34, v34
	s_nop 0
	v_mul_f32_e32 v34, v41, v34
	v_mul_f32_e32 v37, v34, v37
	v_cvt_pk_bf16_f32 v34, v42, v43
	v_cvt_pk_bf16_f32 v35, v44, v45
	v_cvt_pk_bf16_f32 v36, v46, v47
	v_cvt_pk_bf16_f32 v37, v40, v37
	global_store_dwordx4 v[38:39], v[34:37], off
	s_nop 1
	v_mul_f32_e32 v36, 0xbfb8aa3b, v30
	v_exp_f32_e32 v36, v36
	v_add_u32_e32 v34, 0xa0, v139
	v_mad_i64_i32 v[34:35], s[6:7], v34, s74, v[134:135]
	v_add_f32_e32 v36, 1.0, v36
	v_rcp_f32_e32 v36, v36
	s_nop 0
	v_mul_f32_e32 v30, v30, v36
	v_mul_f32_e32 v26, v30, v26
	v_mul_f32_e32 v30, 0xbfb8aa3b, v31
	v_exp_f32_e32 v30, v30
	s_nop 0
	v_add_f32_e32 v30, 1.0, v30
	v_rcp_f32_e32 v30, v30
	s_nop 0
	v_mul_f32_e32 v30, v31, v30
	v_mul_f32_e32 v27, v30, v27
	v_mul_f32_e32 v30, 0xbfb8aa3b, v32
	v_exp_f32_e32 v30, v30
	s_nop 0
	v_add_f32_e32 v30, 1.0, v30
	v_rcp_f32_e32 v30, v30
	s_nop 0
	v_mul_f32_e32 v30, v32, v30
	v_mul_f32_e32 v28, v30, v28
	v_mul_f32_e32 v30, 0xbfb8aa3b, v33
	v_exp_f32_e32 v30, v30
	s_nop 0
	v_add_f32_e32 v30, 1.0, v30
	v_rcp_f32_e32 v30, v30
	s_nop 0
	v_mul_f32_e32 v30, v33, v30
	v_mul_f32_e32 v29, v30, v29
	v_mul_f32_e32 v30, 0xbfb8aa3b, v22
	v_exp_f32_e32 v30, v30
	s_nop 0
	v_add_f32_e32 v30, 1.0, v30
	v_rcp_f32_e32 v30, v30
	s_nop 0
	v_mul_f32_e32 v22, v22, v30
	v_mul_f32_e32 v30, v22, v18
	v_mul_f32_e32 v18, 0xbfb8aa3b, v23
	v_exp_f32_e32 v18, v18
	s_nop 0
	v_add_f32_e32 v18, 1.0, v18
	v_rcp_f32_e32 v18, v18
	s_nop 0
	v_mul_f32_e32 v18, v23, v18
	v_mul_f32_e32 v31, v18, v19
	v_mul_f32_e32 v18, 0xbfb8aa3b, v24
	v_exp_f32_e32 v18, v18
	v_lshl_add_u64 v[22:23], v[34:35], 0, v[114:115]
	v_add_f32_e32 v18, 1.0, v18
	v_rcp_f32_e32 v18, v18
	s_nop 0
	v_mul_f32_e32 v18, v24, v18
	v_mul_f32_e32 v24, v18, v20
	v_mul_f32_e32 v18, 0xbfb8aa3b, v25
	v_exp_f32_e32 v18, v18
	s_nop 0
	v_add_f32_e32 v18, 1.0, v18
	v_rcp_f32_e32 v18, v18
	s_nop 0
	v_mul_f32_e32 v18, v25, v18
	v_mul_f32_e32 v21, v18, v21
	v_cvt_pk_bf16_f32 v18, v26, v27
	v_cvt_pk_bf16_f32 v19, v28, v29
	v_cvt_pk_bf16_f32 v20, v30, v31
	v_cvt_pk_bf16_f32 v21, v24, v21
	global_store_dwordx4 v[22:23], v[18:21], off
	s_nop 1
	v_mul_f32_e32 v20, 0xbfb8aa3b, v14
	v_exp_f32_e32 v20, v20
	v_add_u32_e32 v18, 0xb0, v139
	v_mad_i64_i32 v[18:19], s[6:7], v18, s74, v[134:135]
	v_add_f32_e32 v20, 1.0, v20
	v_rcp_f32_e32 v20, v20
	s_mov_b64 s[6:7], s[42:43]
	v_mul_f32_e32 v14, v14, v20
	v_mul_f32_e32 v10, v14, v10
	v_mul_f32_e32 v14, 0xbfb8aa3b, v15
	v_exp_f32_e32 v14, v14
	s_nop 0
	v_add_f32_e32 v14, 1.0, v14
	v_rcp_f32_e32 v14, v14
	s_nop 0
	v_mul_f32_e32 v14, v15, v14
	v_mul_f32_e32 v11, v14, v11
	v_mul_f32_e32 v14, 0xbfb8aa3b, v16
	v_exp_f32_e32 v14, v14
	s_nop 0
	v_add_f32_e32 v14, 1.0, v14
	v_rcp_f32_e32 v14, v14
	s_nop 0
	v_mul_f32_e32 v14, v16, v14
	v_mul_f32_e32 v12, v14, v12
	v_mul_f32_e32 v14, 0xbfb8aa3b, v17
	v_exp_f32_e32 v14, v14
	s_nop 0
	v_add_f32_e32 v14, 1.0, v14
	v_rcp_f32_e32 v14, v14
	s_nop 0
	v_mul_f32_e32 v14, v17, v14
	v_mul_f32_e32 v13, v14, v13
	v_mul_f32_e32 v14, 0xbfb8aa3b, v6
	v_exp_f32_e32 v14, v14
	s_nop 0
	v_add_f32_e32 v14, 1.0, v14
	v_rcp_f32_e32 v14, v14
	s_nop 0
	v_mul_f32_e32 v6, v6, v14
	v_mul_f32_e32 v14, v6, v2
	v_mul_f32_e32 v2, 0xbfb8aa3b, v7
	v_exp_f32_e32 v2, v2
	s_nop 0
	v_add_f32_e32 v2, 1.0, v2
	v_rcp_f32_e32 v2, v2
	s_nop 0
	v_mul_f32_e32 v2, v7, v2
	v_mul_f32_e32 v15, v2, v3
	v_mul_f32_e32 v2, 0xbfb8aa3b, v8
	v_exp_f32_e32 v2, v2
	v_lshl_add_u64 v[6:7], v[18:19], 0, v[114:115]
	v_add_f32_e32 v2, 1.0, v2
	v_rcp_f32_e32 v2, v2
	s_nop 0
	v_mul_f32_e32 v2, v8, v2
	v_mul_f32_e32 v8, v2, v4
	v_mul_f32_e32 v2, 0xbfb8aa3b, v9
	v_exp_f32_e32 v2, v2
	s_nop 0
	v_add_f32_e32 v2, 1.0, v2
	v_rcp_f32_e32 v2, v2
	s_nop 0
	v_mul_f32_e32 v2, v9, v2
	v_mul_f32_e32 v5, v2, v5
	v_cvt_pk_bf16_f32 v2, v10, v11
	v_cvt_pk_bf16_f32 v3, v12, v13
	v_cvt_pk_bf16_f32 v4, v14, v15
	v_cvt_pk_bf16_f32 v5, v8, v5
	global_store_dwordx4 v[6:7], v[2:5], off
	s_cbranch_vccz .LBB0_48
	s_waitcnt vmcnt(0)
	v_readlane_b32 s0, v255, 8
	v_readlane_b32 s62, v255, 10
	v_readlane_b32 s84, v255, 12
	s_cmpk_gt_u32 s22, 0xff
	v_readlane_b32 s1, v255, 9
	s_mov_b64 s[58:59], s[92:93]
	v_readlane_b32 s63, v255, 11
	v_readlane_b32 s85, v255, 13
	s_cbranch_scc1 .LBB0_55
	s_barrier

.LBB0_97:
	s_add_u32 s7, s50, 0xfff80080
	s_addc_u32 s11, s51, -1
	s_add_i32 s43, 0, 0x10000
	v_add_u32_e32 v132, s43, v135
	ds_read_b128 v[138:141], v132
	ds_read_b128 v[142:145], v132 offset:1024
	ds_read_b128 v[148:151], v132 offset:2048
	ds_read_b128 v[152:155], v132 offset:3072
	s_cmp_eq_u32 s6, 28
	s_cselect_b32 s79, s45, s11
	s_cselect_b32 s78, s44, s7
	s_cselect_b32 s91, s47, s9
	s_cselect_b32 s90, s46, s8
	v_lshl_add_u64 v[132:133], s[50:51], 0, v[130:131]
	s_add_i32 m0, s49, 0xc000
	ds_read_b128 v[156:159], v136
	ds_read_b128 v[160:163], v136 offset:1024
	ds_read_b128 v[164:167], v136 offset:2048
	ds_read_b128 v[168:171], v136 offset:3072
	ds_read_b128 v[172:175], v136 offset:4096
	ds_read_b128 v[176:179], v136 offset:5120
	ds_read_b128 v[180:183], v136 offset:6144
	ds_read_b128 v[184:187], v136 offset:7168
	global_load_lds_dwordx4 v[132:133], off
	v_lshl_add_u64 v[132:133], v[132:133], 0, s[60:61]
	s_add_i32 m0, s49, 0xe000
	s_nop 0
	global_load_lds_dwordx4 v[132:133], off
	s_waitcnt lgkmcnt(8)
	s_setprio 1
	s_barrier
	s_waitcnt lgkmcnt(0)
	v_mfma_f32_16x16x32_bf16 v[126:129], v[138:141], v[156:159], v[126:129]
	v_mfma_f32_16x16x32_bf16 v[122:125], v[148:151], v[156:159], v[122:125]
	v_mfma_f32_16x16x32_bf16 v[118:121], v[138:141], v[164:167], v[118:121]
	v_mfma_f32_16x16x32_bf16 v[110:113], v[148:151], v[164:167], v[110:113]
	v_mfma_f32_16x16x32_bf16 v[102:105], v[138:141], v[172:175], v[102:105]
	v_mfma_f32_16x16x32_bf16 v[94:97], v[148:151], v[172:175], v[94:97]
	v_mfma_f32_16x16x32_bf16 v[86:89], v[138:141], v[180:183], v[86:89]
	v_mfma_f32_16x16x32_bf16 v[78:81], v[148:151], v[180:183], v[78:81]
	v_mfma_f32_16x16x32_bf16 v[126:129], v[142:145], v[160:163], v[126:129]
	v_mfma_f32_16x16x32_bf16 v[122:125], v[152:155], v[160:163], v[122:125]
	v_mfma_f32_16x16x32_bf16 v[118:121], v[142:145], v[168:171], v[118:121]
	v_mfma_f32_16x16x32_bf16 v[110:113], v[152:155], v[168:171], v[110:113]
	v_mfma_f32_16x16x32_bf16 v[102:105], v[142:145], v[176:179], v[102:105]
	v_mfma_f32_16x16x32_bf16 v[94:97], v[152:155], v[176:179], v[94:97]
	v_mfma_f32_16x16x32_bf16 v[86:89], v[142:145], v[184:187], v[86:89]
	v_mfma_f32_16x16x32_bf16 v[78:81], v[152:155], v[184:187], v[78:81]
	s_barrier
	s_setprio 0
	s_add_i32 s7, 0, 0x14000
	v_add_u32_e32 v132, s7, v135
	s_add_i32 s11, s43, s57
	ds_read_b128 v[188:191], v132
	ds_read_b128 v[192:195], v132 offset:1024
	ds_read_b128 v[196:199], v132 offset:2048
	ds_read_b128 v[200:203], v132 offset:3072
	v_lshl_add_u64 v[132:133], s[90:91], 0, v[0:1]
	s_mov_b32 m0, s11
	v_lshl_add_u64 v[204:205], v[132:133], 0, s[60:61]
	global_load_lds_dwordx4 v[132:133], off
	s_add_i32 m0, s11, 0x2000
	s_nop 0
	global_load_lds_dwordx4 v[204:205], off
	s_setprio 1
	s_barrier
	s_waitcnt lgkmcnt(0)
	v_mfma_f32_16x16x32_bf16 v[114:117], v[188:191], v[156:159], v[114:117]
	v_mfma_f32_16x16x32_bf16 v[106:109], v[196:199], v[156:159], v[106:109]
	v_mfma_f32_16x16x32_bf16 v[98:101], v[188:191], v[164:167], v[98:101]
	v_mfma_f32_16x16x32_bf16 v[90:93], v[196:199], v[164:167], v[90:93]
	v_mfma_f32_16x16x32_bf16 v[82:85], v[188:191], v[172:175], v[82:85]
	v_mfma_f32_16x16x32_bf16 v[74:77], v[196:199], v[172:175], v[74:77]
	v_mfma_f32_16x16x32_bf16 v[70:73], v[188:191], v[180:183], v[70:73]
	v_mfma_f32_16x16x32_bf16 v[66:69], v[196:199], v[180:183], v[66:69]
	v_mfma_f32_16x16x32_bf16 v[114:117], v[192:195], v[160:163], v[114:117]
	v_mfma_f32_16x16x32_bf16 v[106:109], v[200:203], v[160:163], v[106:109]
	v_mfma_f32_16x16x32_bf16 v[98:101], v[192:195], v[168:171], v[98:101]
	v_mfma_f32_16x16x32_bf16 v[90:93], v[200:203], v[168:171], v[90:93]
	v_mfma_f32_16x16x32_bf16 v[82:85], v[192:195], v[176:179], v[82:85]
	v_mfma_f32_16x16x32_bf16 v[74:77], v[200:203], v[176:179], v[74:77]
	v_mfma_f32_16x16x32_bf16 v[70:73], v[192:195], v[184:187], v[70:73]
	v_mfma_f32_16x16x32_bf16 v[66:69], v[200:203], v[184:187], v[66:69]
	s_barrier
	s_setprio 0
	s_mov_b32 m0, s49
	v_lshl_add_u64 v[204:205], s[78:79], 0, v[0:1]
	ds_read_b128 v[156:159], v136 offset:16384
	ds_read_b128 v[160:163], v136 offset:17408
	ds_read_b128 v[164:167], v136 offset:18432
	ds_read_b128 v[168:171], v136 offset:19456
	ds_read_b128 v[172:175], v136 offset:20480
	ds_read_b128 v[176:179], v136 offset:21504
	ds_read_b128 v[180:183], v136 offset:22528
	ds_read_b128 v[184:187], v136 offset:23552
	global_load_lds_dwordx4 v[204:205], off
	v_lshl_add_u64 v[206:207], v[204:205], 0, s[60:61]
	s_mov_b32 m0, s58
	s_nop 0
	global_load_lds_dwordx4 v[206:207], off
	s_setprio 1
	s_barrier
	s_waitcnt lgkmcnt(0)
	v_mfma_f32_16x16x32_bf16 v[62:65], v[138:141], v[156:159], v[62:65]
	v_mfma_f32_16x16x32_bf16 v[58:61], v[148:151], v[156:159], v[58:61]
	v_mfma_f32_16x16x32_bf16 v[54:57], v[138:141], v[164:167], v[54:57]
	v_mfma_f32_16x16x32_bf16 v[46:49], v[148:151], v[164:167], v[46:49]
	v_mfma_f32_16x16x32_bf16 v[38:41], v[138:141], v[172:175], v[38:41]
	v_mfma_f32_16x16x32_bf16 v[30:33], v[148:151], v[172:175], v[30:33]
	v_mfma_f32_16x16x32_bf16 v[22:25], v[138:141], v[180:183], v[22:25]
	v_mfma_f32_16x16x32_bf16 v[14:17], v[148:151], v[180:183], v[14:17]
	v_mfma_f32_16x16x32_bf16 v[62:65], v[142:145], v[160:163], v[62:65]
	v_mfma_f32_16x16x32_bf16 v[58:61], v[152:155], v[160:163], v[58:61]
	v_mfma_f32_16x16x32_bf16 v[54:57], v[142:145], v[168:171], v[54:57]
	v_mfma_f32_16x16x32_bf16 v[46:49], v[152:155], v[168:171], v[46:49]
	v_mfma_f32_16x16x32_bf16 v[38:41], v[142:145], v[176:179], v[38:41]
	v_mfma_f32_16x16x32_bf16 v[30:33], v[152:155], v[176:179], v[30:33]
	v_mfma_f32_16x16x32_bf16 v[22:25], v[142:145], v[184:187], v[22:25]
	v_mfma_f32_16x16x32_bf16 v[14:17], v[152:155], v[184:187], v[14:17]
	s_barrier
	s_setprio 0
	s_add_i32 s7, s7, s57
	v_lshl_add_u64 v[138:139], v[132:133], 0, s[20:21]
	s_mov_b32 m0, s7
	s_nop 0
	global_load_lds_dwordx4 v[138:139], off
	v_lshl_add_u64 v[138:139], v[132:133], 0, s[64:65]
	s_add_i32 m0, s7, 0x2000
	s_nop 0
	global_load_lds_dwordx4 v[138:139], off
	s_waitcnt vmcnt(6)
	s_setprio 1
	s_barrier
	v_mfma_f32_16x16x32_bf16 v[50:53], v[188:191], v[156:159], v[50:53]
	v_mfma_f32_16x16x32_bf16 v[42:45], v[196:199], v[156:159], v[42:45]
	v_mfma_f32_16x16x32_bf16 v[34:37], v[188:191], v[164:167], v[34:37]
	v_mfma_f32_16x16x32_bf16 v[26:29], v[196:199], v[164:167], v[26:29]
	v_mfma_f32_16x16x32_bf16 v[18:21], v[188:191], v[172:175], v[18:21]
	v_mfma_f32_16x16x32_bf16 v[10:13], v[196:199], v[172:175], v[10:13]
	v_mfma_f32_16x16x32_bf16 v[6:9], v[188:191], v[180:183], v[6:9]
	v_mfma_f32_16x16x32_bf16 v[2:5], v[196:199], v[180:183], v[2:5]
	v_mfma_f32_16x16x32_bf16 v[50:53], v[192:195], v[160:163], v[50:53]
	v_mfma_f32_16x16x32_bf16 v[42:45], v[200:203], v[160:163], v[42:45]
	v_mfma_f32_16x16x32_bf16 v[34:37], v[192:195], v[168:171], v[34:37]
	v_mfma_f32_16x16x32_bf16 v[26:29], v[200:203], v[168:171], v[26:29]
	v_mfma_f32_16x16x32_bf16 v[18:21], v[192:195], v[176:179], v[18:21]
	v_mfma_f32_16x16x32_bf16 v[10:13], v[200:203], v[176:179], v[10:13]
	v_mfma_f32_16x16x32_bf16 v[6:9], v[192:195], v[184:187], v[6:9]
	v_mfma_f32_16x16x32_bf16 v[2:5], v[200:203], v[184:187], v[2:5]
	s_barrier
	s_setprio 0
	s_add_i32 s7, 0, 0x18000
	v_add_u32_e32 v137, s7, v135
	ds_read_b128 v[138:141], v137
	ds_read_b128 v[142:145], v137 offset:1024
	ds_read_b128 v[148:151], v137 offset:2048
	ds_read_b128 v[152:155], v137 offset:3072
	s_mov_b32 m0, s59
	v_lshl_add_u64 v[188:189], v[204:205], 0, s[20:21]
	ds_read_b128 v[156:159], v136 offset:32768
	ds_read_b128 v[160:163], v136 offset:33792
	ds_read_b128 v[164:167], v136 offset:34816
	ds_read_b128 v[168:171], v136 offset:35840
	ds_read_b128 v[172:175], v136 offset:36864
	ds_read_b128 v[176:179], v136 offset:37888
	ds_read_b128 v[180:183], v136 offset:38912
	ds_read_b128 v[184:187], v136 offset:39936
	global_load_lds_dwordx4 v[188:189], off
	v_lshl_add_u64 v[188:189], v[204:205], 0, s[64:65]
	s_mov_b32 m0, s62
	s_nop 0
	global_load_lds_dwordx4 v[188:189], off
	s_waitcnt lgkmcnt(8)
	s_setprio 1
	s_barrier
	s_waitcnt lgkmcnt(0)
	v_mfma_f32_16x16x32_bf16 v[126:129], v[138:141], v[156:159], v[126:129]
	v_mfma_f32_16x16x32_bf16 v[122:125], v[148:151], v[156:159], v[122:125]
	v_mfma_f32_16x16x32_bf16 v[118:121], v[138:141], v[164:167], v[118:121]
	v_mfma_f32_16x16x32_bf16 v[110:113], v[148:151], v[164:167], v[110:113]
	v_mfma_f32_16x16x32_bf16 v[102:105], v[138:141], v[172:175], v[102:105]
	v_mfma_f32_16x16x32_bf16 v[94:97], v[148:151], v[172:175], v[94:97]
	v_mfma_f32_16x16x32_bf16 v[86:89], v[138:141], v[180:183], v[86:89]
	v_mfma_f32_16x16x32_bf16 v[78:81], v[148:151], v[180:183], v[78:81]
	v_mfma_f32_16x16x32_bf16 v[126:129], v[142:145], v[160:163], v[126:129]
	v_mfma_f32_16x16x32_bf16 v[122:125], v[152:155], v[160:163], v[122:125]
	v_mfma_f32_16x16x32_bf16 v[118:121], v[142:145], v[168:171], v[118:121]
	v_mfma_f32_16x16x32_bf16 v[110:113], v[152:155], v[168:171], v[110:113]
	v_mfma_f32_16x16x32_bf16 v[102:105], v[142:145], v[176:179], v[102:105]
	v_mfma_f32_16x16x32_bf16 v[94:97], v[152:155], v[176:179], v[94:97]
	v_mfma_f32_16x16x32_bf16 v[86:89], v[142:145], v[184:187], v[86:89]
	v_mfma_f32_16x16x32_bf16 v[78:81], v[152:155], v[184:187], v[78:81]
	s_barrier
	s_setprio 0
	s_add_i32 s11, 0, 0x1c000
	s_add_i32 s7, s7, s57
	v_add_u32_e32 v137, s11, v135
	v_lshl_add_u64 v[206:207], v[132:133], 0, s[34:35]
	s_mov_b32 m0, s7
	ds_read_b128 v[188:191], v137
	ds_read_b128 v[192:195], v137 offset:1024
	ds_read_b128 v[196:199], v137 offset:2048
	ds_read_b128 v[200:203], v137 offset:3072
	global_load_lds_dwordx4 v[206:207], off
	v_lshl_add_u64 v[206:207], v[132:133], 0, s[66:67]
	s_add_i32 m0, s7, 0x2000
	s_nop 0
	global_load_lds_dwordx4 v[206:207], off
	s_setprio 1
	s_barrier
	s_waitcnt lgkmcnt(0)
	v_mfma_f32_16x16x32_bf16 v[114:117], v[188:191], v[156:159], v[114:117]
	v_mfma_f32_16x16x32_bf16 v[106:109], v[196:199], v[156:159], v[106:109]
	v_mfma_f32_16x16x32_bf16 v[98:101], v[188:191], v[164:167], v[98:101]
	v_mfma_f32_16x16x32_bf16 v[90:93], v[196:199], v[164:167], v[90:93]
	v_mfma_f32_16x16x32_bf16 v[82:85], v[188:191], v[172:175], v[82:85]
	v_mfma_f32_16x16x32_bf16 v[74:77], v[196:199], v[172:175], v[74:77]
	v_mfma_f32_16x16x32_bf16 v[70:73], v[188:191], v[180:183], v[70:73]
	v_mfma_f32_16x16x32_bf16 v[66:69], v[196:199], v[180:183], v[66:69]
	v_mfma_f32_16x16x32_bf16 v[114:117], v[192:195], v[160:163], v[114:117]
	v_mfma_f32_16x16x32_bf16 v[106:109], v[200:203], v[160:163], v[106:109]
	v_mfma_f32_16x16x32_bf16 v[98:101], v[192:195], v[168:171], v[98:101]
	v_mfma_f32_16x16x32_bf16 v[90:93], v[200:203], v[168:171], v[90:93]
	v_mfma_f32_16x16x32_bf16 v[82:85], v[192:195], v[176:179], v[82:85]
	v_mfma_f32_16x16x32_bf16 v[74:77], v[200:203], v[176:179], v[74:77]
	v_mfma_f32_16x16x32_bf16 v[70:73], v[192:195], v[184:187], v[70:73]
	v_mfma_f32_16x16x32_bf16 v[66:69], v[200:203], v[184:187], v[66:69]
	s_barrier
	s_setprio 0
	s_mov_b32 m0, s85
	v_lshl_add_u64 v[206:207], v[204:205], 0, s[34:35]
	ds_read_b128 v[156:159], v136 offset:49152
	ds_read_b128 v[160:163], v136 offset:50176
	ds_read_b128 v[164:167], v136 offset:51200
	ds_read_b128 v[168:171], v136 offset:52224
	ds_read_b128 v[172:175], v136 offset:53248
	ds_read_b128 v[176:179], v136 offset:54272
	ds_read_b128 v[180:183], v136 offset:55296
	ds_read_b128 v[184:187], v136 offset:56320
	global_load_lds_dwordx4 v[206:207], off
	v_lshl_add_u64 v[204:205], v[204:205], 0, s[66:67]
	s_mov_b32 m0, s86
	s_nop 0
	global_load_lds_dwordx4 v[204:205], off
	s_setprio 1
	s_barrier
	s_waitcnt lgkmcnt(0)
	v_mfma_f32_16x16x32_bf16 v[62:65], v[138:141], v[156:159], v[62:65]
	v_mfma_f32_16x16x32_bf16 v[58:61], v[148:151], v[156:159], v[58:61]
	v_mfma_f32_16x16x32_bf16 v[54:57], v[138:141], v[164:167], v[54:57]
	v_mfma_f32_16x16x32_bf16 v[46:49], v[148:151], v[164:167], v[46:49]
	v_mfma_f32_16x16x32_bf16 v[38:41], v[138:141], v[172:175], v[38:41]
	v_mfma_f32_16x16x32_bf16 v[30:33], v[148:151], v[172:175], v[30:33]
	v_mfma_f32_16x16x32_bf16 v[22:25], v[138:141], v[180:183], v[22:25]
	v_mfma_f32_16x16x32_bf16 v[14:17], v[148:151], v[180:183], v[14:17]
	v_mfma_f32_16x16x32_bf16 v[62:65], v[142:145], v[160:163], v[62:65]
	v_mfma_f32_16x16x32_bf16 v[58:61], v[152:155], v[160:163], v[58:61]
	v_mfma_f32_16x16x32_bf16 v[54:57], v[142:145], v[168:171], v[54:57]
	v_mfma_f32_16x16x32_bf16 v[46:49], v[152:155], v[168:171], v[46:49]
	v_mfma_f32_16x16x32_bf16 v[38:41], v[142:145], v[176:179], v[38:41]
	v_mfma_f32_16x16x32_bf16 v[30:33], v[152:155], v[176:179], v[30:33]
	v_mfma_f32_16x16x32_bf16 v[22:25], v[142:145], v[184:187], v[22:25]
	v_mfma_f32_16x16x32_bf16 v[14:17], v[152:155], v[184:187], v[14:17]
	s_barrier
	s_setprio 0
	s_add_i32 s7, s11, s57
	v_lshl_add_u64 v[138:139], v[132:133], 0, s[16:17]
	s_mov_b32 m0, s7
	v_lshl_add_u64 v[132:133], v[132:133], 0, s[80:81]
	global_load_lds_dwordx4 v[138:139], off
	s_add_i32 m0, s7, 0x2000
	s_nop 0
	global_load_lds_dwordx4 v[132:133], off
	s_waitcnt vmcnt(6)
	s_setprio 1
	s_barrier
	v_mfma_f32_16x16x32_bf16 v[50:53], v[188:191], v[156:159], v[50:53]
	v_mfma_f32_16x16x32_bf16 v[42:45], v[196:199], v[156:159], v[42:45]
	v_mfma_f32_16x16x32_bf16 v[34:37], v[188:191], v[164:167], v[34:37]
	v_mfma_f32_16x16x32_bf16 v[26:29], v[196:199], v[164:167], v[26:29]
	v_mfma_f32_16x16x32_bf16 v[18:21], v[188:191], v[172:175], v[18:21]
	v_mfma_f32_16x16x32_bf16 v[10:13], v[196:199], v[172:175], v[10:13]
	v_mfma_f32_16x16x32_bf16 v[6:9], v[188:191], v[180:183], v[6:9]
	v_mfma_f32_16x16x32_bf16 v[2:5], v[196:199], v[180:183], v[2:5]
	v_mfma_f32_16x16x32_bf16 v[50:53], v[192:195], v[160:163], v[50:53]
	v_mfma_f32_16x16x32_bf16 v[42:45], v[200:203], v[160:163], v[42:45]
	v_mfma_f32_16x16x32_bf16 v[34:37], v[192:195], v[168:171], v[34:37]
	v_mfma_f32_16x16x32_bf16 v[26:29], v[200:203], v[168:171], v[26:29]
	v_mfma_f32_16x16x32_bf16 v[18:21], v[192:195], v[176:179], v[18:21]
	v_mfma_f32_16x16x32_bf16 v[10:13], v[200:203], v[176:179], v[10:13]
	v_mfma_f32_16x16x32_bf16 v[6:9], v[192:195], v[184:187], v[6:9]
	v_mfma_f32_16x16x32_bf16 v[2:5], v[200:203], v[184:187], v[2:5]
	s_barrier
	s_setprio 0
	s_add_i32 s6, s6, 2
	s_add_u32 s8, s8, 0x100
	s_addc_u32 s9, s9, 0
	s_add_u32 s50, s50, 0x100
	s_addc_u32 s51, s51, 0
	s_cmp_gt_u32 s6, 29
	s_cbranch_scc0 .LBB0_97
	v_mov_b32_e32 v137, v134
	s_lshl_b32 s6, s88, 8
	v_ashrrev_i32_e32 v132, 2, v137
	s_or_b32 s6, s6, s84
	v_and_b32_e32 v132, -4, v132
	v_add_u32_e32 v132, s6, v132
	s_lshl_b32 s6, s48, 8
	s_add_i32 s6, s6, s63
	v_and_or_b32 v188, v137, 15, s6
	v_ashrrev_i32_e32 v189, 31, v188
	v_ashrrev_i32_e32 v133, 31, v132
	v_lshlrev_b64 v[206:207], 13, v[188:189]
	v_or_b32_e32 v156, 16, v188
	v_or_b32_e32 v172, 32, v188
	v_or_b32_e32 v188, 48, v188
	v_lshlrev_b64 v[132:133], 2, v[132:133]
	v_ashrrev_i32_e32 v157, 31, v156
	v_ashrrev_i32_e32 v173, 31, v172
	v_ashrrev_i32_e32 v189, 31, v188
	v_lshl_add_u64 v[204:205], s[4:5], 0, v[132:133]
	v_lshlrev_b64 v[208:209], 13, v[156:157]
	v_lshlrev_b64 v[210:211], 13, v[172:173]
	v_lshlrev_b64 v[212:213], 13, v[188:189]
	v_lshl_add_u64 v[152:153], v[204:205], 0, v[206:207]
	v_lshl_add_u64 v[168:169], v[204:205], 0, v[208:209]
	v_lshl_add_u64 v[184:185], v[204:205], 0, v[210:211]
	v_lshl_add_u64 v[200:201], v[204:205], 0, v[212:213]
	global_load_dwordx4 v[138:141], v[152:153], off
	global_load_dwordx4 v[142:145], v[152:153], off offset:64
	global_load_dwordx4 v[148:151], v[152:153], off offset:512
	s_nop 0
	global_load_dwordx4 v[152:155], v[152:153], off offset:576
	s_nop 0
	global_load_dwordx4 v[156:159], v[168:169], off
	global_load_dwordx4 v[160:163], v[168:169], off offset:64
	global_load_dwordx4 v[164:167], v[168:169], off offset:512
	s_nop 0
	global_load_dwordx4 v[168:171], v[168:169], off offset:576
	s_nop 0
	global_load_dwordx4 v[172:175], v[184:185], off
	global_load_dwordx4 v[176:179], v[184:185], off offset:64
	global_load_dwordx4 v[180:183], v[184:185], off offset:512
	s_nop 0
	global_load_dwordx4 v[184:187], v[184:185], off offset:576
	s_nop 0
	global_load_dwordx4 v[188:191], v[200:201], off
	global_load_dwordx4 v[192:195], v[200:201], off offset:64
	global_load_dwordx4 v[196:199], v[200:201], off offset:512
	s_nop 0
	global_load_dwordx4 v[200:203], v[200:201], off offset:576
	s_waitcnt vmcnt(0) lgkmcnt(0)
	v_pk_add_f32 v[126:127], v[126:127], v[138:139]
	v_lshl_add_u64 v[138:139], s[4:5], 0, v[206:207]
	v_lshl_add_u64 v[138:139], v[138:139], 0, v[132:133]
	v_pk_add_f32 v[116:117], v[116:117], v[150:151]
	v_pk_add_f32 v[114:115], v[114:115], v[148:149]
	global_store_dwordx4 v[138:139], v[114:117], off offset:512
	v_pk_add_f32 v[100:101], v[100:101], v[166:167]
	v_pk_add_f32 v[98:99], v[98:99], v[164:165]
	v_lshl_add_u64 v[114:115], s[4:5], 0, v[208:209]
	v_lshl_add_u64 v[114:115], v[114:115], 0, v[132:133]
	global_store_dwordx4 v[114:115], v[98:101], off offset:512
	v_pk_add_f32 v[84:85], v[84:85], v[182:183]
	v_pk_add_f32 v[82:83], v[82:83], v[180:181]
	v_lshl_add_u64 v[98:99], s[4:5], 0, v[210:211]
	v_lshl_add_u64 v[98:99], v[98:99], 0, v[132:133]
	v_pk_add_f32 v[108:109], v[108:109], v[154:155]
	v_pk_add_f32 v[106:107], v[106:107], v[152:153]
	v_pk_add_f32 v[92:93], v[92:93], v[170:171]
	v_pk_add_f32 v[90:91], v[90:91], v[168:169]
	global_store_dwordx4 v[98:99], v[82:85], off offset:512
	v_pk_add_f32 v[76:77], v[76:77], v[186:187]
	v_pk_add_f32 v[74:75], v[74:75], v[184:185]
	v_lshl_add_u64 v[82:83], s[4:5], 0, v[212:213]
	global_store_dwordx4 v[138:139], v[106:109], off offset:576
	global_store_dwordx4 v[114:115], v[90:93], off offset:576
	global_store_dwordx4 v[98:99], v[74:77], off offset:576
	v_pk_add_f32 v[108:109], v[120:121], v[158:159]
	v_pk_add_f32 v[106:107], v[118:119], v[156:157]
	v_pk_add_f32 v[92:93], v[104:105], v[174:175]
	v_pk_add_f32 v[90:91], v[102:103], v[172:173]
	v_pk_add_f32 v[76:77], v[88:89], v[190:191]
	v_pk_add_f32 v[74:75], v[86:87], v[188:189]
	v_lshl_add_u64 v[82:83], v[82:83], 0, v[132:133]
	v_pk_add_f32 v[128:129], v[128:129], v[140:141]
	v_pk_add_f32 v[124:125], v[124:125], v[144:145]
	v_pk_add_f32 v[122:123], v[122:123], v[142:143]
	global_store_dwordx4 v[114:115], v[106:109], off
	global_store_dwordx4 v[98:99], v[90:93], off
	global_store_dwordx4 v[82:83], v[74:77], off
	v_pk_add_f32 v[108:109], v[112:113], v[162:163]
	v_pk_add_f32 v[106:107], v[110:111], v[160:161]
	v_pk_add_f32 v[92:93], v[96:97], v[178:179]
	v_pk_add_f32 v[90:91], v[94:95], v[176:177]
	v_pk_add_f32 v[76:77], v[80:81], v[194:195]
	v_pk_add_f32 v[74:75], v[78:79], v[192:193]
	v_pk_add_f32 v[72:73], v[72:73], v[198:199]
	v_pk_add_f32 v[70:71], v[70:71], v[196:197]
	v_pk_add_f32 v[68:69], v[68:69], v[202:203]
	v_pk_add_f32 v[66:67], v[66:67], v[200:201]
	global_store_dwordx4 v[138:139], v[126:129], off
	global_store_dwordx4 v[138:139], v[122:125], off offset:64
	global_store_dwordx4 v[114:115], v[106:109], off offset:64
	global_store_dwordx4 v[98:99], v[90:93], off offset:64
	global_store_dwordx4 v[82:83], v[74:77], off offset:64
	global_store_dwordx4 v[82:83], v[70:73], off offset:512
	global_store_dwordx4 v[82:83], v[66:69], off offset:576
	s_mov_b64 s[6:7], 0x120000
	v_lshl_add_u64 v[140:141], v[206:207], 0, s[6:7]
	s_mov_b64 s[6:7], 0x140000
	v_lshl_add_u64 v[138:139], v[206:207], 0, s[0:1]
	v_lshl_add_u64 v[142:143], v[206:207], 0, s[6:7]
	v_lshl_add_u64 v[144:145], v[206:207], 0, s[28:29]
	v_lshl_add_u64 v[78:79], v[204:205], 0, v[138:139]
	v_lshl_add_u64 v[94:95], v[204:205], 0, v[140:141]
	v_lshl_add_u64 v[110:111], v[204:205], 0, v[142:143]
	v_lshl_add_u64 v[126:127], v[204:205], 0, v[144:145]
	global_load_dwordx4 v[66:69], v[78:79], off
	global_load_dwordx4 v[70:73], v[78:79], off offset:64
	global_load_dwordx4 v[74:77], v[78:79], off offset:512
	s_nop 0
	global_load_dwordx4 v[78:81], v[78:79], off offset:576
	s_nop 0
	global_load_dwordx4 v[82:85], v[94:95], off
	global_load_dwordx4 v[86:89], v[94:95], off offset:64
	global_load_dwordx4 v[90:93], v[94:95], off offset:512
	s_nop 0
	global_load_dwordx4 v[94:97], v[94:95], off offset:576
	s_nop 0
	global_load_dwordx4 v[98:101], v[110:111], off
	global_load_dwordx4 v[102:105], v[110:111], off offset:64
	global_load_dwordx4 v[106:109], v[110:111], off offset:512
	s_nop 0
	global_load_dwordx4 v[110:113], v[110:111], off offset:576
	s_nop 0
	global_load_dwordx4 v[114:117], v[126:127], off
	global_load_dwordx4 v[118:121], v[126:127], off offset:64
	global_load_dwordx4 v[122:125], v[126:127], off offset:512
	s_nop 0
	global_load_dwordx4 v[126:129], v[126:127], off offset:576
	s_waitcnt vmcnt(0) lgkmcnt(0)
	v_pk_add_f32 v[62:63], v[62:63], v[66:67]
	v_lshl_add_u64 v[66:67], s[4:5], 0, v[138:139]
	v_lshl_add_u64 v[66:67], v[66:67], 0, v[132:133]
	v_pk_add_f32 v[52:53], v[52:53], v[76:77]
	v_pk_add_f32 v[50:51], v[50:51], v[74:75]
	global_store_dwordx4 v[66:67], v[50:53], off offset:512
	v_pk_add_f32 v[36:37], v[36:37], v[92:93]
	v_pk_add_f32 v[34:35], v[34:35], v[90:91]
	v_lshl_add_u64 v[50:51], s[4:5], 0, v[140:141]
	v_lshl_add_u64 v[50:51], v[50:51], 0, v[132:133]
	global_store_dwordx4 v[50:51], v[34:37], off offset:512
	v_pk_add_f32 v[20:21], v[20:21], v[108:109]
	v_pk_add_f32 v[18:19], v[18:19], v[106:107]
	v_lshl_add_u64 v[34:35], s[4:5], 0, v[142:143]
	v_lshl_add_u64 v[34:35], v[34:35], 0, v[132:133]
	v_pk_add_f32 v[44:45], v[44:45], v[80:81]
	v_pk_add_f32 v[42:43], v[42:43], v[78:79]
	v_pk_add_f32 v[28:29], v[28:29], v[96:97]
	v_pk_add_f32 v[26:27], v[26:27], v[94:95]
	global_store_dwordx4 v[34:35], v[18:21], off offset:512
	v_pk_add_f32 v[12:13], v[12:13], v[112:113]
	v_pk_add_f32 v[10:11], v[10:11], v[110:111]
	v_lshl_add_u64 v[18:19], s[4:5], 0, v[144:145]
	global_store_dwordx4 v[66:67], v[42:45], off offset:576
	global_store_dwordx4 v[50:51], v[26:29], off offset:576
	global_store_dwordx4 v[34:35], v[10:13], off offset:576
	v_pk_add_f32 v[44:45], v[56:57], v[84:85]
	v_pk_add_f32 v[42:43], v[54:55], v[82:83]
	v_pk_add_f32 v[28:29], v[40:41], v[100:101]
	v_pk_add_f32 v[26:27], v[38:39], v[98:99]
	v_pk_add_f32 v[12:13], v[24:25], v[116:117]
	v_pk_add_f32 v[10:11], v[22:23], v[114:115]
	v_lshl_add_u64 v[18:19], v[18:19], 0, v[132:133]
	v_pk_add_f32 v[64:65], v[64:65], v[68:69]
	v_pk_add_f32 v[60:61], v[60:61], v[72:73]
	v_pk_add_f32 v[58:59], v[58:59], v[70:71]
	global_store_dwordx4 v[50:51], v[42:45], off
	global_store_dwordx4 v[34:35], v[26:29], off
	global_store_dwordx4 v[18:19], v[10:13], off
	v_pk_add_f32 v[44:45], v[48:49], v[88:89]
	v_pk_add_f32 v[42:43], v[46:47], v[86:87]
	v_pk_add_f32 v[28:29], v[32:33], v[104:105]
	v_pk_add_f32 v[26:27], v[30:31], v[102:103]
	v_pk_add_f32 v[12:13], v[16:17], v[120:121]
	v_pk_add_f32 v[10:11], v[14:15], v[118:119]
	v_pk_add_f32 v[8:9], v[8:9], v[124:125]
	v_pk_add_f32 v[6:7], v[6:7], v[122:123]
	v_pk_add_f32 v[4:5], v[4:5], v[128:129]
	v_pk_add_f32 v[2:3], v[2:3], v[126:127]
	global_store_dwordx4 v[66:67], v[62:65], off
	global_store_dwordx4 v[66:67], v[58:61], off offset:64
	global_store_dwordx4 v[50:51], v[42:45], off offset:64
	global_store_dwordx4 v[34:35], v[26:29], off offset:64
	global_store_dwordx4 v[18:19], v[10:13], off offset:64
	global_store_dwordx4 v[18:19], v[6:9], off offset:512
	global_store_dwordx4 v[18:19], v[2:5], off offset:576
	v_readlane_b32 s50, v255, 28
	s_and_b64 vcc, exec, s[40:41]
	s_mov_b32 s48, s42
	s_mov_b32 s88, s10
	s_mov_b64 s[8:9], s[46:47]
	s_mov_b64 s[6:7], s[44:45]
	v_readlane_b32 s51, v255, 29
	s_movk_i32 s91, 0x60
	s_mov_b32 s78, 0x2a000000
	s_mov_b32 s79, 0x3fffe
	s_mov_b32 s90, 0xc0000
	s_cbranch_vccz .LBB0_90
	s_waitcnt vmcnt(0)
	s_cmpk_gt_u32 s52, 0xff
	s_cbranch_scc1 .LBB0_101
	s_barrier

.LBB0_229:
	s_add_i32 s11, 0, 0x10000
	v_add_u32_e32 v206, s11, v148
	ds_read_b128 v[4:7], v206
	ds_read_b128 v[8:11], v206 offset:1024
	ds_read_b128 v[12:15], v206 offset:2048
	ds_read_b128 v[16:19], v206 offset:3072
	v_lshl_add_u64 v[2:3], s[8:9], 0, v[138:139]
	s_add_i32 s10, s57, 0xc000
	v_lshl_add_u64 v[52:53], v[2:3], 0, s[72:73]
	s_mov_b32 m0, s10
	s_mov_b64 vcc, 0x18080
	s_add_i32 s8, s57, 0xe000
	ds_read_b128 v[20:23], v149
	ds_read_b128 v[24:27], v149 offset:1024
	ds_read_b128 v[28:31], v149 offset:2048
	ds_read_b128 v[32:35], v149 offset:3072
	ds_read_b128 v[36:39], v149 offset:4096
	ds_read_b128 v[40:43], v149 offset:5120
	ds_read_b128 v[44:47], v149 offset:6144
	ds_read_b128 v[48:51], v149 offset:7168
	global_load_lds_dwordx4 v[52:53], off
	v_lshl_add_u64 v[52:53], v[2:3], 0, vcc
	s_mov_b32 m0, s8
	s_nop 0
	global_load_lds_dwordx4 v[52:53], off
	s_waitcnt lgkmcnt(8)
	s_setprio 1
	s_barrier
	s_waitcnt lgkmcnt(0)
	v_mfma_f32_16x16x32_bf16 v[52:55], v[4:7], v[20:23], 0
	v_mfma_f32_16x16x32_bf16 v[56:59], v[12:15], v[20:23], 0
	v_mfma_f32_16x16x32_bf16 v[60:63], v[4:7], v[28:31], 0
	v_mfma_f32_16x16x32_bf16 v[64:67], v[12:15], v[28:31], 0
	v_mfma_f32_16x16x32_bf16 v[68:71], v[4:7], v[36:39], 0
	v_mfma_f32_16x16x32_bf16 v[72:75], v[12:15], v[36:39], 0
	v_mfma_f32_16x16x32_bf16 v[80:83], v[12:15], v[44:47], 0
	v_mfma_f32_16x16x32_bf16 v[52:55], v[8:11], v[24:27], v[52:55]
	v_mfma_f32_16x16x32_bf16 v[56:59], v[16:19], v[24:27], v[56:59]
	v_mfma_f32_16x16x32_bf16 v[60:63], v[8:11], v[32:35], v[60:63]
	v_mfma_f32_16x16x32_bf16 v[64:67], v[16:19], v[32:35], v[64:67]
	v_mfma_f32_16x16x32_bf16 v[68:71], v[8:11], v[40:43], v[68:71]
	v_mfma_f32_16x16x32_bf16 v[72:75], v[16:19], v[40:43], v[72:75]
	v_mfma_f32_16x16x32_bf16 v[76:79], v[4:7], v[44:47], 0
	v_mfma_f32_16x16x32_bf16 v[80:83], v[16:19], v[48:51], v[80:83]
	v_mfma_f32_16x16x32_bf16 v[76:79], v[8:11], v[48:51], v[76:79]
	s_barrier
	s_setprio 0
	s_add_i32 s9, 0, 0x14000
	v_lshl_add_u64 v[136:137], s[6:7], 0, v[0:1]
	s_mov_b64 s[40:41], 0x100
	s_add_i32 s11, s11, s56
	v_add_u32_e32 v207, s9, v148
	v_lshl_add_u64 v[100:101], v[136:137], 0, s[40:41]
	s_mov_b32 m0, s11
	s_mov_b64 s[78:79], 0x8100
	s_add_i32 s6, s11, 0x2000
	ds_read_b128 v[84:87], v207
	ds_read_b128 v[88:91], v207 offset:1024
	ds_read_b128 v[92:95], v207 offset:2048
	ds_read_b128 v[96:99], v207 offset:3072
	global_load_lds_dwordx4 v[100:101], off
	v_lshl_add_u64 v[100:101], v[136:137], 0, s[78:79]
	s_mov_b32 m0, s6
	s_nop 0
	global_load_lds_dwordx4 v[100:101], off
	s_setprio 1
	s_barrier
	s_waitcnt lgkmcnt(0)
	v_mfma_f32_16x16x32_bf16 v[100:103], v[84:87], v[20:23], 0
	v_mfma_f32_16x16x32_bf16 v[20:23], v[92:95], v[20:23], 0
	v_mfma_f32_16x16x32_bf16 v[100:103], v[88:91], v[24:27], v[100:103]
	v_mfma_f32_16x16x32_bf16 v[20:23], v[96:99], v[24:27], v[20:23]
	v_mfma_f32_16x16x32_bf16 v[24:27], v[84:87], v[28:31], 0
	v_mfma_f32_16x16x32_bf16 v[28:31], v[92:95], v[28:31], 0
	v_mfma_f32_16x16x32_bf16 v[24:27], v[88:91], v[32:35], v[24:27]
	v_mfma_f32_16x16x32_bf16 v[28:31], v[96:99], v[32:35], v[28:31]
	v_mfma_f32_16x16x32_bf16 v[32:35], v[84:87], v[36:39], 0
	v_mfma_f32_16x16x32_bf16 v[36:39], v[92:95], v[36:39], 0
	v_mfma_f32_16x16x32_bf16 v[32:35], v[88:91], v[40:43], v[32:35]
	v_mfma_f32_16x16x32_bf16 v[36:39], v[96:99], v[40:43], v[36:39]
	v_mfma_f32_16x16x32_bf16 v[40:43], v[84:87], v[44:47], 0
	v_mfma_f32_16x16x32_bf16 v[44:47], v[92:95], v[44:47], 0
	v_mfma_f32_16x16x32_bf16 v[40:43], v[88:91], v[48:51], v[40:43]
	v_mfma_f32_16x16x32_bf16 v[44:47], v[96:99], v[48:51], v[44:47]
	s_barrier
	s_setprio 0
	s_mov_b32 m0, s57
	v_lshl_add_u64 v[132:133], v[2:3], 0, s[40:41]
	ds_read_b128 v[48:51], v149 offset:16384
	ds_read_b128 v[104:107], v149 offset:17408
	ds_read_b128 v[108:111], v149 offset:18432
	ds_read_b128 v[112:115], v149 offset:19456
	ds_read_b128 v[116:119], v149 offset:20480
	ds_read_b128 v[120:123], v149 offset:21504
	ds_read_b128 v[124:127], v149 offset:22528
	ds_read_b128 v[128:131], v149 offset:23552
	global_load_lds_dwordx4 v[132:133], off
	v_lshl_add_u64 v[132:133], v[2:3], 0, s[78:79]
	s_mov_b32 m0, s58
	s_nop 0
	global_load_lds_dwordx4 v[132:133], off
	s_setprio 1
	s_barrier
	s_waitcnt lgkmcnt(0)
	v_mfma_f32_16x16x32_bf16 v[132:135], v[4:7], v[48:51], 0
	v_mfma_f32_16x16x32_bf16 v[150:153], v[4:7], v[108:111], 0
	v_mfma_f32_16x16x32_bf16 v[158:161], v[4:7], v[116:119], 0
	v_mfma_f32_16x16x32_bf16 v[4:7], v[4:7], v[124:127], 0
	v_mfma_f32_16x16x32_bf16 v[132:135], v[8:11], v[104:107], v[132:135]
	v_mfma_f32_16x16x32_bf16 v[150:153], v[8:11], v[112:115], v[150:153]
	v_mfma_f32_16x16x32_bf16 v[158:161], v[8:11], v[120:123], v[158:161]
	v_mfma_f32_16x16x32_bf16 v[4:7], v[8:11], v[128:131], v[4:7]
	v_mfma_f32_16x16x32_bf16 v[8:11], v[12:15], v[124:127], 0
	v_mfma_f32_16x16x32_bf16 v[140:143], v[12:15], v[48:51], 0
	v_mfma_f32_16x16x32_bf16 v[154:157], v[12:15], v[108:111], 0
	v_mfma_f32_16x16x32_bf16 v[162:165], v[12:15], v[116:119], 0
	v_mfma_f32_16x16x32_bf16 v[8:11], v[16:19], v[128:131], v[8:11]
	v_mfma_f32_16x16x32_bf16 v[140:143], v[16:19], v[104:107], v[140:143]
	v_mfma_f32_16x16x32_bf16 v[154:157], v[16:19], v[112:115], v[154:157]
	v_mfma_f32_16x16x32_bf16 v[162:165], v[16:19], v[120:123], v[162:165]
	s_barrier
	s_setprio 0
	s_mov_b64 s[40:41], 0x10100
	s_add_i32 s9, s9, s56
	v_lshl_add_u64 v[12:13], v[136:137], 0, s[40:41]
	s_mov_b32 m0, s9
	s_mov_b64 s[78:79], 0x18100
	s_add_i32 s7, s9, 0x2000
	global_load_lds_dwordx4 v[12:13], off
	v_lshl_add_u64 v[12:13], v[136:137], 0, s[78:79]
	s_mov_b32 m0, s7
	s_nop 0
	global_load_lds_dwordx4 v[12:13], off
	s_waitcnt vmcnt(6)
	s_setprio 1
	s_barrier
	v_mfma_f32_16x16x32_bf16 v[12:15], v[84:87], v[48:51], 0
	v_mfma_f32_16x16x32_bf16 v[16:19], v[92:95], v[48:51], 0
	v_mfma_f32_16x16x32_bf16 v[12:15], v[88:91], v[104:107], v[12:15]
	v_mfma_f32_16x16x32_bf16 v[16:19], v[96:99], v[104:107], v[16:19]
	v_mfma_f32_16x16x32_bf16 v[48:51], v[84:87], v[108:111], 0
	v_mfma_f32_16x16x32_bf16 v[104:107], v[92:95], v[108:111], 0
	v_mfma_f32_16x16x32_bf16 v[108:111], v[84:87], v[116:119], 0
	v_mfma_f32_16x16x32_bf16 v[84:87], v[84:87], v[124:127], 0
	v_mfma_f32_16x16x32_bf16 v[48:51], v[88:91], v[112:115], v[48:51]
	v_mfma_f32_16x16x32_bf16 v[104:107], v[96:99], v[112:115], v[104:107]
	v_mfma_f32_16x16x32_bf16 v[108:111], v[88:91], v[120:123], v[108:111]
	v_mfma_f32_16x16x32_bf16 v[112:115], v[92:95], v[116:119], 0
	v_mfma_f32_16x16x32_bf16 v[84:87], v[88:91], v[128:131], v[84:87]
	v_mfma_f32_16x16x32_bf16 v[88:91], v[92:95], v[124:127], 0
	v_mfma_f32_16x16x32_bf16 v[112:115], v[96:99], v[120:123], v[112:115]
	v_mfma_f32_16x16x32_bf16 v[88:91], v[96:99], v[128:131], v[88:91]
	s_barrier
	s_setprio 0
	s_add_i32 s53, 0, 0x18000
	v_add_u32_e32 v222, s53, v148
	ds_read_b128 v[92:95], v222
	ds_read_b128 v[96:99], v222 offset:1024
	ds_read_b128 v[116:119], v222 offset:2048
	ds_read_b128 v[120:123], v222 offset:3072
	s_mov_b32 m0, s59
	v_lshl_add_u64 v[144:145], v[2:3], 0, s[40:41]
	ds_read_b128 v[124:127], v149 offset:32768
	ds_read_b128 v[128:131], v149 offset:33792
	ds_read_b128 v[166:169], v149 offset:34816
	ds_read_b128 v[170:173], v149 offset:35840
	ds_read_b128 v[174:177], v149 offset:36864
	ds_read_b128 v[178:181], v149 offset:37888
	ds_read_b128 v[182:185], v149 offset:38912
	ds_read_b128 v[186:189], v149 offset:39936
	global_load_lds_dwordx4 v[144:145], off
	v_lshl_add_u64 v[144:145], v[2:3], 0, s[78:79]
	s_mov_b32 m0, s62
	s_nop 0
	global_load_lds_dwordx4 v[144:145], off
	s_waitcnt lgkmcnt(8)
	s_setprio 1
	s_barrier
	s_waitcnt lgkmcnt(0)
	v_mfma_f32_16x16x32_bf16 v[52:55], v[92:95], v[124:127], v[52:55]
	v_mfma_f32_16x16x32_bf16 v[56:59], v[116:119], v[124:127], v[56:59]
	v_mfma_f32_16x16x32_bf16 v[60:63], v[92:95], v[166:169], v[60:63]
	v_mfma_f32_16x16x32_bf16 v[64:67], v[116:119], v[166:169], v[64:67]
	v_mfma_f32_16x16x32_bf16 v[68:71], v[92:95], v[174:177], v[68:71]
	v_mfma_f32_16x16x32_bf16 v[72:75], v[116:119], v[174:177], v[72:75]
	v_mfma_f32_16x16x32_bf16 v[80:83], v[116:119], v[182:185], v[80:83]
	v_mfma_f32_16x16x32_bf16 v[52:55], v[96:99], v[128:131], v[52:55]
	v_mfma_f32_16x16x32_bf16 v[56:59], v[120:123], v[128:131], v[56:59]
	v_mfma_f32_16x16x32_bf16 v[60:63], v[96:99], v[170:173], v[60:63]
	v_mfma_f32_16x16x32_bf16 v[64:67], v[120:123], v[170:173], v[64:67]
	v_mfma_f32_16x16x32_bf16 v[68:71], v[96:99], v[178:181], v[68:71]
	v_mfma_f32_16x16x32_bf16 v[72:75], v[120:123], v[178:181], v[72:75]
	v_mfma_f32_16x16x32_bf16 v[76:79], v[92:95], v[182:185], v[76:79]
	v_mfma_f32_16x16x32_bf16 v[80:83], v[120:123], v[186:189], v[80:83]
	v_mfma_f32_16x16x32_bf16 v[76:79], v[96:99], v[186:189], v[76:79]
	s_barrier
	s_setprio 0
	s_add_i32 s41, 0, 0x1c000
	s_mov_b64 s[78:79], 0x180
	s_add_i32 s53, s53, s56
	v_add_u32_e32 v226, s41, v148
	v_lshl_add_u64 v[144:145], v[136:137], 0, s[78:79]
	s_mov_b32 m0, s53
	s_mov_b64 s[0:1], 0x8180
	s_add_i32 s22, s53, 0x2000
	ds_read_b128 v[190:193], v226
	ds_read_b128 v[194:197], v226 offset:1024
	ds_read_b128 v[198:201], v226 offset:2048
	ds_read_b128 v[202:205], v226 offset:3072
	global_load_lds_dwordx4 v[144:145], off
	v_lshl_add_u64 v[144:145], v[136:137], 0, s[0:1]
	s_mov_b32 m0, s22
	s_nop 0
	global_load_lds_dwordx4 v[144:145], off
	s_setprio 1
	s_barrier
	s_waitcnt lgkmcnt(0)
	v_mfma_f32_16x16x32_bf16 v[100:103], v[190:193], v[124:127], v[100:103]
	v_mfma_f32_16x16x32_bf16 v[20:23], v[198:201], v[124:127], v[20:23]
	v_mfma_f32_16x16x32_bf16 v[24:27], v[190:193], v[166:169], v[24:27]
	v_mfma_f32_16x16x32_bf16 v[28:31], v[198:201], v[166:169], v[28:31]
	v_mfma_f32_16x16x32_bf16 v[32:35], v[190:193], v[174:177], v[32:35]
	v_mfma_f32_16x16x32_bf16 v[36:39], v[198:201], v[174:177], v[36:39]
	v_mfma_f32_16x16x32_bf16 v[40:43], v[190:193], v[182:185], v[40:43]
	v_mfma_f32_16x16x32_bf16 v[44:47], v[198:201], v[182:185], v[44:47]
	v_mfma_f32_16x16x32_bf16 v[100:103], v[194:197], v[128:131], v[100:103]
	v_mfma_f32_16x16x32_bf16 v[20:23], v[202:205], v[128:131], v[20:23]
	v_mfma_f32_16x16x32_bf16 v[24:27], v[194:197], v[170:173], v[24:27]
	v_mfma_f32_16x16x32_bf16 v[28:31], v[202:205], v[170:173], v[28:31]
	v_mfma_f32_16x16x32_bf16 v[32:35], v[194:197], v[178:181], v[32:35]
	v_mfma_f32_16x16x32_bf16 v[36:39], v[202:205], v[178:181], v[36:39]
	v_mfma_f32_16x16x32_bf16 v[40:43], v[194:197], v[186:189], v[40:43]
	v_mfma_f32_16x16x32_bf16 v[44:47], v[202:205], v[186:189], v[44:47]
	s_barrier
	s_setprio 0
	s_mov_b32 m0, s85
	v_lshl_add_u64 v[144:145], v[2:3], 0, s[78:79]
	ds_read_b128 v[124:127], v149 offset:49152
	ds_read_b128 v[128:131], v149 offset:50176
	ds_read_b128 v[166:169], v149 offset:51200
	ds_read_b128 v[170:173], v149 offset:52224
	ds_read_b128 v[174:177], v149 offset:53248
	ds_read_b128 v[178:181], v149 offset:54272
	ds_read_b128 v[182:185], v149 offset:55296
	ds_read_b128 v[186:189], v149 offset:56320
	global_load_lds_dwordx4 v[144:145], off
	v_lshl_add_u64 v[144:145], v[2:3], 0, s[0:1]
	s_mov_b32 m0, s86
	s_nop 0
	global_load_lds_dwordx4 v[144:145], off
	s_setprio 1
	s_barrier
	s_waitcnt lgkmcnt(0)
	v_mfma_f32_16x16x32_bf16 v[132:135], v[92:95], v[124:127], v[132:135]
	v_mfma_f32_16x16x32_bf16 v[150:153], v[92:95], v[166:169], v[150:153]
	v_mfma_f32_16x16x32_bf16 v[4:7], v[92:95], v[182:185], v[4:7]
	v_mfma_f32_16x16x32_bf16 v[8:11], v[116:119], v[182:185], v[8:11]
	v_mfma_f32_16x16x32_bf16 v[132:135], v[96:99], v[128:131], v[132:135]
	v_mfma_f32_16x16x32_bf16 v[140:143], v[116:119], v[124:127], v[140:143]
	v_mfma_f32_16x16x32_bf16 v[150:153], v[96:99], v[170:173], v[150:153]
	v_mfma_f32_16x16x32_bf16 v[154:157], v[116:119], v[166:169], v[154:157]
	v_mfma_f32_16x16x32_bf16 v[158:161], v[92:95], v[174:177], v[158:161]
	v_mfma_f32_16x16x32_bf16 v[162:165], v[116:119], v[174:177], v[162:165]
	v_mfma_f32_16x16x32_bf16 v[4:7], v[96:99], v[186:189], v[4:7]
	v_mfma_f32_16x16x32_bf16 v[8:11], v[120:123], v[186:189], v[8:11]
	v_mfma_f32_16x16x32_bf16 v[140:143], v[120:123], v[128:131], v[140:143]
	v_mfma_f32_16x16x32_bf16 v[154:157], v[120:123], v[170:173], v[154:157]
	v_mfma_f32_16x16x32_bf16 v[158:161], v[96:99], v[178:181], v[158:161]
	v_mfma_f32_16x16x32_bf16 v[162:165], v[120:123], v[178:181], v[162:165]
	s_barrier
	s_setprio 0
	s_mov_b64 s[0:1], 0x10180
	s_add_i32 s41, s41, s56
	v_lshl_add_u64 v[92:93], v[136:137], 0, s[0:1]
	s_mov_b32 m0, s41
	s_mov_b64 s[78:79], 0x18180
	s_add_i32 s40, s41, 0x2000
	global_load_lds_dwordx4 v[92:93], off
	v_lshl_add_u64 v[92:93], v[136:137], 0, s[78:79]
	s_mov_b32 m0, s40
	s_nop 0
	global_load_lds_dwordx4 v[92:93], off
	s_waitcnt vmcnt(6)
	s_setprio 1
	s_barrier
	v_mfma_f32_16x16x32_bf16 v[12:15], v[190:193], v[124:127], v[12:15]
	v_mfma_f32_16x16x32_bf16 v[16:19], v[198:201], v[124:127], v[16:19]
	v_mfma_f32_16x16x32_bf16 v[48:51], v[190:193], v[166:169], v[48:51]
	v_mfma_f32_16x16x32_bf16 v[92:95], v[198:201], v[166:169], v[104:107]
	v_mfma_f32_16x16x32_bf16 v[96:99], v[190:193], v[174:177], v[108:111]
	v_mfma_f32_16x16x32_bf16 v[104:107], v[198:201], v[174:177], v[112:115]
	v_mfma_f32_16x16x32_bf16 v[84:87], v[190:193], v[182:185], v[84:87]
	v_mfma_f32_16x16x32_bf16 v[88:91], v[198:201], v[182:185], v[88:91]
	v_mfma_f32_16x16x32_bf16 v[12:15], v[194:197], v[128:131], v[12:15]
	v_mfma_f32_16x16x32_bf16 v[16:19], v[202:205], v[128:131], v[16:19]
	v_mfma_f32_16x16x32_bf16 v[48:51], v[194:197], v[170:173], v[48:51]
	v_mfma_f32_16x16x32_bf16 v[92:95], v[202:205], v[170:173], v[92:95]
	v_mfma_f32_16x16x32_bf16 v[96:99], v[194:197], v[178:181], v[96:99]
	v_mfma_f32_16x16x32_bf16 v[104:107], v[202:205], v[178:181], v[104:107]
	v_mfma_f32_16x16x32_bf16 v[84:87], v[194:197], v[186:189], v[84:87]
	v_mfma_f32_16x16x32_bf16 v[88:91], v[202:205], v[186:189], v[88:91]
	s_barrier
	s_setprio 0
	ds_read_b128 v[108:111], v206
	ds_read_b128 v[112:115], v206 offset:1024
	ds_read_b128 v[116:119], v206 offset:2048
	ds_read_b128 v[120:123], v206 offset:3072
	s_mov_b32 m0, s10
	v_lshl_add_u64 v[136:137], v[2:3], 0, s[0:1]
	ds_read_b128 v[124:127], v149
	ds_read_b128 v[128:131], v149 offset:1024
	ds_read_b128 v[166:169], v149 offset:2048
	ds_read_b128 v[170:173], v149 offset:3072
	ds_read_b128 v[174:177], v149 offset:4096
	ds_read_b128 v[178:181], v149 offset:5120
	ds_read_b128 v[182:185], v149 offset:6144
	ds_read_b128 v[186:189], v149 offset:7168
	global_load_lds_dwordx4 v[136:137], off
	v_lshl_add_u64 v[2:3], v[2:3], 0, s[78:79]
	s_mov_b32 m0, s8
	s_nop 0
	global_load_lds_dwordx4 v[2:3], off
	s_waitcnt lgkmcnt(8)
	s_setprio 1
	s_barrier
	s_waitcnt lgkmcnt(0)
	v_mfma_f32_16x16x32_bf16 v[52:55], v[108:111], v[124:127], v[52:55]
	v_mfma_f32_16x16x32_bf16 v[56:59], v[116:119], v[124:127], v[56:59]
	v_mfma_f32_16x16x32_bf16 v[60:63], v[108:111], v[166:169], v[60:63]
	v_mfma_f32_16x16x32_bf16 v[64:67], v[116:119], v[166:169], v[64:67]
	v_mfma_f32_16x16x32_bf16 v[68:71], v[108:111], v[174:177], v[68:71]
	v_mfma_f32_16x16x32_bf16 v[72:75], v[116:119], v[174:177], v[72:75]
	v_mfma_f32_16x16x32_bf16 v[80:83], v[116:119], v[182:185], v[80:83]
	v_mfma_f32_16x16x32_bf16 v[52:55], v[112:115], v[128:131], v[52:55]
	v_mfma_f32_16x16x32_bf16 v[56:59], v[120:123], v[128:131], v[56:59]
	v_mfma_f32_16x16x32_bf16 v[60:63], v[112:115], v[170:173], v[60:63]
	v_mfma_f32_16x16x32_bf16 v[64:67], v[120:123], v[170:173], v[64:67]
	v_mfma_f32_16x16x32_bf16 v[68:71], v[112:115], v[178:181], v[68:71]
	v_mfma_f32_16x16x32_bf16 v[72:75], v[120:123], v[178:181], v[72:75]
	v_mfma_f32_16x16x32_bf16 v[76:79], v[108:111], v[182:185], v[76:79]
	v_mfma_f32_16x16x32_bf16 v[80:83], v[120:123], v[186:189], v[80:83]
	v_mfma_f32_16x16x32_bf16 v[76:79], v[112:115], v[186:189], v[76:79]
	s_barrier
	s_setprio 0
	s_mov_b32 m0, s11
	v_lshl_add_u64 v[144:145], s[50:51], 0, v[0:1]
	ds_read_b128 v[190:193], v207
	ds_read_b128 v[194:197], v207 offset:1024
	ds_read_b128 v[198:201], v207 offset:2048
	ds_read_b128 v[202:205], v207 offset:3072
	global_load_lds_dwordx4 v[144:145], off
	v_lshl_add_u64 v[2:3], v[144:145], 0, s[68:69]
	s_mov_b32 m0, s6
	s_nop 0
	global_load_lds_dwordx4 v[2:3], off
	s_setprio 1
	s_barrier
	s_waitcnt lgkmcnt(0)
	v_mfma_f32_16x16x32_bf16 v[100:103], v[190:193], v[124:127], v[100:103]
	v_mfma_f32_16x16x32_bf16 v[20:23], v[198:201], v[124:127], v[20:23]
	v_mfma_f32_16x16x32_bf16 v[24:27], v[190:193], v[166:169], v[24:27]
	v_mfma_f32_16x16x32_bf16 v[28:31], v[198:201], v[166:169], v[28:31]
	v_mfma_f32_16x16x32_bf16 v[32:35], v[190:193], v[174:177], v[32:35]
	v_mfma_f32_16x16x32_bf16 v[36:39], v[198:201], v[174:177], v[36:39]
	v_mfma_f32_16x16x32_bf16 v[40:43], v[190:193], v[182:185], v[40:43]
	v_mfma_f32_16x16x32_bf16 v[100:103], v[194:197], v[128:131], v[100:103]
	v_mfma_f32_16x16x32_bf16 v[20:23], v[202:205], v[128:131], v[20:23]
	v_mfma_f32_16x16x32_bf16 v[24:27], v[194:197], v[170:173], v[24:27]
	v_mfma_f32_16x16x32_bf16 v[28:31], v[202:205], v[170:173], v[28:31]
	v_mfma_f32_16x16x32_bf16 v[32:35], v[194:197], v[178:181], v[32:35]
	v_mfma_f32_16x16x32_bf16 v[36:39], v[202:205], v[178:181], v[36:39]
	v_mfma_f32_16x16x32_bf16 v[166:169], v[194:197], v[186:189], v[40:43]
	v_mfma_f32_16x16x32_bf16 v[40:43], v[198:201], v[182:185], v[44:47]
	v_mfma_f32_16x16x32_bf16 v[170:173], v[202:205], v[186:189], v[40:43]
	s_barrier
	s_setprio 0
	s_mov_b32 m0, s57
	v_lshl_add_u64 v[234:235], s[48:49], 0, v[138:139]
	s_nop 2
	ds_read_b128 v[40:43], v149 offset:16384
	ds_read_b128 v[44:47], v149 offset:17408
	ds_read_b128 v[124:127], v149 offset:18432
	ds_read_b128 v[128:131], v149 offset:19456
	ds_read_b128 v[174:177], v149 offset:20480
	ds_read_b128 v[178:181], v149 offset:21504
	ds_read_b128 v[182:185], v149 offset:22528
	ds_read_b128 v[186:189], v149 offset:23552
	global_load_lds_dwordx4 v[234:235], off
	v_lshl_add_u64 v[2:3], v[234:235], 0, s[68:69]
	s_mov_b32 m0, s58
	s_nop 0
	global_load_lds_dwordx4 v[2:3], off
	s_setprio 1
	s_barrier
	s_waitcnt lgkmcnt(0)
	v_mfma_f32_16x16x32_bf16 v[132:135], v[108:111], v[40:43], v[132:135]
	v_mfma_f32_16x16x32_bf16 v[206:209], v[112:115], v[44:47], v[132:135]
	v_mfma_f32_16x16x32_bf16 v[132:135], v[116:119], v[40:43], v[140:143]
	v_mfma_f32_16x16x32_bf16 v[140:143], v[120:123], v[44:47], v[132:135]
	v_mfma_f32_16x16x32_bf16 v[132:135], v[108:111], v[124:127], v[150:153]
	v_mfma_f32_16x16x32_bf16 v[150:153], v[112:115], v[128:131], v[132:135]
	v_mfma_f32_16x16x32_bf16 v[132:135], v[116:119], v[124:127], v[154:157]
	v_mfma_f32_16x16x32_bf16 v[154:157], v[120:123], v[128:131], v[132:135]
	v_mfma_f32_16x16x32_bf16 v[132:135], v[108:111], v[174:177], v[158:161]
	v_mfma_f32_16x16x32_bf16 v[2:5], v[108:111], v[182:185], v[4:7]
	v_mfma_f32_16x16x32_bf16 v[6:9], v[116:119], v[182:185], v[8:11]
	v_mfma_f32_16x16x32_bf16 v[158:161], v[112:115], v[178:181], v[132:135]
	v_mfma_f32_16x16x32_bf16 v[132:135], v[116:119], v[174:177], v[162:165]
	v_mfma_f32_16x16x32_bf16 v[2:5], v[112:115], v[186:189], v[2:5]
	v_mfma_f32_16x16x32_bf16 v[6:9], v[120:123], v[186:189], v[6:9]
	v_mfma_f32_16x16x32_bf16 v[162:165], v[120:123], v[178:181], v[132:135]
	s_barrier
	s_setprio 0
	s_mov_b32 m0, s9
	v_lshl_add_u64 v[10:11], v[144:145], 0, s[38:39]
	s_mov_b64 s[8:9], 0x18000
	global_load_lds_dwordx4 v[10:11], off
	v_lshl_add_u64 v[10:11], v[144:145], 0, s[8:9]
	s_mov_b32 m0, s7
	s_nop 0
	global_load_lds_dwordx4 v[10:11], off
	s_waitcnt vmcnt(6)
	s_setprio 1
	s_barrier
	v_mfma_f32_16x16x32_bf16 v[10:13], v[190:193], v[40:43], v[12:15]
	v_mfma_f32_16x16x32_bf16 v[14:17], v[198:201], v[40:43], v[16:19]
	v_mfma_f32_16x16x32_bf16 v[40:43], v[190:193], v[124:127], v[48:51]
	v_mfma_f32_16x16x32_bf16 v[210:213], v[194:197], v[128:131], v[40:43]
	v_mfma_f32_16x16x32_bf16 v[40:43], v[198:201], v[124:127], v[92:95]
	v_mfma_f32_16x16x32_bf16 v[214:217], v[202:205], v[128:131], v[40:43]
	v_mfma_f32_16x16x32_bf16 v[40:43], v[190:193], v[174:177], v[96:99]
	v_mfma_f32_16x16x32_bf16 v[218:221], v[194:197], v[178:181], v[40:43]
	v_mfma_f32_16x16x32_bf16 v[40:43], v[198:201], v[174:177], v[104:107]
	v_mfma_f32_16x16x32_bf16 v[174:177], v[202:205], v[178:181], v[40:43]
	v_mfma_f32_16x16x32_bf16 v[40:43], v[190:193], v[182:185], v[84:87]
	v_mfma_f32_16x16x32_bf16 v[10:13], v[194:197], v[44:47], v[10:13]
	v_mfma_f32_16x16x32_bf16 v[14:17], v[202:205], v[44:47], v[14:17]
	v_mfma_f32_16x16x32_bf16 v[178:181], v[194:197], v[186:189], v[40:43]
	v_mfma_f32_16x16x32_bf16 v[40:43], v[198:201], v[182:185], v[88:91]
	v_mfma_f32_16x16x32_bf16 v[182:185], v[202:205], v[186:189], v[40:43]
	s_barrier
	s_setprio 0
	ds_read_b128 v[186:189], v222
	ds_read_b128 v[190:193], v222 offset:1024
	ds_read_b128 v[194:197], v222 offset:2048
	ds_read_b128 v[198:201], v222 offset:3072
	s_mov_b32 m0, s59
	v_lshl_add_u64 v[18:19], v[234:235], 0, s[38:39]
	ds_read_b128 v[40:43], v149 offset:32768
	ds_read_b128 v[44:47], v149 offset:33792
	ds_read_b128 v[48:51], v149 offset:34816
	ds_read_b128 v[84:87], v149 offset:35840
	ds_read_b128 v[88:91], v149 offset:36864
	ds_read_b128 v[92:95], v149 offset:37888
	ds_read_b128 v[96:99], v149 offset:38912
	ds_read_b128 v[202:205], v149 offset:39936
	global_load_lds_dwordx4 v[18:19], off
	v_lshl_add_u64 v[18:19], v[234:235], 0, s[8:9]
	s_mov_b32 m0, s62
	s_nop 0
	global_load_lds_dwordx4 v[18:19], off
	s_waitcnt lgkmcnt(8)
	s_setprio 1
	s_barrier
	s_waitcnt lgkmcnt(0)
	v_mfma_f32_16x16x32_bf16 v[52:55], v[186:189], v[40:43], v[52:55]
	v_mfma_f32_16x16x32_bf16 v[134:137], v[190:193], v[44:47], v[52:55]
	v_mfma_f32_16x16x32_bf16 v[52:55], v[194:197], v[40:43], v[56:59]
	v_mfma_f32_16x16x32_bf16 v[130:133], v[198:201], v[44:47], v[52:55]
	v_mfma_f32_16x16x32_bf16 v[52:55], v[186:189], v[48:51], v[60:63]
	v_mfma_f32_16x16x32_bf16 v[126:129], v[190:193], v[84:87], v[52:55]
	v_mfma_f32_16x16x32_bf16 v[52:55], v[194:197], v[48:51], v[64:67]
	v_mfma_f32_16x16x32_bf16 v[122:125], v[198:201], v[84:87], v[52:55]
	v_mfma_f32_16x16x32_bf16 v[52:55], v[186:189], v[88:91], v[68:71]
	v_mfma_f32_16x16x32_bf16 v[118:121], v[190:193], v[92:95], v[52:55]
	v_mfma_f32_16x16x32_bf16 v[52:55], v[194:197], v[88:91], v[72:75]
	v_mfma_f32_16x16x32_bf16 v[114:117], v[198:201], v[92:95], v[52:55]
	v_mfma_f32_16x16x32_bf16 v[52:55], v[186:189], v[96:99], v[76:79]
	v_mfma_f32_16x16x32_bf16 v[110:113], v[190:193], v[202:205], v[52:55]
	v_mfma_f32_16x16x32_bf16 v[52:55], v[194:197], v[96:99], v[80:83]
	v_mfma_f32_16x16x32_bf16 v[106:109], v[198:201], v[202:205], v[52:55]
	s_barrier
	s_setprio 0
	s_mov_b32 m0, s53
	v_lshl_add_u64 v[18:19], v[144:145], 0, s[34:35]
	s_mov_b64 s[6:7], 0x8080
	ds_read_b128 v[74:77], v226
	ds_read_b128 v[78:81], v226 offset:1024
	ds_read_b128 v[222:225], v226 offset:2048
	ds_read_b128 v[226:229], v226 offset:3072
	global_load_lds_dwordx4 v[18:19], off
	v_lshl_add_u64 v[18:19], v[144:145], 0, s[6:7]
	s_mov_b32 m0, s22
	s_nop 0
	global_load_lds_dwordx4 v[18:19], off
	s_setprio 1
	s_barrier
	s_waitcnt lgkmcnt(0)
	v_mfma_f32_16x16x32_bf16 v[18:21], v[222:225], v[40:43], v[20:23]
	v_mfma_f32_16x16x32_bf16 v[52:55], v[74:77], v[40:43], v[100:103]
	v_mfma_f32_16x16x32_bf16 v[58:61], v[226:229], v[44:47], v[18:21]
	v_mfma_f32_16x16x32_bf16 v[18:21], v[74:77], v[48:51], v[24:27]
	v_mfma_f32_16x16x32_bf16 v[62:65], v[78:81], v[44:47], v[52:55]
	v_mfma_f32_16x16x32_bf16 v[54:57], v[78:81], v[84:87], v[18:21]
	v_mfma_f32_16x16x32_bf16 v[18:21], v[222:225], v[48:51], v[28:31]
	v_mfma_f32_16x16x32_bf16 v[50:53], v[226:229], v[84:87], v[18:21]
	v_mfma_f32_16x16x32_bf16 v[18:21], v[74:77], v[88:91], v[32:35]
	v_mfma_f32_16x16x32_bf16 v[46:49], v[78:81], v[92:95], v[18:21]
	v_mfma_f32_16x16x32_bf16 v[18:21], v[222:225], v[88:91], v[36:39]
	v_mfma_f32_16x16x32_bf16 v[42:45], v[226:229], v[92:95], v[18:21]
	v_mfma_f32_16x16x32_bf16 v[18:21], v[74:77], v[96:99], v[166:169]
	v_mfma_f32_16x16x32_bf16 v[38:41], v[78:81], v[202:205], v[18:21]
	v_mfma_f32_16x16x32_bf16 v[18:21], v[222:225], v[96:99], v[170:173]
	v_mfma_f32_16x16x32_bf16 v[34:37], v[226:229], v[202:205], v[18:21]
	s_barrier
	s_setprio 0
	s_mov_b32 m0, s85
	v_lshl_add_u64 v[26:27], v[234:235], 0, s[34:35]
	s_nop 2
	ds_read_b128 v[18:21], v149 offset:49152
	ds_read_b128 v[22:25], v149 offset:50176
	ds_read_b128 v[166:169], v149 offset:51200
	ds_read_b128 v[170:173], v149 offset:52224
	ds_read_b128 v[202:205], v149 offset:53248
	ds_read_b128 v[230:233], v149 offset:54272
	ds_read_b128 v[248:251], v149 offset:55296
	ds_read_b128 v[244:247], v149 offset:56320
	global_load_lds_dwordx4 v[26:27], off
	v_lshl_add_u64 v[26:27], v[234:235], 0, s[6:7]
	s_mov_b32 m0, s86
	s_nop 0
	global_load_lds_dwordx4 v[26:27], off
	s_setprio 1
	s_barrier
	s_waitcnt lgkmcnt(0)
	v_mfma_f32_16x16x32_bf16 v[26:29], v[186:189], v[18:21], v[206:209]
	v_mfma_f32_16x16x32_bf16 v[102:105], v[190:193], v[22:25], v[26:29]
	v_mfma_f32_16x16x32_bf16 v[26:29], v[194:197], v[18:21], v[140:143]
	v_mfma_f32_16x16x32_bf16 v[98:101], v[198:201], v[22:25], v[26:29]
	v_mfma_f32_16x16x32_bf16 v[26:29], v[186:189], v[166:169], v[150:153]
	v_mfma_f32_16x16x32_bf16 v[94:97], v[190:193], v[170:173], v[26:29]
	v_mfma_f32_16x16x32_bf16 v[26:29], v[194:197], v[166:169], v[154:157]
	v_mfma_f32_16x16x32_bf16 v[90:93], v[198:201], v[170:173], v[26:29]
	v_mfma_f32_16x16x32_bf16 v[26:29], v[186:189], v[202:205], v[158:161]
	v_mfma_f32_16x16x32_bf16 v[2:5], v[186:189], v[248:251], v[2:5]
	v_mfma_f32_16x16x32_bf16 v[86:89], v[190:193], v[230:233], v[26:29]
	v_mfma_f32_16x16x32_bf16 v[26:29], v[194:197], v[202:205], v[162:165]
	v_mfma_f32_16x16x32_bf16 v[70:73], v[190:193], v[244:247], v[2:5]
	v_mfma_f32_16x16x32_bf16 v[2:5], v[194:197], v[248:251], v[6:9]
	v_mfma_f32_16x16x32_bf16 v[82:85], v[198:201], v[230:233], v[26:29]
	v_mfma_f32_16x16x32_bf16 v[66:69], v[198:201], v[244:247], v[2:5]
	s_barrier
	s_setprio 0
	s_mov_b32 m0, s41
	s_nop 2
	v_lshl_add_u64 v[2:3], v[144:145], 0, s[72:73]
	global_load_lds_dwordx4 v[2:3], off
	v_lshl_add_u64 v[2:3], v[144:145], 0, vcc
	s_mov_b32 m0, s40
	s_nop 0
	global_load_lds_dwordx4 v[2:3], off
	s_waitcnt vmcnt(6)
	s_setprio 1
	s_barrier
	v_mfma_f32_16x16x32_bf16 v[2:5], v[74:77], v[18:21], v[10:13]
	v_mfma_f32_16x16x32_bf16 v[30:33], v[78:81], v[22:25], v[2:5]
	v_mfma_f32_16x16x32_bf16 v[2:5], v[222:225], v[18:21], v[14:17]
	v_mfma_f32_16x16x32_bf16 v[26:29], v[226:229], v[22:25], v[2:5]
	v_mfma_f32_16x16x32_bf16 v[2:5], v[74:77], v[166:169], v[210:213]
	v_mfma_f32_16x16x32_bf16 v[22:25], v[78:81], v[170:173], v[2:5]
	v_mfma_f32_16x16x32_bf16 v[2:5], v[222:225], v[166:169], v[214:217]
	v_mfma_f32_16x16x32_bf16 v[18:21], v[226:229], v[170:173], v[2:5]
	v_mfma_f32_16x16x32_bf16 v[2:5], v[74:77], v[202:205], v[218:221]
	v_mfma_f32_16x16x32_bf16 v[14:17], v[78:81], v[230:233], v[2:5]
	v_mfma_f32_16x16x32_bf16 v[2:5], v[222:225], v[202:205], v[174:177]
	v_mfma_f32_16x16x32_bf16 v[10:13], v[226:229], v[230:233], v[2:5]
	v_mfma_f32_16x16x32_bf16 v[2:5], v[74:77], v[248:251], v[178:181]
	v_mfma_f32_16x16x32_bf16 v[6:9], v[78:81], v[244:247], v[2:5]
	v_mfma_f32_16x16x32_bf16 v[2:5], v[222:225], v[248:251], v[182:185]
	v_mfma_f32_16x16x32_bf16 v[2:5], v[226:229], v[244:247], v[2:5]
	s_barrier
	s_setprio 0
	v_mov_b32_e32 v150, v146
	s_cmp_gt_i32 s52, 1
	s_mov_b64 s[8:9], -1
	s_cbranch_scc0 .LBB0_231
	s_lshl_b32 s6, s52, 13
	s_and_b32 s6, s6, 0x2000
	s_add_u32 s6, s44, s6
	s_addc_u32 s7, s45, 0
	s_mov_b64 s[8:9], 0

.LBB0_292:
	s_add_u32 s6, s4, 0x100
	s_addc_u32 s7, s5, 0
	s_add_i32 s11, 0, 0x10000
	v_add_u32_e32 v138, s11, v141
	ds_read_b128 v[130:133], v138
	ds_read_b128 v[148:151], v138 offset:1024
	ds_read_b128 v[152:155], v138 offset:2048
	ds_read_b128 v[156:159], v138 offset:3072
	s_cmp_eq_u32 s10, 28
	s_cselect_b32 s41, s47, s7
	s_cselect_b32 s40, s46, s6
	s_cselect_b32 s93, s49, s9
	s_cselect_b32 s92, s48, s8
	v_lshl_add_u64 v[144:145], s[4:5], 0, v[136:137]
	v_lshl_add_u64 v[192:193], v[144:145], 0, s[16:17]
	s_add_i32 m0, s54, 0xc000
	ds_read_b128 v[160:163], v142
	ds_read_b128 v[164:167], v142 offset:1024
	ds_read_b128 v[168:171], v142 offset:2048
	ds_read_b128 v[172:175], v142 offset:3072
	ds_read_b128 v[176:179], v142 offset:4096
	ds_read_b128 v[180:183], v142 offset:5120
	ds_read_b128 v[184:187], v142 offset:6144
	ds_read_b128 v[188:191], v142 offset:7168
	global_load_lds_dwordx4 v[192:193], off
	v_lshl_add_u64 v[144:145], v[144:145], 0, s[80:81]
	s_add_i32 m0, s54, 0xe000
	s_nop 0
	global_load_lds_dwordx4 v[144:145], off
	s_waitcnt lgkmcnt(8)
	s_setprio 1
	s_barrier
	s_waitcnt lgkmcnt(0)
	v_mfma_f32_16x16x32_bf16 v[126:129], v[130:133], v[160:163], v[126:129]
	v_mfma_f32_16x16x32_bf16 v[122:125], v[152:155], v[160:163], v[122:125]
	v_mfma_f32_16x16x32_bf16 v[110:113], v[130:133], v[168:171], v[110:113]
	v_mfma_f32_16x16x32_bf16 v[106:109], v[152:155], v[168:171], v[106:109]
	v_mfma_f32_16x16x32_bf16 v[94:97], v[130:133], v[176:179], v[94:97]
	v_mfma_f32_16x16x32_bf16 v[90:93], v[152:155], v[176:179], v[90:93]
	v_mfma_f32_16x16x32_bf16 v[78:81], v[130:133], v[184:187], v[78:81]
	v_mfma_f32_16x16x32_bf16 v[74:77], v[152:155], v[184:187], v[74:77]
	v_mfma_f32_16x16x32_bf16 v[126:129], v[148:151], v[164:167], v[126:129]
	v_mfma_f32_16x16x32_bf16 v[122:125], v[156:159], v[164:167], v[122:125]
	v_mfma_f32_16x16x32_bf16 v[110:113], v[148:151], v[172:175], v[110:113]
	v_mfma_f32_16x16x32_bf16 v[106:109], v[156:159], v[172:175], v[106:109]
	v_mfma_f32_16x16x32_bf16 v[94:97], v[148:151], v[180:183], v[94:97]
	v_mfma_f32_16x16x32_bf16 v[90:93], v[156:159], v[180:183], v[90:93]
	v_mfma_f32_16x16x32_bf16 v[78:81], v[148:151], v[188:191], v[78:81]
	v_mfma_f32_16x16x32_bf16 v[74:77], v[156:159], v[188:191], v[74:77]
	s_barrier
	s_setprio 0
	s_add_i32 s4, 0, 0x14000
	s_add_i32 s5, s11, s53
	v_add_u32_e32 v138, s4, v141
	v_lshl_add_u64 v[144:145], s[92:93], 0, v[0:1]
	s_mov_b32 m0, s5
	ds_read_b128 v[192:195], v138
	ds_read_b128 v[196:199], v138 offset:1024
	ds_read_b128 v[200:203], v138 offset:2048
	ds_read_b128 v[204:207], v138 offset:3072
	global_load_lds_dwordx4 v[144:145], off
	v_lshl_add_u64 v[208:209], v[144:145], 0, s[60:61]
	s_add_i32 m0, s5, 0x2000
	s_nop 0
	global_load_lds_dwordx4 v[208:209], off
	s_setprio 1
	s_barrier
	s_waitcnt lgkmcnt(0)
	v_mfma_f32_16x16x32_bf16 v[118:121], v[192:195], v[160:163], v[118:121]
	v_mfma_f32_16x16x32_bf16 v[114:117], v[200:203], v[160:163], v[114:117]
	v_mfma_f32_16x16x32_bf16 v[102:105], v[192:195], v[168:171], v[102:105]
	v_mfma_f32_16x16x32_bf16 v[98:101], v[200:203], v[168:171], v[98:101]
	v_mfma_f32_16x16x32_bf16 v[86:89], v[192:195], v[176:179], v[86:89]
	v_mfma_f32_16x16x32_bf16 v[82:85], v[200:203], v[176:179], v[82:85]
	v_mfma_f32_16x16x32_bf16 v[70:73], v[192:195], v[184:187], v[70:73]
	v_mfma_f32_16x16x32_bf16 v[66:69], v[200:203], v[184:187], v[66:69]
	v_mfma_f32_16x16x32_bf16 v[118:121], v[196:199], v[164:167], v[118:121]
	v_mfma_f32_16x16x32_bf16 v[114:117], v[204:207], v[164:167], v[114:117]
	v_mfma_f32_16x16x32_bf16 v[102:105], v[196:199], v[172:175], v[102:105]
	v_mfma_f32_16x16x32_bf16 v[98:101], v[204:207], v[172:175], v[98:101]
	v_mfma_f32_16x16x32_bf16 v[86:89], v[196:199], v[180:183], v[86:89]
	v_mfma_f32_16x16x32_bf16 v[82:85], v[204:207], v[180:183], v[82:85]
	v_mfma_f32_16x16x32_bf16 v[70:73], v[196:199], v[188:191], v[70:73]
	v_mfma_f32_16x16x32_bf16 v[66:69], v[204:207], v[188:191], v[66:69]
	s_barrier
	s_setprio 0
	s_mov_b32 m0, s54
	v_lshl_add_u64 v[208:209], s[40:41], 0, v[134:135]
	ds_read_b128 v[160:163], v142 offset:16384
	ds_read_b128 v[164:167], v142 offset:17408
	ds_read_b128 v[168:171], v142 offset:18432
	ds_read_b128 v[172:175], v142 offset:19456
	ds_read_b128 v[176:179], v142 offset:20480
	ds_read_b128 v[180:183], v142 offset:21504
	ds_read_b128 v[184:187], v142 offset:22528
	ds_read_b128 v[188:191], v142 offset:23552
	global_load_lds_dwordx4 v[208:209], off
	v_lshl_add_u64 v[210:211], v[208:209], 0, s[60:61]
	s_mov_b32 m0, s55
	s_nop 0
	global_load_lds_dwordx4 v[210:211], off
	s_setprio 1
	s_barrier
	s_waitcnt lgkmcnt(0)
	v_mfma_f32_16x16x32_bf16 v[62:65], v[130:133], v[160:163], v[62:65]
	v_mfma_f32_16x16x32_bf16 v[58:61], v[152:155], v[160:163], v[58:61]
	v_mfma_f32_16x16x32_bf16 v[46:49], v[130:133], v[168:171], v[46:49]
	v_mfma_f32_16x16x32_bf16 v[42:45], v[152:155], v[168:171], v[42:45]
	v_mfma_f32_16x16x32_bf16 v[30:33], v[130:133], v[176:179], v[30:33]
	v_mfma_f32_16x16x32_bf16 v[26:29], v[152:155], v[176:179], v[26:29]
	v_mfma_f32_16x16x32_bf16 v[14:17], v[130:133], v[184:187], v[14:17]
	v_mfma_f32_16x16x32_bf16 v[10:13], v[152:155], v[184:187], v[10:13]
	v_mfma_f32_16x16x32_bf16 v[62:65], v[148:151], v[164:167], v[62:65]
	v_mfma_f32_16x16x32_bf16 v[58:61], v[156:159], v[164:167], v[58:61]
	v_mfma_f32_16x16x32_bf16 v[46:49], v[148:151], v[172:175], v[46:49]
	v_mfma_f32_16x16x32_bf16 v[42:45], v[156:159], v[172:175], v[42:45]
	v_mfma_f32_16x16x32_bf16 v[30:33], v[148:151], v[180:183], v[30:33]
	v_mfma_f32_16x16x32_bf16 v[26:29], v[156:159], v[180:183], v[26:29]
	v_mfma_f32_16x16x32_bf16 v[14:17], v[148:151], v[188:191], v[14:17]
	v_mfma_f32_16x16x32_bf16 v[10:13], v[156:159], v[188:191], v[10:13]
	s_barrier
	s_setprio 0
	s_add_i32 s4, s4, s53
	v_lshl_add_u64 v[130:131], v[144:145], 0, s[20:21]
	s_mov_b32 m0, s4
	s_nop 0
	global_load_lds_dwordx4 v[130:131], off
	v_lshl_add_u64 v[130:131], v[144:145], 0, s[64:65]
	s_add_i32 m0, s4, 0x2000
	s_nop 0
	global_load_lds_dwordx4 v[130:131], off
	s_waitcnt vmcnt(6)
	s_setprio 1
	s_barrier
	v_mfma_f32_16x16x32_bf16 v[54:57], v[192:195], v[160:163], v[54:57]
	v_mfma_f32_16x16x32_bf16 v[50:53], v[200:203], v[160:163], v[50:53]
	v_mfma_f32_16x16x32_bf16 v[38:41], v[192:195], v[168:171], v[38:41]
	v_mfma_f32_16x16x32_bf16 v[34:37], v[200:203], v[168:171], v[34:37]
	v_mfma_f32_16x16x32_bf16 v[22:25], v[192:195], v[176:179], v[22:25]
	v_mfma_f32_16x16x32_bf16 v[18:21], v[200:203], v[176:179], v[18:21]
	v_mfma_f32_16x16x32_bf16 v[6:9], v[192:195], v[184:187], v[6:9]
	v_mfma_f32_16x16x32_bf16 v[2:5], v[200:203], v[184:187], v[2:5]
	v_mfma_f32_16x16x32_bf16 v[54:57], v[196:199], v[164:167], v[54:57]
	v_mfma_f32_16x16x32_bf16 v[50:53], v[204:207], v[164:167], v[50:53]
	v_mfma_f32_16x16x32_bf16 v[38:41], v[196:199], v[172:175], v[38:41]
	v_mfma_f32_16x16x32_bf16 v[34:37], v[204:207], v[172:175], v[34:37]
	v_mfma_f32_16x16x32_bf16 v[22:25], v[196:199], v[180:183], v[22:25]
	v_mfma_f32_16x16x32_bf16 v[18:21], v[204:207], v[180:183], v[18:21]
	v_mfma_f32_16x16x32_bf16 v[6:9], v[196:199], v[188:191], v[6:9]
	v_mfma_f32_16x16x32_bf16 v[2:5], v[204:207], v[188:191], v[2:5]
	s_barrier
	s_setprio 0
	s_add_i32 s4, 0, 0x18000
	v_add_u32_e32 v138, s4, v141
	ds_read_b128 v[130:133], v138
	ds_read_b128 v[148:151], v138 offset:1024
	ds_read_b128 v[152:155], v138 offset:2048
	ds_read_b128 v[156:159], v138 offset:3072
	s_mov_b32 m0, s56
	v_lshl_add_u64 v[192:193], v[208:209], 0, s[20:21]
	ds_read_b128 v[160:163], v142 offset:32768
	ds_read_b128 v[164:167], v142 offset:33792
	ds_read_b128 v[168:171], v142 offset:34816
	ds_read_b128 v[172:175], v142 offset:35840
	ds_read_b128 v[176:179], v142 offset:36864
	ds_read_b128 v[180:183], v142 offset:37888
	ds_read_b128 v[184:187], v142 offset:38912
	ds_read_b128 v[188:191], v142 offset:39936
	global_load_lds_dwordx4 v[192:193], off
	v_lshl_add_u64 v[192:193], v[208:209], 0, s[64:65]
	s_mov_b32 m0, s57
	s_nop 0
	global_load_lds_dwordx4 v[192:193], off
	s_waitcnt lgkmcnt(8)
	s_setprio 1
	s_barrier
	s_waitcnt lgkmcnt(0)
	v_mfma_f32_16x16x32_bf16 v[126:129], v[130:133], v[160:163], v[126:129]
	v_mfma_f32_16x16x32_bf16 v[122:125], v[152:155], v[160:163], v[122:125]
	v_mfma_f32_16x16x32_bf16 v[110:113], v[130:133], v[168:171], v[110:113]
	v_mfma_f32_16x16x32_bf16 v[106:109], v[152:155], v[168:171], v[106:109]
	v_mfma_f32_16x16x32_bf16 v[94:97], v[130:133], v[176:179], v[94:97]
	v_mfma_f32_16x16x32_bf16 v[90:93], v[152:155], v[176:179], v[90:93]
	v_mfma_f32_16x16x32_bf16 v[78:81], v[130:133], v[184:187], v[78:81]
	v_mfma_f32_16x16x32_bf16 v[74:77], v[152:155], v[184:187], v[74:77]
	v_mfma_f32_16x16x32_bf16 v[126:129], v[148:151], v[164:167], v[126:129]
	v_mfma_f32_16x16x32_bf16 v[122:125], v[156:159], v[164:167], v[122:125]
	v_mfma_f32_16x16x32_bf16 v[110:113], v[148:151], v[172:175], v[110:113]
	v_mfma_f32_16x16x32_bf16 v[106:109], v[156:159], v[172:175], v[106:109]
	v_mfma_f32_16x16x32_bf16 v[94:97], v[148:151], v[180:183], v[94:97]
	v_mfma_f32_16x16x32_bf16 v[90:93], v[156:159], v[180:183], v[90:93]
	v_mfma_f32_16x16x32_bf16 v[78:81], v[148:151], v[188:191], v[78:81]
	v_mfma_f32_16x16x32_bf16 v[74:77], v[156:159], v[188:191], v[74:77]
	s_barrier
	s_setprio 0
	s_add_i32 s5, 0, 0x1c000
	s_add_i32 s4, s4, s53
	v_add_u32_e32 v138, s5, v141
	v_lshl_add_u64 v[210:211], v[144:145], 0, s[34:35]
	s_mov_b32 m0, s4
	ds_read_b128 v[192:195], v138
	ds_read_b128 v[196:199], v138 offset:1024
	ds_read_b128 v[200:203], v138 offset:2048
	ds_read_b128 v[204:207], v138 offset:3072
	global_load_lds_dwordx4 v[210:211], off
	v_lshl_add_u64 v[210:211], v[144:145], 0, s[66:67]
	s_add_i32 m0, s4, 0x2000
	s_nop 0
	global_load_lds_dwordx4 v[210:211], off
	s_setprio 1
	s_barrier
	s_waitcnt lgkmcnt(0)
	v_mfma_f32_16x16x32_bf16 v[118:121], v[192:195], v[160:163], v[118:121]
	v_mfma_f32_16x16x32_bf16 v[114:117], v[200:203], v[160:163], v[114:117]
	v_mfma_f32_16x16x32_bf16 v[102:105], v[192:195], v[168:171], v[102:105]
	v_mfma_f32_16x16x32_bf16 v[98:101], v[200:203], v[168:171], v[98:101]
	v_mfma_f32_16x16x32_bf16 v[86:89], v[192:195], v[176:179], v[86:89]
	v_mfma_f32_16x16x32_bf16 v[82:85], v[200:203], v[176:179], v[82:85]
	v_mfma_f32_16x16x32_bf16 v[70:73], v[192:195], v[184:187], v[70:73]
	v_mfma_f32_16x16x32_bf16 v[66:69], v[200:203], v[184:187], v[66:69]
	v_mfma_f32_16x16x32_bf16 v[118:121], v[196:199], v[164:167], v[118:121]
	v_mfma_f32_16x16x32_bf16 v[114:117], v[204:207], v[164:167], v[114:117]
	v_mfma_f32_16x16x32_bf16 v[102:105], v[196:199], v[172:175], v[102:105]
	v_mfma_f32_16x16x32_bf16 v[98:101], v[204:207], v[172:175], v[98:101]
	v_mfma_f32_16x16x32_bf16 v[86:89], v[196:199], v[180:183], v[86:89]
	v_mfma_f32_16x16x32_bf16 v[82:85], v[204:207], v[180:183], v[82:85]
	v_mfma_f32_16x16x32_bf16 v[70:73], v[196:199], v[188:191], v[70:73]
	v_mfma_f32_16x16x32_bf16 v[66:69], v[204:207], v[188:191], v[66:69]
	s_barrier
	s_setprio 0
	s_mov_b32 m0, s62
	v_lshl_add_u64 v[210:211], v[208:209], 0, s[34:35]
	ds_read_b128 v[160:163], v142 offset:49152
	ds_read_b128 v[164:167], v142 offset:50176
	ds_read_b128 v[168:171], v142 offset:51200
	ds_read_b128 v[172:175], v142 offset:52224
	ds_read_b128 v[176:179], v142 offset:53248
	ds_read_b128 v[180:183], v142 offset:54272
	ds_read_b128 v[184:187], v142 offset:55296
	ds_read_b128 v[188:191], v142 offset:56320
	global_load_lds_dwordx4 v[210:211], off
	v_lshl_add_u64 v[208:209], v[208:209], 0, s[66:67]
	s_mov_b32 m0, s63
	s_nop 0
	global_load_lds_dwordx4 v[208:209], off
	s_setprio 1
	s_barrier
	s_waitcnt lgkmcnt(0)
	v_mfma_f32_16x16x32_bf16 v[62:65], v[130:133], v[160:163], v[62:65]
	v_mfma_f32_16x16x32_bf16 v[58:61], v[152:155], v[160:163], v[58:61]
	v_mfma_f32_16x16x32_bf16 v[46:49], v[130:133], v[168:171], v[46:49]
	v_mfma_f32_16x16x32_bf16 v[42:45], v[152:155], v[168:171], v[42:45]
	v_mfma_f32_16x16x32_bf16 v[30:33], v[130:133], v[176:179], v[30:33]
	v_mfma_f32_16x16x32_bf16 v[26:29], v[152:155], v[176:179], v[26:29]
	v_mfma_f32_16x16x32_bf16 v[14:17], v[130:133], v[184:187], v[14:17]
	v_mfma_f32_16x16x32_bf16 v[10:13], v[152:155], v[184:187], v[10:13]
	v_mfma_f32_16x16x32_bf16 v[62:65], v[148:151], v[164:167], v[62:65]
	v_mfma_f32_16x16x32_bf16 v[58:61], v[156:159], v[164:167], v[58:61]
	v_mfma_f32_16x16x32_bf16 v[46:49], v[148:151], v[172:175], v[46:49]
	v_mfma_f32_16x16x32_bf16 v[42:45], v[156:159], v[172:175], v[42:45]
	v_mfma_f32_16x16x32_bf16 v[30:33], v[148:151], v[180:183], v[30:33]
	v_mfma_f32_16x16x32_bf16 v[26:29], v[156:159], v[180:183], v[26:29]
	v_mfma_f32_16x16x32_bf16 v[14:17], v[148:151], v[188:191], v[14:17]
	v_mfma_f32_16x16x32_bf16 v[10:13], v[156:159], v[188:191], v[10:13]
	s_barrier
	s_setprio 0
	s_add_i32 s4, s5, s53
	v_lshl_add_u64 v[130:131], v[144:145], 0, s[16:17]
	s_mov_b32 m0, s4
	s_nop 0
	global_load_lds_dwordx4 v[130:131], off
	v_lshl_add_u64 v[130:131], v[144:145], 0, s[80:81]
	s_add_i32 m0, s4, 0x2000
	s_nop 0
	global_load_lds_dwordx4 v[130:131], off
	s_waitcnt vmcnt(6)
	s_setprio 1
	s_barrier
	v_mfma_f32_16x16x32_bf16 v[54:57], v[192:195], v[160:163], v[54:57]
	v_mfma_f32_16x16x32_bf16 v[50:53], v[200:203], v[160:163], v[50:53]
	v_mfma_f32_16x16x32_bf16 v[38:41], v[192:195], v[168:171], v[38:41]
	v_mfma_f32_16x16x32_bf16 v[34:37], v[200:203], v[168:171], v[34:37]
	v_mfma_f32_16x16x32_bf16 v[22:25], v[192:195], v[176:179], v[22:25]
	v_mfma_f32_16x16x32_bf16 v[18:21], v[200:203], v[176:179], v[18:21]
	v_mfma_f32_16x16x32_bf16 v[6:9], v[192:195], v[184:187], v[6:9]
	v_mfma_f32_16x16x32_bf16 v[2:5], v[200:203], v[184:187], v[2:5]
	v_mfma_f32_16x16x32_bf16 v[54:57], v[196:199], v[164:167], v[54:57]
	v_mfma_f32_16x16x32_bf16 v[50:53], v[204:207], v[164:167], v[50:53]
	v_mfma_f32_16x16x32_bf16 v[38:41], v[196:199], v[172:175], v[38:41]
	v_mfma_f32_16x16x32_bf16 v[34:37], v[204:207], v[172:175], v[34:37]
	v_mfma_f32_16x16x32_bf16 v[22:25], v[196:199], v[180:183], v[22:25]
	v_mfma_f32_16x16x32_bf16 v[18:21], v[204:207], v[180:183], v[18:21]
	v_mfma_f32_16x16x32_bf16 v[6:9], v[196:199], v[188:191], v[6:9]
	v_mfma_f32_16x16x32_bf16 v[2:5], v[204:207], v[188:191], v[2:5]
	s_barrier
	s_setprio 0
	s_add_i32 s10, s10, 2
	s_add_u32 s8, s8, 0x100
	s_addc_u32 s9, s9, 0
	s_cmp_gt_u32 s10, 29
	s_mov_b64 s[4:5], s[6:7]
	s_cbranch_scc0 .LBB0_292
	s_cmp_eq_u32 s52, 3
	v_mov_b32_e32 v144, v139
	s_cselect_b64 s[4:5], -1, 0
	s_cmp_lt_i32 s52, 5
	s_cbranch_scc1 .LBB0_295
	s_cmp_eq_u32 s52, 5
	s_cselect_b64 s[6:7], -1, 0
	s_movk_i32 s93, 0xf800
	s_cbranch_execz .LBB0_296
	s_branch .LBB0_297

.LBB0_485:
	s_add_u32 s7, s46, 0xffea0080
	s_addc_u32 s78, s47, -1
	s_add_i32 s79, 0, 0x10000
	v_add_u32_e32 v132, s79, v135
	ds_read_b128 v[138:141], v132
	ds_read_b128 v[142:145], v132 offset:1024
	ds_read_b128 v[148:151], v132 offset:2048
	ds_read_b128 v[152:155], v132 offset:3072
	s_cmpk_eq_i32 s6, 0x54
	s_cselect_b32 s89, s43, s78
	s_cselect_b32 s88, s42, s7
	s_cselect_b32 s91, s45, s9
	s_cselect_b32 s90, s44, s8
	v_lshl_add_u64 v[132:133], s[46:47], 0, v[130:131]
	s_add_i32 m0, s54, 0xc000
	ds_read_b128 v[156:159], v136
	ds_read_b128 v[160:163], v136 offset:1024
	ds_read_b128 v[164:167], v136 offset:2048
	ds_read_b128 v[168:171], v136 offset:3072
	ds_read_b128 v[172:175], v136 offset:4096
	ds_read_b128 v[176:179], v136 offset:5120
	ds_read_b128 v[180:183], v136 offset:6144
	ds_read_b128 v[184:187], v136 offset:7168
	global_load_lds_dwordx4 v[132:133], off
	v_lshl_add_u64 v[132:133], v[132:133], 0, s[26:27]
	s_add_i32 m0, s54, 0xe000
	s_nop 0
	global_load_lds_dwordx4 v[132:133], off
	s_waitcnt lgkmcnt(8)
	s_setprio 1
	s_barrier
	s_waitcnt lgkmcnt(0)
	v_mfma_f32_16x16x32_bf16 v[126:129], v[138:141], v[156:159], v[126:129]
	v_mfma_f32_16x16x32_bf16 v[122:125], v[148:151], v[156:159], v[122:125]
	v_mfma_f32_16x16x32_bf16 v[118:121], v[138:141], v[164:167], v[118:121]
	v_mfma_f32_16x16x32_bf16 v[110:113], v[148:151], v[164:167], v[110:113]
	v_mfma_f32_16x16x32_bf16 v[102:105], v[138:141], v[172:175], v[102:105]
	v_mfma_f32_16x16x32_bf16 v[94:97], v[148:151], v[172:175], v[94:97]
	v_mfma_f32_16x16x32_bf16 v[86:89], v[138:141], v[180:183], v[86:89]
	v_mfma_f32_16x16x32_bf16 v[78:81], v[148:151], v[180:183], v[78:81]
	v_mfma_f32_16x16x32_bf16 v[126:129], v[142:145], v[160:163], v[126:129]
	v_mfma_f32_16x16x32_bf16 v[122:125], v[152:155], v[160:163], v[122:125]
	v_mfma_f32_16x16x32_bf16 v[118:121], v[142:145], v[168:171], v[118:121]
	v_mfma_f32_16x16x32_bf16 v[110:113], v[152:155], v[168:171], v[110:113]
	v_mfma_f32_16x16x32_bf16 v[102:105], v[142:145], v[176:179], v[102:105]
	v_mfma_f32_16x16x32_bf16 v[94:97], v[152:155], v[176:179], v[94:97]
	v_mfma_f32_16x16x32_bf16 v[86:89], v[142:145], v[184:187], v[86:89]
	v_mfma_f32_16x16x32_bf16 v[78:81], v[152:155], v[184:187], v[78:81]
	s_barrier
	s_setprio 0
	s_add_i32 s7, 0, 0x14000
	v_add_u32_e32 v132, s7, v135
	s_add_i32 s78, s79, s53
	ds_read_b128 v[188:191], v132
	ds_read_b128 v[192:195], v132 offset:1024
	ds_read_b128 v[196:199], v132 offset:2048
	ds_read_b128 v[200:203], v132 offset:3072
	v_lshl_add_u64 v[132:133], s[90:91], 0, v[0:1]
	s_mov_b32 m0, s78
	v_lshl_add_u64 v[204:205], v[132:133], 0, s[26:27]
	global_load_lds_dwordx4 v[132:133], off
	s_add_i32 m0, s78, 0x2000
	s_nop 0
	global_load_lds_dwordx4 v[204:205], off
	s_setprio 1
	s_barrier
	s_waitcnt lgkmcnt(0)
	v_mfma_f32_16x16x32_bf16 v[114:117], v[188:191], v[156:159], v[114:117]
	v_mfma_f32_16x16x32_bf16 v[106:109], v[196:199], v[156:159], v[106:109]
	v_mfma_f32_16x16x32_bf16 v[98:101], v[188:191], v[164:167], v[98:101]
	v_mfma_f32_16x16x32_bf16 v[90:93], v[196:199], v[164:167], v[90:93]
	v_mfma_f32_16x16x32_bf16 v[82:85], v[188:191], v[172:175], v[82:85]
	v_mfma_f32_16x16x32_bf16 v[74:77], v[196:199], v[172:175], v[74:77]
	v_mfma_f32_16x16x32_bf16 v[70:73], v[188:191], v[180:183], v[70:73]
	v_mfma_f32_16x16x32_bf16 v[66:69], v[196:199], v[180:183], v[66:69]
	v_mfma_f32_16x16x32_bf16 v[114:117], v[192:195], v[160:163], v[114:117]
	v_mfma_f32_16x16x32_bf16 v[106:109], v[200:203], v[160:163], v[106:109]
	v_mfma_f32_16x16x32_bf16 v[98:101], v[192:195], v[168:171], v[98:101]
	v_mfma_f32_16x16x32_bf16 v[90:93], v[200:203], v[168:171], v[90:93]
	v_mfma_f32_16x16x32_bf16 v[82:85], v[192:195], v[176:179], v[82:85]
	v_mfma_f32_16x16x32_bf16 v[74:77], v[200:203], v[176:179], v[74:77]
	v_mfma_f32_16x16x32_bf16 v[70:73], v[192:195], v[184:187], v[70:73]
	v_mfma_f32_16x16x32_bf16 v[66:69], v[200:203], v[184:187], v[66:69]
	s_barrier
	s_setprio 0
	s_mov_b32 m0, s54
	v_lshl_add_u64 v[204:205], s[88:89], 0, v[0:1]
	ds_read_b128 v[156:159], v136 offset:16384
	ds_read_b128 v[160:163], v136 offset:17408
	ds_read_b128 v[164:167], v136 offset:18432
	ds_read_b128 v[168:171], v136 offset:19456
	ds_read_b128 v[172:175], v136 offset:20480
	ds_read_b128 v[176:179], v136 offset:21504
	ds_read_b128 v[180:183], v136 offset:22528
	ds_read_b128 v[184:187], v136 offset:23552
	global_load_lds_dwordx4 v[204:205], off
	v_lshl_add_u64 v[206:207], v[204:205], 0, s[26:27]
	s_mov_b32 m0, s55
	s_nop 0
	global_load_lds_dwordx4 v[206:207], off
	s_setprio 1
	s_barrier
	s_waitcnt lgkmcnt(0)
	v_mfma_f32_16x16x32_bf16 v[62:65], v[138:141], v[156:159], v[62:65]
	v_mfma_f32_16x16x32_bf16 v[58:61], v[148:151], v[156:159], v[58:61]
	v_mfma_f32_16x16x32_bf16 v[54:57], v[138:141], v[164:167], v[54:57]
	v_mfma_f32_16x16x32_bf16 v[46:49], v[148:151], v[164:167], v[46:49]
	v_mfma_f32_16x16x32_bf16 v[38:41], v[138:141], v[172:175], v[38:41]
	v_mfma_f32_16x16x32_bf16 v[30:33], v[148:151], v[172:175], v[30:33]
	v_mfma_f32_16x16x32_bf16 v[22:25], v[138:141], v[180:183], v[22:25]
	v_mfma_f32_16x16x32_bf16 v[14:17], v[148:151], v[180:183], v[14:17]
	v_mfma_f32_16x16x32_bf16 v[62:65], v[142:145], v[160:163], v[62:65]
	v_mfma_f32_16x16x32_bf16 v[58:61], v[152:155], v[160:163], v[58:61]
	v_mfma_f32_16x16x32_bf16 v[54:57], v[142:145], v[168:171], v[54:57]
	v_mfma_f32_16x16x32_bf16 v[46:49], v[152:155], v[168:171], v[46:49]
	v_mfma_f32_16x16x32_bf16 v[38:41], v[142:145], v[176:179], v[38:41]
	v_mfma_f32_16x16x32_bf16 v[30:33], v[152:155], v[176:179], v[30:33]
	v_mfma_f32_16x16x32_bf16 v[22:25], v[142:145], v[184:187], v[22:25]
	v_mfma_f32_16x16x32_bf16 v[14:17], v[152:155], v[184:187], v[14:17]
	s_barrier
	s_setprio 0
	s_add_i32 s7, s7, s53
	v_lshl_add_u64 v[138:139], v[132:133], 0, s[28:29]
	s_mov_b32 m0, s7
	s_nop 0
	global_load_lds_dwordx4 v[138:139], off
	v_lshl_add_u64 v[138:139], v[132:133], 0, s[30:31]
	s_add_i32 m0, s7, 0x2000
	s_nop 0
	global_load_lds_dwordx4 v[138:139], off
	s_waitcnt vmcnt(6)
	s_setprio 1
	s_barrier
	v_mfma_f32_16x16x32_bf16 v[50:53], v[188:191], v[156:159], v[50:53]
	v_mfma_f32_16x16x32_bf16 v[42:45], v[196:199], v[156:159], v[42:45]
	v_mfma_f32_16x16x32_bf16 v[34:37], v[188:191], v[164:167], v[34:37]
	v_mfma_f32_16x16x32_bf16 v[26:29], v[196:199], v[164:167], v[26:29]
	v_mfma_f32_16x16x32_bf16 v[18:21], v[188:191], v[172:175], v[18:21]
	v_mfma_f32_16x16x32_bf16 v[10:13], v[196:199], v[172:175], v[10:13]
	v_mfma_f32_16x16x32_bf16 v[6:9], v[188:191], v[180:183], v[6:9]
	v_mfma_f32_16x16x32_bf16 v[2:5], v[196:199], v[180:183], v[2:5]
	v_mfma_f32_16x16x32_bf16 v[50:53], v[192:195], v[160:163], v[50:53]
	v_mfma_f32_16x16x32_bf16 v[42:45], v[200:203], v[160:163], v[42:45]
	v_mfma_f32_16x16x32_bf16 v[34:37], v[192:195], v[168:171], v[34:37]
	v_mfma_f32_16x16x32_bf16 v[26:29], v[200:203], v[168:171], v[26:29]
	v_mfma_f32_16x16x32_bf16 v[18:21], v[192:195], v[176:179], v[18:21]
	v_mfma_f32_16x16x32_bf16 v[10:13], v[200:203], v[176:179], v[10:13]
	v_mfma_f32_16x16x32_bf16 v[6:9], v[192:195], v[184:187], v[6:9]
	v_mfma_f32_16x16x32_bf16 v[2:5], v[200:203], v[184:187], v[2:5]
	s_barrier
	s_setprio 0
	s_add_i32 s7, 0, 0x18000
	v_add_u32_e32 v137, s7, v135
	ds_read_b128 v[138:141], v137
	ds_read_b128 v[142:145], v137 offset:1024
	ds_read_b128 v[148:151], v137 offset:2048
	ds_read_b128 v[152:155], v137 offset:3072
	s_mov_b32 m0, s56
	v_lshl_add_u64 v[188:189], v[204:205], 0, s[28:29]
	ds_read_b128 v[156:159], v136 offset:32768
	ds_read_b128 v[160:163], v136 offset:33792
	ds_read_b128 v[164:167], v136 offset:34816
	ds_read_b128 v[168:171], v136 offset:35840
	ds_read_b128 v[172:175], v136 offset:36864
	ds_read_b128 v[176:179], v136 offset:37888
	ds_read_b128 v[180:183], v136 offset:38912
	ds_read_b128 v[184:187], v136 offset:39936
	global_load_lds_dwordx4 v[188:189], off
	v_lshl_add_u64 v[188:189], v[204:205], 0, s[30:31]
	s_mov_b32 m0, s57
	s_nop 0
	global_load_lds_dwordx4 v[188:189], off
	s_waitcnt lgkmcnt(8)
	s_setprio 1
	s_barrier
	s_waitcnt lgkmcnt(0)
	v_mfma_f32_16x16x32_bf16 v[126:129], v[138:141], v[156:159], v[126:129]
	v_mfma_f32_16x16x32_bf16 v[122:125], v[148:151], v[156:159], v[122:125]
	v_mfma_f32_16x16x32_bf16 v[118:121], v[138:141], v[164:167], v[118:121]
	v_mfma_f32_16x16x32_bf16 v[110:113], v[148:151], v[164:167], v[110:113]
	v_mfma_f32_16x16x32_bf16 v[102:105], v[138:141], v[172:175], v[102:105]
	v_mfma_f32_16x16x32_bf16 v[94:97], v[148:151], v[172:175], v[94:97]
	v_mfma_f32_16x16x32_bf16 v[86:89], v[138:141], v[180:183], v[86:89]
	v_mfma_f32_16x16x32_bf16 v[78:81], v[148:151], v[180:183], v[78:81]
	v_mfma_f32_16x16x32_bf16 v[126:129], v[142:145], v[160:163], v[126:129]
	v_mfma_f32_16x16x32_bf16 v[122:125], v[152:155], v[160:163], v[122:125]
	v_mfma_f32_16x16x32_bf16 v[118:121], v[142:145], v[168:171], v[118:121]
	v_mfma_f32_16x16x32_bf16 v[110:113], v[152:155], v[168:171], v[110:113]
	v_mfma_f32_16x16x32_bf16 v[102:105], v[142:145], v[176:179], v[102:105]
	v_mfma_f32_16x16x32_bf16 v[94:97], v[152:155], v[176:179], v[94:97]
	v_mfma_f32_16x16x32_bf16 v[86:89], v[142:145], v[184:187], v[86:89]
	v_mfma_f32_16x16x32_bf16 v[78:81], v[152:155], v[184:187], v[78:81]
	s_barrier
	s_setprio 0
	s_add_i32 s78, 0, 0x1c000
	s_add_i32 s7, s7, s53
	v_add_u32_e32 v137, s78, v135
	v_lshl_add_u64 v[206:207], v[132:133], 0, s[34:35]
	s_mov_b32 m0, s7
	ds_read_b128 v[188:191], v137
	ds_read_b128 v[192:195], v137 offset:1024
	ds_read_b128 v[196:199], v137 offset:2048
	ds_read_b128 v[200:203], v137 offset:3072
	global_load_lds_dwordx4 v[206:207], off
	v_lshl_add_u64 v[206:207], v[132:133], 0, s[36:37]
	s_add_i32 m0, s7, 0x2000
	s_nop 0
	global_load_lds_dwordx4 v[206:207], off
	s_setprio 1
	s_barrier
	s_waitcnt lgkmcnt(0)
	v_mfma_f32_16x16x32_bf16 v[114:117], v[188:191], v[156:159], v[114:117]
	v_mfma_f32_16x16x32_bf16 v[106:109], v[196:199], v[156:159], v[106:109]
	v_mfma_f32_16x16x32_bf16 v[98:101], v[188:191], v[164:167], v[98:101]
	v_mfma_f32_16x16x32_bf16 v[90:93], v[196:199], v[164:167], v[90:93]
	v_mfma_f32_16x16x32_bf16 v[82:85], v[188:191], v[172:175], v[82:85]
	v_mfma_f32_16x16x32_bf16 v[74:77], v[196:199], v[172:175], v[74:77]
	v_mfma_f32_16x16x32_bf16 v[70:73], v[188:191], v[180:183], v[70:73]
	v_mfma_f32_16x16x32_bf16 v[66:69], v[196:199], v[180:183], v[66:69]
	v_mfma_f32_16x16x32_bf16 v[114:117], v[192:195], v[160:163], v[114:117]
	v_mfma_f32_16x16x32_bf16 v[106:109], v[200:203], v[160:163], v[106:109]
	v_mfma_f32_16x16x32_bf16 v[98:101], v[192:195], v[168:171], v[98:101]
	v_mfma_f32_16x16x32_bf16 v[90:93], v[200:203], v[168:171], v[90:93]
	v_mfma_f32_16x16x32_bf16 v[82:85], v[192:195], v[176:179], v[82:85]
	v_mfma_f32_16x16x32_bf16 v[74:77], v[200:203], v[176:179], v[74:77]
	v_mfma_f32_16x16x32_bf16 v[70:73], v[192:195], v[184:187], v[70:73]
	v_mfma_f32_16x16x32_bf16 v[66:69], v[200:203], v[184:187], v[66:69]
	s_barrier
	s_setprio 0
	s_mov_b32 m0, s62
	v_lshl_add_u64 v[206:207], v[204:205], 0, s[34:35]
	ds_read_b128 v[156:159], v136 offset:49152
	ds_read_b128 v[160:163], v136 offset:50176
	ds_read_b128 v[164:167], v136 offset:51200
	ds_read_b128 v[168:171], v136 offset:52224
	ds_read_b128 v[172:175], v136 offset:53248
	ds_read_b128 v[176:179], v136 offset:54272
	ds_read_b128 v[180:183], v136 offset:55296
	ds_read_b128 v[184:187], v136 offset:56320
	global_load_lds_dwordx4 v[206:207], off
	v_lshl_add_u64 v[204:205], v[204:205], 0, s[36:37]
	s_mov_b32 m0, s63
	s_nop 0
	global_load_lds_dwordx4 v[204:205], off
	s_setprio 1
	s_barrier
	s_waitcnt lgkmcnt(0)
	v_mfma_f32_16x16x32_bf16 v[62:65], v[138:141], v[156:159], v[62:65]
	v_mfma_f32_16x16x32_bf16 v[58:61], v[148:151], v[156:159], v[58:61]
	v_mfma_f32_16x16x32_bf16 v[54:57], v[138:141], v[164:167], v[54:57]
	v_mfma_f32_16x16x32_bf16 v[46:49], v[148:151], v[164:167], v[46:49]
	v_mfma_f32_16x16x32_bf16 v[38:41], v[138:141], v[172:175], v[38:41]
	v_mfma_f32_16x16x32_bf16 v[30:33], v[148:151], v[172:175], v[30:33]
	v_mfma_f32_16x16x32_bf16 v[22:25], v[138:141], v[180:183], v[22:25]
	v_mfma_f32_16x16x32_bf16 v[14:17], v[148:151], v[180:183], v[14:17]
	v_mfma_f32_16x16x32_bf16 v[62:65], v[142:145], v[160:163], v[62:65]
	v_mfma_f32_16x16x32_bf16 v[58:61], v[152:155], v[160:163], v[58:61]
	v_mfma_f32_16x16x32_bf16 v[54:57], v[142:145], v[168:171], v[54:57]
	v_mfma_f32_16x16x32_bf16 v[46:49], v[152:155], v[168:171], v[46:49]
	v_mfma_f32_16x16x32_bf16 v[38:41], v[142:145], v[176:179], v[38:41]
	v_mfma_f32_16x16x32_bf16 v[30:33], v[152:155], v[176:179], v[30:33]
	v_mfma_f32_16x16x32_bf16 v[22:25], v[142:145], v[184:187], v[22:25]
	v_mfma_f32_16x16x32_bf16 v[14:17], v[152:155], v[184:187], v[14:17]
	s_barrier
	s_setprio 0
	s_add_i32 s7, s78, s53
	v_lshl_add_u64 v[138:139], v[132:133], 0, s[18:19]
	s_mov_b32 m0, s7
	v_lshl_add_u64 v[132:133], v[132:133], 0, s[14:15]
	global_load_lds_dwordx4 v[138:139], off
	s_add_i32 m0, s7, 0x2000
	s_nop 0
	global_load_lds_dwordx4 v[132:133], off
	s_waitcnt vmcnt(6)
	s_setprio 1
	s_barrier
	v_mfma_f32_16x16x32_bf16 v[50:53], v[188:191], v[156:159], v[50:53]
	v_mfma_f32_16x16x32_bf16 v[42:45], v[196:199], v[156:159], v[42:45]
	v_mfma_f32_16x16x32_bf16 v[34:37], v[188:191], v[164:167], v[34:37]
	v_mfma_f32_16x16x32_bf16 v[26:29], v[196:199], v[164:167], v[26:29]
	v_mfma_f32_16x16x32_bf16 v[18:21], v[188:191], v[172:175], v[18:21]
	v_mfma_f32_16x16x32_bf16 v[10:13], v[196:199], v[172:175], v[10:13]
	v_mfma_f32_16x16x32_bf16 v[6:9], v[188:191], v[180:183], v[6:9]
	v_mfma_f32_16x16x32_bf16 v[2:5], v[196:199], v[180:183], v[2:5]
	v_mfma_f32_16x16x32_bf16 v[50:53], v[192:195], v[160:163], v[50:53]
	v_mfma_f32_16x16x32_bf16 v[42:45], v[200:203], v[160:163], v[42:45]
	v_mfma_f32_16x16x32_bf16 v[34:37], v[192:195], v[168:171], v[34:37]
	v_mfma_f32_16x16x32_bf16 v[26:29], v[200:203], v[168:171], v[26:29]
	v_mfma_f32_16x16x32_bf16 v[18:21], v[192:195], v[176:179], v[18:21]
	v_mfma_f32_16x16x32_bf16 v[10:13], v[200:203], v[176:179], v[10:13]
	v_mfma_f32_16x16x32_bf16 v[6:9], v[192:195], v[184:187], v[6:9]
	v_mfma_f32_16x16x32_bf16 v[2:5], v[200:203], v[184:187], v[2:5]
	s_barrier
	s_setprio 0
	s_add_i32 s6, s6, 2
	s_add_u32 s8, s8, 0x100
	s_addc_u32 s9, s9, 0
	s_add_u32 s46, s46, 0x100
	s_addc_u32 s47, s47, 0
	s_cmpk_gt_u32 s6, 0x55
	s_cbranch_scc0 .LBB0_485
	v_mov_b32_e32 v137, v134
	s_lshl_b32 s6, s86, 8
	v_ashrrev_i32_e32 v132, 2, v137
	s_or_b32 s6, s6, s59
	v_and_b32_e32 v132, -4, v132
	v_add_u32_e32 v132, s6, v132
	s_lshl_b32 s6, s85, 8
	s_add_i32 s6, s6, s58
	v_and_or_b32 v188, v137, 15, s6
	v_ashrrev_i32_e32 v189, 31, v188
	v_ashrrev_i32_e32 v133, 31, v132
	v_lshlrev_b64 v[206:207], 13, v[188:189]
	v_or_b32_e32 v156, 16, v188
	v_or_b32_e32 v172, 32, v188
	v_or_b32_e32 v188, 48, v188
	v_lshlrev_b64 v[132:133], 2, v[132:133]
	v_ashrrev_i32_e32 v157, 31, v156
	v_ashrrev_i32_e32 v173, 31, v172
	v_ashrrev_i32_e32 v189, 31, v188
	v_lshl_add_u64 v[204:205], s[4:5], 0, v[132:133]
	v_lshlrev_b64 v[208:209], 13, v[156:157]
	v_lshlrev_b64 v[210:211], 13, v[172:173]
	v_lshlrev_b64 v[212:213], 13, v[188:189]
	v_lshl_add_u64 v[152:153], v[204:205], 0, v[206:207]
	v_lshl_add_u64 v[168:169], v[204:205], 0, v[208:209]
	v_lshl_add_u64 v[184:185], v[204:205], 0, v[210:211]
	v_lshl_add_u64 v[200:201], v[204:205], 0, v[212:213]
	global_load_dwordx4 v[138:141], v[152:153], off
	global_load_dwordx4 v[142:145], v[152:153], off offset:64
	global_load_dwordx4 v[148:151], v[152:153], off offset:512
	s_nop 0
	global_load_dwordx4 v[152:155], v[152:153], off offset:576
	s_nop 0
	global_load_dwordx4 v[156:159], v[168:169], off
	global_load_dwordx4 v[160:163], v[168:169], off offset:64
	global_load_dwordx4 v[164:167], v[168:169], off offset:512
	s_nop 0
	global_load_dwordx4 v[168:171], v[168:169], off offset:576
	s_nop 0
	global_load_dwordx4 v[172:175], v[184:185], off
	global_load_dwordx4 v[176:179], v[184:185], off offset:64
	global_load_dwordx4 v[180:183], v[184:185], off offset:512
	s_nop 0
	global_load_dwordx4 v[184:187], v[184:185], off offset:576
	s_nop 0
	global_load_dwordx4 v[188:191], v[200:201], off
	global_load_dwordx4 v[192:195], v[200:201], off offset:64
	global_load_dwordx4 v[196:199], v[200:201], off offset:512
	s_nop 0
	global_load_dwordx4 v[200:203], v[200:201], off offset:576
	s_waitcnt vmcnt(0) lgkmcnt(0)
	v_pk_fma_f32 v[126:127], v[126:127], 0.5, v[138:139] op_sel_hi:[1,0,1]
	v_lshl_add_u64 v[138:139], s[4:5], 0, v[206:207]
	v_lshl_add_u64 v[138:139], v[138:139], 0, v[132:133]
	v_pk_fma_f32 v[116:117], v[116:117], 0.5, v[150:151] op_sel_hi:[1,0,1]
	v_pk_fma_f32 v[114:115], v[114:115], 0.5, v[148:149] op_sel_hi:[1,0,1]
	global_store_dwordx4 v[138:139], v[114:117], off offset:512
	v_pk_fma_f32 v[100:101], v[100:101], 0.5, v[166:167] op_sel_hi:[1,0,1]
	v_pk_fma_f32 v[98:99], v[98:99], 0.5, v[164:165] op_sel_hi:[1,0,1]
	v_lshl_add_u64 v[114:115], s[4:5], 0, v[208:209]
	v_lshl_add_u64 v[114:115], v[114:115], 0, v[132:133]
	global_store_dwordx4 v[114:115], v[98:101], off offset:512
	v_pk_fma_f32 v[84:85], v[84:85], 0.5, v[182:183] op_sel_hi:[1,0,1]
	v_pk_fma_f32 v[82:83], v[82:83], 0.5, v[180:181] op_sel_hi:[1,0,1]
	v_lshl_add_u64 v[98:99], s[4:5], 0, v[210:211]
	v_lshl_add_u64 v[98:99], v[98:99], 0, v[132:133]
	v_pk_fma_f32 v[108:109], v[108:109], 0.5, v[154:155] op_sel_hi:[1,0,1]
	v_pk_fma_f32 v[106:107], v[106:107], 0.5, v[152:153] op_sel_hi:[1,0,1]
	v_pk_fma_f32 v[92:93], v[92:93], 0.5, v[170:171] op_sel_hi:[1,0,1]
	v_pk_fma_f32 v[90:91], v[90:91], 0.5, v[168:169] op_sel_hi:[1,0,1]
	global_store_dwordx4 v[98:99], v[82:85], off offset:512
	v_pk_fma_f32 v[76:77], v[76:77], 0.5, v[186:187] op_sel_hi:[1,0,1]
	v_pk_fma_f32 v[74:75], v[74:75], 0.5, v[184:185] op_sel_hi:[1,0,1]
	v_lshl_add_u64 v[82:83], s[4:5], 0, v[212:213]
	global_store_dwordx4 v[138:139], v[106:109], off offset:576
	global_store_dwordx4 v[114:115], v[90:93], off offset:576
	global_store_dwordx4 v[98:99], v[74:77], off offset:576
	v_pk_fma_f32 v[108:109], v[120:121], 0.5, v[158:159] op_sel_hi:[1,0,1]
	v_pk_fma_f32 v[106:107], v[118:119], 0.5, v[156:157] op_sel_hi:[1,0,1]
	v_pk_fma_f32 v[92:93], v[104:105], 0.5, v[174:175] op_sel_hi:[1,0,1]
	v_pk_fma_f32 v[90:91], v[102:103], 0.5, v[172:173] op_sel_hi:[1,0,1]
	v_pk_fma_f32 v[76:77], v[88:89], 0.5, v[190:191] op_sel_hi:[1,0,1]
	v_pk_fma_f32 v[74:75], v[86:87], 0.5, v[188:189] op_sel_hi:[1,0,1]
	v_lshl_add_u64 v[82:83], v[82:83], 0, v[132:133]
	v_pk_fma_f32 v[128:129], v[128:129], 0.5, v[140:141] op_sel_hi:[1,0,1]
	v_pk_fma_f32 v[124:125], v[124:125], 0.5, v[144:145] op_sel_hi:[1,0,1]
	v_pk_fma_f32 v[122:123], v[122:123], 0.5, v[142:143] op_sel_hi:[1,0,1]
	global_store_dwordx4 v[114:115], v[106:109], off
	global_store_dwordx4 v[98:99], v[90:93], off
	global_store_dwordx4 v[82:83], v[74:77], off
	v_pk_fma_f32 v[108:109], v[112:113], 0.5, v[162:163] op_sel_hi:[1,0,1]
	v_pk_fma_f32 v[106:107], v[110:111], 0.5, v[160:161] op_sel_hi:[1,0,1]
	v_pk_fma_f32 v[92:93], v[96:97], 0.5, v[178:179] op_sel_hi:[1,0,1]
	v_pk_fma_f32 v[90:91], v[94:95], 0.5, v[176:177] op_sel_hi:[1,0,1]
	v_pk_fma_f32 v[76:77], v[80:81], 0.5, v[194:195] op_sel_hi:[1,0,1]
	v_pk_fma_f32 v[74:75], v[78:79], 0.5, v[192:193] op_sel_hi:[1,0,1]
	v_pk_fma_f32 v[72:73], v[72:73], 0.5, v[198:199] op_sel_hi:[1,0,1]
	v_pk_fma_f32 v[70:71], v[70:71], 0.5, v[196:197] op_sel_hi:[1,0,1]
	v_pk_fma_f32 v[68:69], v[68:69], 0.5, v[202:203] op_sel_hi:[1,0,1]
	v_pk_fma_f32 v[66:67], v[66:67], 0.5, v[200:201] op_sel_hi:[1,0,1]
	global_store_dwordx4 v[138:139], v[126:129], off
	global_store_dwordx4 v[138:139], v[122:125], off offset:64
	global_store_dwordx4 v[114:115], v[106:109], off offset:64
	global_store_dwordx4 v[98:99], v[90:93], off offset:64
	global_store_dwordx4 v[82:83], v[74:77], off offset:64
	global_store_dwordx4 v[82:83], v[70:73], off offset:512
	global_store_dwordx4 v[82:83], v[66:69], off offset:576
	s_mov_b64 s[6:7], 0x120000
	v_lshl_add_u64 v[140:141], v[206:207], 0, s[6:7]
	s_mov_b64 s[6:7], 0x140000
	v_lshl_add_u64 v[138:139], v[206:207], 0, s[0:1]
	v_lshl_add_u64 v[142:143], v[206:207], 0, s[6:7]
	v_lshl_add_u64 v[144:145], v[206:207], 0, s[28:29]
	v_lshl_add_u64 v[78:79], v[204:205], 0, v[138:139]
	v_lshl_add_u64 v[94:95], v[204:205], 0, v[140:141]
	v_lshl_add_u64 v[110:111], v[204:205], 0, v[142:143]
	v_lshl_add_u64 v[126:127], v[204:205], 0, v[144:145]
	global_load_dwordx4 v[66:69], v[78:79], off
	global_load_dwordx4 v[70:73], v[78:79], off offset:64
	global_load_dwordx4 v[74:77], v[78:79], off offset:512
	s_nop 0
	global_load_dwordx4 v[78:81], v[78:79], off offset:576
	s_nop 0
	global_load_dwordx4 v[82:85], v[94:95], off
	global_load_dwordx4 v[86:89], v[94:95], off offset:64
	global_load_dwordx4 v[90:93], v[94:95], off offset:512
	s_nop 0
	global_load_dwordx4 v[94:97], v[94:95], off offset:576
	s_nop 0
	global_load_dwordx4 v[98:101], v[110:111], off
	global_load_dwordx4 v[102:105], v[110:111], off offset:64
	global_load_dwordx4 v[106:109], v[110:111], off offset:512
	s_nop 0
	global_load_dwordx4 v[110:113], v[110:111], off offset:576
	s_nop 0
	global_load_dwordx4 v[114:117], v[126:127], off
	global_load_dwordx4 v[118:121], v[126:127], off offset:64
	global_load_dwordx4 v[122:125], v[126:127], off offset:512
	s_nop 0
	global_load_dwordx4 v[126:129], v[126:127], off offset:576
	s_waitcnt vmcnt(0) lgkmcnt(0)
	v_pk_fma_f32 v[62:63], v[62:63], 0.5, v[66:67] op_sel_hi:[1,0,1]
	v_lshl_add_u64 v[66:67], s[4:5], 0, v[138:139]
	v_lshl_add_u64 v[66:67], v[66:67], 0, v[132:133]
	v_pk_fma_f32 v[52:53], v[52:53], 0.5, v[76:77] op_sel_hi:[1,0,1]
	v_pk_fma_f32 v[50:51], v[50:51], 0.5, v[74:75] op_sel_hi:[1,0,1]
	global_store_dwordx4 v[66:67], v[50:53], off offset:512
	v_pk_fma_f32 v[36:37], v[36:37], 0.5, v[92:93] op_sel_hi:[1,0,1]
	v_pk_fma_f32 v[34:35], v[34:35], 0.5, v[90:91] op_sel_hi:[1,0,1]
	v_lshl_add_u64 v[50:51], s[4:5], 0, v[140:141]
	v_lshl_add_u64 v[50:51], v[50:51], 0, v[132:133]
	global_store_dwordx4 v[50:51], v[34:37], off offset:512
	v_pk_fma_f32 v[20:21], v[20:21], 0.5, v[108:109] op_sel_hi:[1,0,1]
	v_pk_fma_f32 v[18:19], v[18:19], 0.5, v[106:107] op_sel_hi:[1,0,1]
	v_lshl_add_u64 v[34:35], s[4:5], 0, v[142:143]
	v_lshl_add_u64 v[34:35], v[34:35], 0, v[132:133]
	v_pk_fma_f32 v[44:45], v[44:45], 0.5, v[80:81] op_sel_hi:[1,0,1]
	v_pk_fma_f32 v[42:43], v[42:43], 0.5, v[78:79] op_sel_hi:[1,0,1]
	v_pk_fma_f32 v[28:29], v[28:29], 0.5, v[96:97] op_sel_hi:[1,0,1]
	v_pk_fma_f32 v[26:27], v[26:27], 0.5, v[94:95] op_sel_hi:[1,0,1]
	global_store_dwordx4 v[34:35], v[18:21], off offset:512
	v_pk_fma_f32 v[12:13], v[12:13], 0.5, v[112:113] op_sel_hi:[1,0,1]
	v_pk_fma_f32 v[10:11], v[10:11], 0.5, v[110:111] op_sel_hi:[1,0,1]
	v_lshl_add_u64 v[18:19], s[4:5], 0, v[144:145]
	global_store_dwordx4 v[66:67], v[42:45], off offset:576
	global_store_dwordx4 v[50:51], v[26:29], off offset:576
	global_store_dwordx4 v[34:35], v[10:13], off offset:576
	v_pk_fma_f32 v[44:45], v[56:57], 0.5, v[84:85] op_sel_hi:[1,0,1]
	v_pk_fma_f32 v[42:43], v[54:55], 0.5, v[82:83] op_sel_hi:[1,0,1]
	v_pk_fma_f32 v[28:29], v[40:41], 0.5, v[100:101] op_sel_hi:[1,0,1]
	v_pk_fma_f32 v[26:27], v[38:39], 0.5, v[98:99] op_sel_hi:[1,0,1]
	v_pk_fma_f32 v[12:13], v[24:25], 0.5, v[116:117] op_sel_hi:[1,0,1]
	v_pk_fma_f32 v[10:11], v[22:23], 0.5, v[114:115] op_sel_hi:[1,0,1]
	v_lshl_add_u64 v[18:19], v[18:19], 0, v[132:133]
	v_pk_fma_f32 v[64:65], v[64:65], 0.5, v[68:69] op_sel_hi:[1,0,1]
	v_pk_fma_f32 v[60:61], v[60:61], 0.5, v[72:73] op_sel_hi:[1,0,1]
	v_pk_fma_f32 v[58:59], v[58:59], 0.5, v[70:71] op_sel_hi:[1,0,1]
	global_store_dwordx4 v[50:51], v[42:45], off
	global_store_dwordx4 v[34:35], v[26:29], off
	global_store_dwordx4 v[18:19], v[10:13], off
	v_pk_fma_f32 v[44:45], v[48:49], 0.5, v[88:89] op_sel_hi:[1,0,1]
	v_pk_fma_f32 v[42:43], v[46:47], 0.5, v[86:87] op_sel_hi:[1,0,1]
	v_pk_fma_f32 v[28:29], v[32:33], 0.5, v[104:105] op_sel_hi:[1,0,1]
	v_pk_fma_f32 v[26:27], v[30:31], 0.5, v[102:103] op_sel_hi:[1,0,1]
	v_pk_fma_f32 v[12:13], v[16:17], 0.5, v[120:121] op_sel_hi:[1,0,1]
	v_pk_fma_f32 v[10:11], v[14:15], 0.5, v[118:119] op_sel_hi:[1,0,1]
	v_pk_fma_f32 v[8:9], v[8:9], 0.5, v[124:125] op_sel_hi:[1,0,1]
	v_pk_fma_f32 v[6:7], v[6:7], 0.5, v[122:123] op_sel_hi:[1,0,1]
	v_pk_fma_f32 v[4:5], v[4:5], 0.5, v[128:129] op_sel_hi:[1,0,1]
	v_pk_fma_f32 v[2:3], v[2:3], 0.5, v[126:127] op_sel_hi:[1,0,1]
	global_store_dwordx4 v[66:67], v[62:65], off
	global_store_dwordx4 v[66:67], v[58:61], off offset:64
	global_store_dwordx4 v[50:51], v[42:45], off offset:64
	global_store_dwordx4 v[34:35], v[26:29], off offset:64
	global_store_dwordx4 v[18:19], v[10:13], off offset:64
	global_store_dwordx4 v[18:19], v[6:9], off offset:512
	global_store_dwordx4 v[18:19], v[2:5], off offset:576
	s_and_b64 vcc, exec, s[40:41]
	s_mov_b32 s85, s10
	s_mov_b32 s86, s11
	s_mov_b64 s[8:9], s[44:45]
	s_mov_b64 s[6:7], s[42:43]
	s_movk_i32 s89, 0x37ff
	s_mov_b32 s88, 0x16000
	s_movk_i32 s91, 0x60
	s_mov_b32 s78, 0x2a000000
	s_mov_b32 s79, 0x3fffe
	s_mov_b32 s90, 0xc0000
	s_cbranch_vccz .LBB0_478
	s_waitcnt vmcnt(0)
	s_cmpk_gt_u32 s48, 0xff
	s_cbranch_scc1 .LBB0_489
	s_barrier

.LBB0_503:
	s_add_u32 s8, s6, 0x100
	s_addc_u32 s9, s7, 0
	s_add_i32 s78, 0, 0x10000
	v_add_u32_e32 v134, s78, v137
	ds_read_b128 v[140:143], v134
	ds_read_b128 v[148:151], v134 offset:1024
	ds_read_b128 v[152:155], v134 offset:2048
	ds_read_b128 v[156:159], v134 offset:3072
	s_cmp_eq_u32 s87, 28
	s_cselect_b32 s89, s43, s9
	s_cselect_b32 s88, s42, s8
	s_cselect_b32 s91, s47, s86
	s_cselect_b32 s90, s46, s41
	v_lshl_add_u64 v[134:135], s[6:7], 0, v[132:133]
	v_lshl_add_u64 v[144:145], v[134:135], 0, s[16:17]
	s_add_i32 m0, s49, 0xc000
	ds_read_b128 v[160:163], v138
	ds_read_b128 v[164:167], v138 offset:1024
	ds_read_b128 v[168:171], v138 offset:2048
	ds_read_b128 v[172:175], v138 offset:3072
	ds_read_b128 v[176:179], v138 offset:4096
	ds_read_b128 v[180:183], v138 offset:5120
	ds_read_b128 v[184:187], v138 offset:6144
	ds_read_b128 v[188:191], v138 offset:7168
	global_load_lds_dwordx4 v[144:145], off
	v_lshl_add_u64 v[134:135], v[134:135], 0, s[80:81]
	s_add_i32 m0, s49, 0xe000
	s_nop 0
	global_load_lds_dwordx4 v[134:135], off
	s_waitcnt lgkmcnt(8)
	s_setprio 1
	s_barrier
	s_waitcnt lgkmcnt(0)
	v_mfma_f32_16x16x32_bf16 v[126:129], v[140:143], v[160:163], v[126:129]
	v_mfma_f32_16x16x32_bf16 v[118:121], v[152:155], v[160:163], v[118:121]
	v_mfma_f32_16x16x32_bf16 v[110:113], v[140:143], v[168:171], v[110:113]
	v_mfma_f32_16x16x32_bf16 v[102:105], v[152:155], v[168:171], v[102:105]
	v_mfma_f32_16x16x32_bf16 v[94:97], v[140:143], v[176:179], v[94:97]
	v_mfma_f32_16x16x32_bf16 v[86:89], v[152:155], v[176:179], v[86:89]
	v_mfma_f32_16x16x32_bf16 v[78:81], v[140:143], v[184:187], v[78:81]
	v_mfma_f32_16x16x32_bf16 v[70:73], v[152:155], v[184:187], v[70:73]
	v_mfma_f32_16x16x32_bf16 v[126:129], v[148:151], v[164:167], v[126:129]
	v_mfma_f32_16x16x32_bf16 v[118:121], v[156:159], v[164:167], v[118:121]
	v_mfma_f32_16x16x32_bf16 v[110:113], v[148:151], v[172:175], v[110:113]
	v_mfma_f32_16x16x32_bf16 v[102:105], v[156:159], v[172:175], v[102:105]
	v_mfma_f32_16x16x32_bf16 v[94:97], v[148:151], v[180:183], v[94:97]
	v_mfma_f32_16x16x32_bf16 v[86:89], v[156:159], v[180:183], v[86:89]
	v_mfma_f32_16x16x32_bf16 v[78:81], v[148:151], v[188:191], v[78:81]
	v_mfma_f32_16x16x32_bf16 v[70:73], v[156:159], v[188:191], v[70:73]
	s_barrier
	s_setprio 0
	s_add_i32 s6, 0, 0x14000
	v_add_u32_e32 v134, s6, v137
	s_add_i32 s7, s78, s54
	ds_read_b128 v[192:195], v134
	ds_read_b128 v[196:199], v134 offset:1024
	ds_read_b128 v[200:203], v134 offset:2048
	ds_read_b128 v[204:207], v134 offset:3072
	v_lshl_add_u64 v[134:135], s[90:91], 0, v[0:1]
	s_mov_b32 m0, s7
	v_lshl_add_u64 v[144:145], v[134:135], 0, s[60:61]
	global_load_lds_dwordx4 v[134:135], off
	s_add_i32 m0, s7, 0x2000
	s_nop 0
	global_load_lds_dwordx4 v[144:145], off
	s_setprio 1
	s_barrier
	s_waitcnt lgkmcnt(0)
	v_mfma_f32_16x16x32_bf16 v[122:125], v[192:195], v[160:163], v[122:125]
	v_mfma_f32_16x16x32_bf16 v[114:117], v[200:203], v[160:163], v[114:117]
	v_mfma_f32_16x16x32_bf16 v[106:109], v[192:195], v[168:171], v[106:109]
	v_mfma_f32_16x16x32_bf16 v[98:101], v[200:203], v[168:171], v[98:101]
	v_mfma_f32_16x16x32_bf16 v[90:93], v[192:195], v[176:179], v[90:93]
	v_mfma_f32_16x16x32_bf16 v[82:85], v[200:203], v[176:179], v[82:85]
	v_mfma_f32_16x16x32_bf16 v[74:77], v[192:195], v[184:187], v[74:77]
	v_mfma_f32_16x16x32_bf16 v[66:69], v[200:203], v[184:187], v[66:69]
	v_mfma_f32_16x16x32_bf16 v[122:125], v[196:199], v[164:167], v[122:125]
	v_mfma_f32_16x16x32_bf16 v[114:117], v[204:207], v[164:167], v[114:117]
	v_mfma_f32_16x16x32_bf16 v[106:109], v[196:199], v[172:175], v[106:109]
	v_mfma_f32_16x16x32_bf16 v[98:101], v[204:207], v[172:175], v[98:101]
	v_mfma_f32_16x16x32_bf16 v[90:93], v[196:199], v[180:183], v[90:93]
	v_mfma_f32_16x16x32_bf16 v[82:85], v[204:207], v[180:183], v[82:85]
	v_mfma_f32_16x16x32_bf16 v[74:77], v[196:199], v[188:191], v[74:77]
	v_mfma_f32_16x16x32_bf16 v[66:69], v[204:207], v[188:191], v[66:69]
	s_barrier
	s_setprio 0
	s_mov_b32 m0, s49
	v_lshl_add_u64 v[144:145], s[88:89], 0, v[130:131]
	ds_read_b128 v[160:163], v138 offset:16384
	ds_read_b128 v[164:167], v138 offset:17408
	ds_read_b128 v[168:171], v138 offset:18432
	ds_read_b128 v[172:175], v138 offset:19456
	ds_read_b128 v[176:179], v138 offset:20480
	ds_read_b128 v[180:183], v138 offset:21504
	ds_read_b128 v[184:187], v138 offset:22528
	ds_read_b128 v[188:191], v138 offset:23552
	global_load_lds_dwordx4 v[144:145], off
	v_lshl_add_u64 v[208:209], v[144:145], 0, s[60:61]
	s_mov_b32 m0, s55
	s_nop 0
	global_load_lds_dwordx4 v[208:209], off
	s_setprio 1
	s_barrier
	s_waitcnt lgkmcnt(0)
	v_mfma_f32_16x16x32_bf16 v[62:65], v[140:143], v[160:163], v[62:65]
	v_mfma_f32_16x16x32_bf16 v[54:57], v[152:155], v[160:163], v[54:57]
	v_mfma_f32_16x16x32_bf16 v[46:49], v[140:143], v[168:171], v[46:49]
	v_mfma_f32_16x16x32_bf16 v[38:41], v[152:155], v[168:171], v[38:41]
	v_mfma_f32_16x16x32_bf16 v[30:33], v[140:143], v[176:179], v[30:33]
	v_mfma_f32_16x16x32_bf16 v[22:25], v[152:155], v[176:179], v[22:25]
	v_mfma_f32_16x16x32_bf16 v[14:17], v[140:143], v[184:187], v[14:17]
	v_mfma_f32_16x16x32_bf16 v[6:9], v[152:155], v[184:187], v[6:9]
	v_mfma_f32_16x16x32_bf16 v[62:65], v[148:151], v[164:167], v[62:65]
	v_mfma_f32_16x16x32_bf16 v[54:57], v[156:159], v[164:167], v[54:57]
	v_mfma_f32_16x16x32_bf16 v[46:49], v[148:151], v[172:175], v[46:49]
	v_mfma_f32_16x16x32_bf16 v[38:41], v[156:159], v[172:175], v[38:41]
	v_mfma_f32_16x16x32_bf16 v[30:33], v[148:151], v[180:183], v[30:33]
	v_mfma_f32_16x16x32_bf16 v[22:25], v[156:159], v[180:183], v[22:25]
	v_mfma_f32_16x16x32_bf16 v[14:17], v[148:151], v[188:191], v[14:17]
	v_mfma_f32_16x16x32_bf16 v[6:9], v[156:159], v[188:191], v[6:9]
	s_barrier
	s_setprio 0
	s_add_i32 s6, s6, s54
	v_lshl_add_u64 v[140:141], v[134:135], 0, s[20:21]
	s_mov_b32 m0, s6
	s_nop 0
	global_load_lds_dwordx4 v[140:141], off
	v_lshl_add_u64 v[140:141], v[134:135], 0, s[64:65]
	s_add_i32 m0, s6, 0x2000
	s_nop 0
	global_load_lds_dwordx4 v[140:141], off
	s_waitcnt vmcnt(6)
	s_setprio 1
	s_barrier
	v_mfma_f32_16x16x32_bf16 v[58:61], v[192:195], v[160:163], v[58:61]
	v_mfma_f32_16x16x32_bf16 v[50:53], v[200:203], v[160:163], v[50:53]
	v_mfma_f32_16x16x32_bf16 v[42:45], v[192:195], v[168:171], v[42:45]
	v_mfma_f32_16x16x32_bf16 v[34:37], v[200:203], v[168:171], v[34:37]
	v_mfma_f32_16x16x32_bf16 v[26:29], v[192:195], v[176:179], v[26:29]
	v_mfma_f32_16x16x32_bf16 v[18:21], v[200:203], v[176:179], v[18:21]
	v_mfma_f32_16x16x32_bf16 v[10:13], v[192:195], v[184:187], v[10:13]
	v_mfma_f32_16x16x32_bf16 v[2:5], v[200:203], v[184:187], v[2:5]
	v_mfma_f32_16x16x32_bf16 v[58:61], v[196:199], v[164:167], v[58:61]
	v_mfma_f32_16x16x32_bf16 v[50:53], v[204:207], v[164:167], v[50:53]
	v_mfma_f32_16x16x32_bf16 v[42:45], v[196:199], v[172:175], v[42:45]
	v_mfma_f32_16x16x32_bf16 v[34:37], v[204:207], v[172:175], v[34:37]
	v_mfma_f32_16x16x32_bf16 v[26:29], v[196:199], v[180:183], v[26:29]
	v_mfma_f32_16x16x32_bf16 v[18:21], v[204:207], v[180:183], v[18:21]
	v_mfma_f32_16x16x32_bf16 v[10:13], v[196:199], v[188:191], v[10:13]
	v_mfma_f32_16x16x32_bf16 v[2:5], v[204:207], v[188:191], v[2:5]
	s_barrier
	s_setprio 0
	s_add_i32 s6, 0, 0x18000
	v_add_u32_e32 v139, s6, v137
	ds_read_b128 v[140:143], v139
	ds_read_b128 v[148:151], v139 offset:1024
	ds_read_b128 v[152:155], v139 offset:2048
	ds_read_b128 v[156:159], v139 offset:3072
	s_mov_b32 m0, s56
	v_lshl_add_u64 v[192:193], v[144:145], 0, s[20:21]
	ds_read_b128 v[160:163], v138 offset:32768
	ds_read_b128 v[164:167], v138 offset:33792
	ds_read_b128 v[168:171], v138 offset:34816
	ds_read_b128 v[172:175], v138 offset:35840
	ds_read_b128 v[176:179], v138 offset:36864
	ds_read_b128 v[180:183], v138 offset:37888
	ds_read_b128 v[184:187], v138 offset:38912
	ds_read_b128 v[188:191], v138 offset:39936
	global_load_lds_dwordx4 v[192:193], off
	v_lshl_add_u64 v[192:193], v[144:145], 0, s[64:65]
	s_mov_b32 m0, s57
	s_nop 0
	global_load_lds_dwordx4 v[192:193], off
	s_waitcnt lgkmcnt(8)
	s_setprio 1
	s_barrier
	s_waitcnt lgkmcnt(0)
	v_mfma_f32_16x16x32_bf16 v[126:129], v[140:143], v[160:163], v[126:129]
	v_mfma_f32_16x16x32_bf16 v[118:121], v[152:155], v[160:163], v[118:121]
	v_mfma_f32_16x16x32_bf16 v[110:113], v[140:143], v[168:171], v[110:113]
	v_mfma_f32_16x16x32_bf16 v[102:105], v[152:155], v[168:171], v[102:105]
	v_mfma_f32_16x16x32_bf16 v[94:97], v[140:143], v[176:179], v[94:97]
	v_mfma_f32_16x16x32_bf16 v[86:89], v[152:155], v[176:179], v[86:89]
	v_mfma_f32_16x16x32_bf16 v[78:81], v[140:143], v[184:187], v[78:81]
	v_mfma_f32_16x16x32_bf16 v[70:73], v[152:155], v[184:187], v[70:73]
	v_mfma_f32_16x16x32_bf16 v[126:129], v[148:151], v[164:167], v[126:129]
	v_mfma_f32_16x16x32_bf16 v[118:121], v[156:159], v[164:167], v[118:121]
	v_mfma_f32_16x16x32_bf16 v[110:113], v[148:151], v[172:175], v[110:113]
	v_mfma_f32_16x16x32_bf16 v[102:105], v[156:159], v[172:175], v[102:105]
	v_mfma_f32_16x16x32_bf16 v[94:97], v[148:151], v[180:183], v[94:97]
	v_mfma_f32_16x16x32_bf16 v[86:89], v[156:159], v[180:183], v[86:89]
	v_mfma_f32_16x16x32_bf16 v[78:81], v[148:151], v[188:191], v[78:81]
	v_mfma_f32_16x16x32_bf16 v[70:73], v[156:159], v[188:191], v[70:73]
	s_barrier
	s_setprio 0
	s_add_i32 s7, 0, 0x1c000
	s_add_i32 s6, s6, s54
	v_add_u32_e32 v139, s7, v137
	v_lshl_add_u64 v[208:209], v[134:135], 0, s[34:35]
	s_mov_b32 m0, s6
	ds_read_b128 v[192:195], v139
	ds_read_b128 v[196:199], v139 offset:1024
	ds_read_b128 v[200:203], v139 offset:2048
	ds_read_b128 v[204:207], v139 offset:3072
	global_load_lds_dwordx4 v[208:209], off
	v_lshl_add_u64 v[208:209], v[134:135], 0, s[66:67]
	s_add_i32 m0, s6, 0x2000
	s_nop 0
	global_load_lds_dwordx4 v[208:209], off
	s_setprio 1
	s_barrier
	s_waitcnt lgkmcnt(0)
	v_mfma_f32_16x16x32_bf16 v[122:125], v[192:195], v[160:163], v[122:125]
	v_mfma_f32_16x16x32_bf16 v[114:117], v[200:203], v[160:163], v[114:117]
	v_mfma_f32_16x16x32_bf16 v[106:109], v[192:195], v[168:171], v[106:109]
	v_mfma_f32_16x16x32_bf16 v[98:101], v[200:203], v[168:171], v[98:101]
	v_mfma_f32_16x16x32_bf16 v[90:93], v[192:195], v[176:179], v[90:93]
	v_mfma_f32_16x16x32_bf16 v[82:85], v[200:203], v[176:179], v[82:85]
	v_mfma_f32_16x16x32_bf16 v[74:77], v[192:195], v[184:187], v[74:77]
	v_mfma_f32_16x16x32_bf16 v[66:69], v[200:203], v[184:187], v[66:69]
	v_mfma_f32_16x16x32_bf16 v[122:125], v[196:199], v[164:167], v[122:125]
	v_mfma_f32_16x16x32_bf16 v[114:117], v[204:207], v[164:167], v[114:117]
	v_mfma_f32_16x16x32_bf16 v[106:109], v[196:199], v[172:175], v[106:109]
	v_mfma_f32_16x16x32_bf16 v[98:101], v[204:207], v[172:175], v[98:101]
	v_mfma_f32_16x16x32_bf16 v[90:93], v[196:199], v[180:183], v[90:93]
	v_mfma_f32_16x16x32_bf16 v[82:85], v[204:207], v[180:183], v[82:85]
	v_mfma_f32_16x16x32_bf16 v[74:77], v[196:199], v[188:191], v[74:77]
	v_mfma_f32_16x16x32_bf16 v[66:69], v[204:207], v[188:191], v[66:69]
	s_barrier
	s_setprio 0
	s_mov_b32 m0, s59
	v_lshl_add_u64 v[208:209], v[144:145], 0, s[34:35]
	ds_read_b128 v[160:163], v138 offset:49152
	ds_read_b128 v[164:167], v138 offset:50176
	ds_read_b128 v[168:171], v138 offset:51200
	ds_read_b128 v[172:175], v138 offset:52224
	ds_read_b128 v[176:179], v138 offset:53248
	ds_read_b128 v[180:183], v138 offset:54272
	ds_read_b128 v[184:187], v138 offset:55296
	ds_read_b128 v[188:191], v138 offset:56320
	global_load_lds_dwordx4 v[208:209], off
	v_lshl_add_u64 v[144:145], v[144:145], 0, s[66:67]
	s_mov_b32 m0, s62
	s_nop 0
	global_load_lds_dwordx4 v[144:145], off
	s_setprio 1
	s_barrier
	s_waitcnt lgkmcnt(0)
	v_mfma_f32_16x16x32_bf16 v[62:65], v[140:143], v[160:163], v[62:65]
	v_mfma_f32_16x16x32_bf16 v[54:57], v[152:155], v[160:163], v[54:57]
	v_mfma_f32_16x16x32_bf16 v[46:49], v[140:143], v[168:171], v[46:49]
	v_mfma_f32_16x16x32_bf16 v[38:41], v[152:155], v[168:171], v[38:41]
	v_mfma_f32_16x16x32_bf16 v[30:33], v[140:143], v[176:179], v[30:33]
	v_mfma_f32_16x16x32_bf16 v[22:25], v[152:155], v[176:179], v[22:25]
	v_mfma_f32_16x16x32_bf16 v[14:17], v[140:143], v[184:187], v[14:17]
	v_mfma_f32_16x16x32_bf16 v[6:9], v[152:155], v[184:187], v[6:9]
	v_mfma_f32_16x16x32_bf16 v[62:65], v[148:151], v[164:167], v[62:65]
	v_mfma_f32_16x16x32_bf16 v[54:57], v[156:159], v[164:167], v[54:57]
	v_mfma_f32_16x16x32_bf16 v[46:49], v[148:151], v[172:175], v[46:49]
	v_mfma_f32_16x16x32_bf16 v[38:41], v[156:159], v[172:175], v[38:41]
	v_mfma_f32_16x16x32_bf16 v[30:33], v[148:151], v[180:183], v[30:33]
	v_mfma_f32_16x16x32_bf16 v[22:25], v[156:159], v[180:183], v[22:25]
	v_mfma_f32_16x16x32_bf16 v[14:17], v[148:151], v[188:191], v[14:17]
	v_mfma_f32_16x16x32_bf16 v[6:9], v[156:159], v[188:191], v[6:9]
	s_barrier
	s_setprio 0
	s_add_i32 s6, s7, s54
	v_lshl_add_u64 v[140:141], v[134:135], 0, s[16:17]
	s_mov_b32 m0, s6
	v_lshl_add_u64 v[134:135], v[134:135], 0, s[80:81]
	global_load_lds_dwordx4 v[140:141], off
	s_add_i32 m0, s6, 0x2000
	s_nop 0
	global_load_lds_dwordx4 v[134:135], off
	s_waitcnt vmcnt(6)
	s_setprio 1
	s_barrier
	v_mfma_f32_16x16x32_bf16 v[58:61], v[192:195], v[160:163], v[58:61]
	v_mfma_f32_16x16x32_bf16 v[50:53], v[200:203], v[160:163], v[50:53]
	v_mfma_f32_16x16x32_bf16 v[42:45], v[192:195], v[168:171], v[42:45]
	v_mfma_f32_16x16x32_bf16 v[34:37], v[200:203], v[168:171], v[34:37]
	v_mfma_f32_16x16x32_bf16 v[26:29], v[192:195], v[176:179], v[26:29]
	v_mfma_f32_16x16x32_bf16 v[18:21], v[200:203], v[176:179], v[18:21]
	v_mfma_f32_16x16x32_bf16 v[10:13], v[192:195], v[184:187], v[10:13]
	v_mfma_f32_16x16x32_bf16 v[2:5], v[200:203], v[184:187], v[2:5]
	v_mfma_f32_16x16x32_bf16 v[58:61], v[196:199], v[164:167], v[58:61]
	v_mfma_f32_16x16x32_bf16 v[50:53], v[204:207], v[164:167], v[50:53]
	v_mfma_f32_16x16x32_bf16 v[42:45], v[196:199], v[172:175], v[42:45]
	v_mfma_f32_16x16x32_bf16 v[34:37], v[204:207], v[172:175], v[34:37]
	v_mfma_f32_16x16x32_bf16 v[26:29], v[196:199], v[180:183], v[26:29]
	v_mfma_f32_16x16x32_bf16 v[18:21], v[204:207], v[180:183], v[18:21]
	v_mfma_f32_16x16x32_bf16 v[10:13], v[196:199], v[188:191], v[10:13]
	v_mfma_f32_16x16x32_bf16 v[2:5], v[204:207], v[188:191], v[2:5]
	s_barrier
	s_setprio 0
	s_add_i32 s87, s87, 2
	s_add_u32 s41, s41, 0x100
	s_addc_u32 s86, s86, 0
	s_cmp_gt_u32 s87, 29
	s_mov_b64 s[6:7], s[8:9]
	s_cbranch_scc0 .LBB0_503
	v_mul_f32_e32 v144, 0xbfb8aa3b, v126
	v_exp_f32_e32 v144, v144
	v_mov_b32_e32 v134, v136
	s_lshl_b32 s6, s48, 8
	v_add_f32_e32 v144, 1.0, v144
	v_rcp_f32_e32 v144, v144
	s_add_i32 s6, s6, s10
	v_and_or_b32 v139, v134, 15, s6
	s_lshl_b32 s6, s85, 7
	v_mul_f32_e32 v126, v126, v144
	v_mul_f32_e32 v122, v126, v122
	v_mul_f32_e32 v126, 0xbfb8aa3b, v127
	v_exp_f32_e32 v126, v126
	v_ashrrev_i32_e32 v134, 1, v134
	s_or_b32 s6, s6, s58
	v_and_b32_e32 v134, -8, v134
	v_add_f32_e32 v126, 1.0, v126
	v_rcp_f32_e32 v126, v126
	v_add_u32_e32 v140, s6, v134
	v_ashrrev_i32_e32 v141, 31, v140
	v_mov_b64_e32 v[134:135], s[4:5]
	v_mul_f32_e32 v126, v127, v126
	v_mul_f32_e32 v123, v126, v123
	v_mul_f32_e32 v126, 0xbfb8aa3b, v128
	v_exp_f32_e32 v126, v126
	v_mad_i64_i32 v[142:143], s[6:7], v139, s74, v[134:135]
	s_and_b64 vcc, exec, s[44:45]
	v_add_f32_e32 v126, 1.0, v126
	v_rcp_f32_e32 v126, v126
	s_mov_b32 s48, s40
	s_mov_b32 s85, s84
	s_mov_b64 s[8:9], s[46:47]
	v_mul_f32_e32 v126, v128, v126
	v_mul_f32_e32 v124, v126, v124
	v_mul_f32_e32 v126, 0xbfb8aa3b, v129
	v_exp_f32_e32 v126, v126
	s_nop 0
	v_add_f32_e32 v126, 1.0, v126
	v_rcp_f32_e32 v126, v126
	s_nop 0
	v_mul_f32_e32 v126, v129, v126
	v_mul_f32_e32 v125, v126, v125
	v_mul_f32_e32 v126, 0xbfb8aa3b, v118
	v_exp_f32_e32 v126, v126
	s_nop 0
	v_add_f32_e32 v126, 1.0, v126
	v_rcp_f32_e32 v126, v126
	s_nop 0
	v_mul_f32_e32 v118, v118, v126
	v_mul_f32_e32 v118, v118, v114
	v_mul_f32_e32 v114, 0xbfb8aa3b, v119
	v_exp_f32_e32 v114, v114
	s_nop 0
	v_add_f32_e32 v114, 1.0, v114
	v_rcp_f32_e32 v114, v114
	s_nop 0
	v_mul_f32_e32 v114, v119, v114
	v_mul_f32_e32 v119, v114, v115
	v_mul_f32_e32 v114, 0xbfb8aa3b, v120
	v_exp_f32_e32 v114, v114
	s_nop 0
	v_add_f32_e32 v114, 1.0, v114
	v_rcp_f32_e32 v114, v114
	s_nop 0
	v_mul_f32_e32 v114, v120, v114
	v_mul_f32_e32 v126, v114, v116
	v_mul_f32_e32 v114, 0xbfb8aa3b, v121
	v_exp_f32_e32 v114, v114
	v_cvt_pk_bf16_f32 v116, v122, v123
	s_nop 0
	v_add_f32_e32 v114, 1.0, v114
	v_rcp_f32_e32 v114, v114
	s_nop 0
	v_mul_f32_e32 v114, v121, v114
	v_mul_f32_e32 v127, v114, v117
	v_lshlrev_b64 v[114:115], 1, v[140:141]
	v_lshl_add_u64 v[120:121], v[142:143], 0, v[114:115]
	v_cvt_pk_bf16_f32 v117, v124, v125
	v_cvt_pk_bf16_f32 v118, v118, v119
	v_cvt_pk_bf16_f32 v119, v126, v127
	global_store_dwordx4 v[120:121], v[116:119], off
	s_nop 1
	v_mul_f32_e32 v118, 0xbfb8aa3b, v110
	v_exp_f32_e32 v118, v118
	v_or_b32_e32 v116, 16, v139
	v_mad_i64_i32 v[116:117], s[6:7], v116, s74, v[134:135]
	v_add_f32_e32 v118, 1.0, v118
	v_rcp_f32_e32 v118, v118
	s_nop 0
	v_mul_f32_e32 v110, v110, v118
	v_mul_f32_e32 v106, v110, v106
	v_mul_f32_e32 v110, 0xbfb8aa3b, v111
	v_exp_f32_e32 v110, v110
	s_nop 0
	v_add_f32_e32 v110, 1.0, v110
	v_rcp_f32_e32 v110, v110
	s_nop 0
	v_mul_f32_e32 v110, v111, v110
	v_mul_f32_e32 v107, v110, v107
	v_mul_f32_e32 v110, 0xbfb8aa3b, v112
	v_exp_f32_e32 v110, v110
	s_nop 0
	v_add_f32_e32 v110, 1.0, v110
	v_rcp_f32_e32 v110, v110
	s_nop 0
	v_mul_f32_e32 v110, v112, v110
	v_mul_f32_e32 v108, v110, v108
	v_mul_f32_e32 v110, 0xbfb8aa3b, v113
	v_exp_f32_e32 v110, v110
	s_nop 0
	v_add_f32_e32 v110, 1.0, v110
	v_rcp_f32_e32 v110, v110
	s_nop 0
	v_mul_f32_e32 v110, v113, v110
	v_mul_f32_e32 v109, v110, v109
	v_mul_f32_e32 v110, 0xbfb8aa3b, v102
	v_exp_f32_e32 v110, v110
	s_nop 0
	v_add_f32_e32 v110, 1.0, v110
	v_rcp_f32_e32 v110, v110
	s_nop 0
	v_mul_f32_e32 v102, v102, v110
	v_mul_f32_e32 v110, v102, v98
	v_mul_f32_e32 v98, 0xbfb8aa3b, v103
	v_exp_f32_e32 v98, v98
	s_nop 0
	v_add_f32_e32 v98, 1.0, v98
	v_rcp_f32_e32 v98, v98
	s_nop 0
	v_mul_f32_e32 v98, v103, v98
	v_mul_f32_e32 v111, v98, v99
	v_mul_f32_e32 v98, 0xbfb8aa3b, v104
	v_exp_f32_e32 v98, v98
	v_lshl_add_u64 v[102:103], v[116:117], 0, v[114:115]
	v_add_f32_e32 v98, 1.0, v98
	v_rcp_f32_e32 v98, v98
	s_nop 0
	v_mul_f32_e32 v98, v104, v98
	v_mul_f32_e32 v104, v98, v100
	v_mul_f32_e32 v98, 0xbfb8aa3b, v105
	v_exp_f32_e32 v98, v98
	s_nop 0
	v_add_f32_e32 v98, 1.0, v98
	v_rcp_f32_e32 v98, v98
	s_nop 0
	v_mul_f32_e32 v98, v105, v98
	v_mul_f32_e32 v101, v98, v101
	v_cvt_pk_bf16_f32 v98, v106, v107
	v_cvt_pk_bf16_f32 v99, v108, v109
	v_cvt_pk_bf16_f32 v100, v110, v111
	v_cvt_pk_bf16_f32 v101, v104, v101
	global_store_dwordx4 v[102:103], v[98:101], off
	s_nop 1
	v_mul_f32_e32 v100, 0xbfb8aa3b, v94
	v_exp_f32_e32 v100, v100
	v_or_b32_e32 v98, 32, v139
	v_mad_i64_i32 v[98:99], s[6:7], v98, s74, v[134:135]
	v_add_f32_e32 v100, 1.0, v100
	v_rcp_f32_e32 v100, v100
	s_nop 0
	v_mul_f32_e32 v94, v94, v100
	v_mul_f32_e32 v90, v94, v90
	v_mul_f32_e32 v94, 0xbfb8aa3b, v95
	v_exp_f32_e32 v94, v94
	s_nop 0
	v_add_f32_e32 v94, 1.0, v94
	v_rcp_f32_e32 v94, v94
	s_nop 0
	v_mul_f32_e32 v94, v95, v94
	v_mul_f32_e32 v91, v94, v91
	v_mul_f32_e32 v94, 0xbfb8aa3b, v96
	v_exp_f32_e32 v94, v94
	s_nop 0
	v_add_f32_e32 v94, 1.0, v94
	v_rcp_f32_e32 v94, v94
	s_nop 0
	v_mul_f32_e32 v94, v96, v94
	v_mul_f32_e32 v92, v94, v92
	v_mul_f32_e32 v94, 0xbfb8aa3b, v97
	v_exp_f32_e32 v94, v94
	s_nop 0
	v_add_f32_e32 v94, 1.0, v94
	v_rcp_f32_e32 v94, v94
	s_nop 0
	v_mul_f32_e32 v94, v97, v94
	v_mul_f32_e32 v93, v94, v93
	v_mul_f32_e32 v94, 0xbfb8aa3b, v86
	v_exp_f32_e32 v94, v94
	s_nop 0
	v_add_f32_e32 v94, 1.0, v94
	v_rcp_f32_e32 v94, v94
	s_nop 0
	v_mul_f32_e32 v86, v86, v94
	v_mul_f32_e32 v94, v86, v82
	v_mul_f32_e32 v82, 0xbfb8aa3b, v87
	v_exp_f32_e32 v82, v82
	s_nop 0
	v_add_f32_e32 v82, 1.0, v82
	v_rcp_f32_e32 v82, v82
	s_nop 0
	v_mul_f32_e32 v82, v87, v82
	v_mul_f32_e32 v95, v82, v83
	v_mul_f32_e32 v82, 0xbfb8aa3b, v88
	v_exp_f32_e32 v82, v82
	v_lshl_add_u64 v[86:87], v[98:99], 0, v[114:115]
	v_add_f32_e32 v82, 1.0, v82
	v_rcp_f32_e32 v82, v82
	s_nop 0
	v_mul_f32_e32 v82, v88, v82
	v_mul_f32_e32 v88, v82, v84
	v_mul_f32_e32 v82, 0xbfb8aa3b, v89
	v_exp_f32_e32 v82, v82
	s_nop 0
	v_add_f32_e32 v82, 1.0, v82
	v_rcp_f32_e32 v82, v82
	s_nop 0
	v_mul_f32_e32 v82, v89, v82
	v_mul_f32_e32 v85, v82, v85
	v_cvt_pk_bf16_f32 v82, v90, v91
	v_cvt_pk_bf16_f32 v83, v92, v93
	v_cvt_pk_bf16_f32 v84, v94, v95
	v_cvt_pk_bf16_f32 v85, v88, v85
	global_store_dwordx4 v[86:87], v[82:85], off
	s_nop 1
	v_mul_f32_e32 v84, 0xbfb8aa3b, v78
	v_exp_f32_e32 v84, v84
	v_or_b32_e32 v82, 48, v139
	v_mad_i64_i32 v[82:83], s[6:7], v82, s74, v[134:135]
	v_add_f32_e32 v84, 1.0, v84
	v_rcp_f32_e32 v84, v84
	s_nop 0
	v_mul_f32_e32 v78, v78, v84
	v_mul_f32_e32 v74, v78, v74
	v_mul_f32_e32 v78, 0xbfb8aa3b, v79
	v_exp_f32_e32 v78, v78
	s_nop 0
	v_add_f32_e32 v78, 1.0, v78
	v_rcp_f32_e32 v78, v78
	s_nop 0
	v_mul_f32_e32 v78, v79, v78
	v_mul_f32_e32 v75, v78, v75
	v_mul_f32_e32 v78, 0xbfb8aa3b, v80
	v_exp_f32_e32 v78, v78
	s_nop 0
	v_add_f32_e32 v78, 1.0, v78
	v_rcp_f32_e32 v78, v78
	s_nop 0
	v_mul_f32_e32 v78, v80, v78
	v_mul_f32_e32 v76, v78, v76
	v_mul_f32_e32 v78, 0xbfb8aa3b, v81
	v_exp_f32_e32 v78, v78
	s_nop 0
	v_add_f32_e32 v78, 1.0, v78
	v_rcp_f32_e32 v78, v78
	s_nop 0
	v_mul_f32_e32 v78, v81, v78
	v_mul_f32_e32 v77, v78, v77
	v_mul_f32_e32 v78, 0xbfb8aa3b, v70
	v_exp_f32_e32 v78, v78
	s_nop 0
	v_add_f32_e32 v78, 1.0, v78
	v_rcp_f32_e32 v78, v78
	s_nop 0
	v_mul_f32_e32 v70, v70, v78
	v_mul_f32_e32 v78, v70, v66
	v_mul_f32_e32 v66, 0xbfb8aa3b, v71
	v_exp_f32_e32 v66, v66
	s_nop 0
	v_add_f32_e32 v66, 1.0, v66
	v_rcp_f32_e32 v66, v66
	s_nop 0
	v_mul_f32_e32 v66, v71, v66
	v_mul_f32_e32 v79, v66, v67
	v_mul_f32_e32 v66, 0xbfb8aa3b, v72
	v_exp_f32_e32 v66, v66
	v_lshl_add_u64 v[70:71], v[82:83], 0, v[114:115]
	v_add_f32_e32 v66, 1.0, v66
	v_rcp_f32_e32 v66, v66
	s_nop 0
	v_mul_f32_e32 v66, v72, v66
	v_mul_f32_e32 v72, v66, v68
	v_mul_f32_e32 v66, 0xbfb8aa3b, v73
	v_exp_f32_e32 v66, v66
	s_nop 0
	v_add_f32_e32 v66, 1.0, v66
	v_rcp_f32_e32 v66, v66
	s_nop 0
	v_mul_f32_e32 v66, v73, v66
	v_mul_f32_e32 v69, v66, v69
	v_cvt_pk_bf16_f32 v66, v74, v75
	v_cvt_pk_bf16_f32 v67, v76, v77
	v_cvt_pk_bf16_f32 v68, v78, v79
	v_cvt_pk_bf16_f32 v69, v72, v69
	global_store_dwordx4 v[70:71], v[66:69], off
	s_nop 1
	v_mul_f32_e32 v68, 0xbfb8aa3b, v62
	v_exp_f32_e32 v68, v68
	v_add_u32_e32 v66, 0x80, v139
	v_mad_i64_i32 v[66:67], s[6:7], v66, s74, v[134:135]
	v_add_f32_e32 v68, 1.0, v68
	v_rcp_f32_e32 v68, v68
	s_nop 0
	v_mul_f32_e32 v62, v62, v68
	v_mul_f32_e32 v58, v62, v58
	v_mul_f32_e32 v62, 0xbfb8aa3b, v63
	v_exp_f32_e32 v62, v62
	s_nop 0
	v_add_f32_e32 v62, 1.0, v62
	v_rcp_f32_e32 v62, v62
	s_nop 0
	v_mul_f32_e32 v62, v63, v62
	v_mul_f32_e32 v59, v62, v59
	v_mul_f32_e32 v62, 0xbfb8aa3b, v64
	v_exp_f32_e32 v62, v62
	s_nop 0
	v_add_f32_e32 v62, 1.0, v62
	v_rcp_f32_e32 v62, v62
	s_nop 0
	v_mul_f32_e32 v62, v64, v62
	v_mul_f32_e32 v60, v62, v60
	v_mul_f32_e32 v62, 0xbfb8aa3b, v65
	v_exp_f32_e32 v62, v62
	s_nop 0
	v_add_f32_e32 v62, 1.0, v62
	v_rcp_f32_e32 v62, v62
	s_nop 0
	v_mul_f32_e32 v62, v65, v62
	v_mul_f32_e32 v61, v62, v61
	v_mul_f32_e32 v62, 0xbfb8aa3b, v54
	v_exp_f32_e32 v62, v62
	s_nop 0
	v_add_f32_e32 v62, 1.0, v62
	v_rcp_f32_e32 v62, v62
	s_nop 0
	v_mul_f32_e32 v54, v54, v62
	v_mul_f32_e32 v62, v54, v50
	v_mul_f32_e32 v50, 0xbfb8aa3b, v55
	v_exp_f32_e32 v50, v50
	s_nop 0
	v_add_f32_e32 v50, 1.0, v50
	v_rcp_f32_e32 v50, v50
	s_nop 0
	v_mul_f32_e32 v50, v55, v50
	v_mul_f32_e32 v63, v50, v51
	v_mul_f32_e32 v50, 0xbfb8aa3b, v56
	v_exp_f32_e32 v50, v50
	v_lshl_add_u64 v[54:55], v[66:67], 0, v[114:115]
	v_add_f32_e32 v50, 1.0, v50
	v_rcp_f32_e32 v50, v50
	s_nop 0
	v_mul_f32_e32 v50, v56, v50
	v_mul_f32_e32 v56, v50, v52
	v_mul_f32_e32 v50, 0xbfb8aa3b, v57
	v_exp_f32_e32 v50, v50
	s_nop 0
	v_add_f32_e32 v50, 1.0, v50
	v_rcp_f32_e32 v50, v50
	s_nop 0
	v_mul_f32_e32 v50, v57, v50
	v_mul_f32_e32 v53, v50, v53
	v_cvt_pk_bf16_f32 v50, v58, v59
	v_cvt_pk_bf16_f32 v51, v60, v61
	v_cvt_pk_bf16_f32 v52, v62, v63
	v_cvt_pk_bf16_f32 v53, v56, v53
	global_store_dwordx4 v[54:55], v[50:53], off
	s_nop 1
	v_mul_f32_e32 v52, 0xbfb8aa3b, v46
	v_exp_f32_e32 v52, v52
	v_add_u32_e32 v50, 0x90, v139
	v_mad_i64_i32 v[50:51], s[6:7], v50, s74, v[134:135]
	v_add_f32_e32 v52, 1.0, v52
	v_rcp_f32_e32 v52, v52
	s_nop 0
	v_mul_f32_e32 v46, v46, v52
	v_mul_f32_e32 v42, v46, v42
	v_mul_f32_e32 v46, 0xbfb8aa3b, v47
	v_exp_f32_e32 v46, v46
	s_nop 0
	v_add_f32_e32 v46, 1.0, v46
	v_rcp_f32_e32 v46, v46
	s_nop 0
	v_mul_f32_e32 v46, v47, v46
	v_mul_f32_e32 v43, v46, v43
	v_mul_f32_e32 v46, 0xbfb8aa3b, v48
	v_exp_f32_e32 v46, v46
	s_nop 0
	v_add_f32_e32 v46, 1.0, v46
	v_rcp_f32_e32 v46, v46
	s_nop 0
	v_mul_f32_e32 v46, v48, v46
	v_mul_f32_e32 v44, v46, v44
	v_mul_f32_e32 v46, 0xbfb8aa3b, v49
	v_exp_f32_e32 v46, v46
	s_nop 0
	v_add_f32_e32 v46, 1.0, v46
	v_rcp_f32_e32 v46, v46
	s_nop 0
	v_mul_f32_e32 v46, v49, v46
	v_mul_f32_e32 v45, v46, v45
	v_mul_f32_e32 v46, 0xbfb8aa3b, v38
	v_exp_f32_e32 v46, v46
	s_nop 0
	v_add_f32_e32 v46, 1.0, v46
	v_rcp_f32_e32 v46, v46
	s_nop 0
	v_mul_f32_e32 v38, v38, v46
	v_mul_f32_e32 v46, v38, v34
	v_mul_f32_e32 v34, 0xbfb8aa3b, v39
	v_exp_f32_e32 v34, v34
	s_nop 0
	v_add_f32_e32 v34, 1.0, v34
	v_rcp_f32_e32 v34, v34
	s_nop 0
	v_mul_f32_e32 v34, v39, v34
	v_mul_f32_e32 v47, v34, v35
	v_mul_f32_e32 v34, 0xbfb8aa3b, v40
	v_exp_f32_e32 v34, v34
	v_lshl_add_u64 v[38:39], v[50:51], 0, v[114:115]
	v_add_f32_e32 v34, 1.0, v34
	v_rcp_f32_e32 v34, v34
	s_nop 0
	v_mul_f32_e32 v34, v40, v34
	v_mul_f32_e32 v40, v34, v36
	v_mul_f32_e32 v34, 0xbfb8aa3b, v41
	v_exp_f32_e32 v34, v34
	s_nop 0
	v_add_f32_e32 v34, 1.0, v34
	v_rcp_f32_e32 v34, v34
	s_nop 0
	v_mul_f32_e32 v34, v41, v34
	v_mul_f32_e32 v37, v34, v37
	v_cvt_pk_bf16_f32 v34, v42, v43
	v_cvt_pk_bf16_f32 v35, v44, v45
	v_cvt_pk_bf16_f32 v36, v46, v47
	v_cvt_pk_bf16_f32 v37, v40, v37
	global_store_dwordx4 v[38:39], v[34:37], off
	s_nop 1
	v_mul_f32_e32 v36, 0xbfb8aa3b, v30
	v_exp_f32_e32 v36, v36
	v_add_u32_e32 v34, 0xa0, v139
	v_mad_i64_i32 v[34:35], s[6:7], v34, s74, v[134:135]
	v_add_f32_e32 v36, 1.0, v36
	v_rcp_f32_e32 v36, v36
	s_nop 0
	v_mul_f32_e32 v30, v30, v36
	v_mul_f32_e32 v26, v30, v26
	v_mul_f32_e32 v30, 0xbfb8aa3b, v31
	v_exp_f32_e32 v30, v30
	s_nop 0
	v_add_f32_e32 v30, 1.0, v30
	v_rcp_f32_e32 v30, v30
	s_nop 0
	v_mul_f32_e32 v30, v31, v30
	v_mul_f32_e32 v27, v30, v27
	v_mul_f32_e32 v30, 0xbfb8aa3b, v32
	v_exp_f32_e32 v30, v30
	s_nop 0
	v_add_f32_e32 v30, 1.0, v30
	v_rcp_f32_e32 v30, v30
	s_nop 0
	v_mul_f32_e32 v30, v32, v30
	v_mul_f32_e32 v28, v30, v28
	v_mul_f32_e32 v30, 0xbfb8aa3b, v33
	v_exp_f32_e32 v30, v30
	s_nop 0
	v_add_f32_e32 v30, 1.0, v30
	v_rcp_f32_e32 v30, v30
	s_nop 0
	v_mul_f32_e32 v30, v33, v30
	v_mul_f32_e32 v29, v30, v29
	v_mul_f32_e32 v30, 0xbfb8aa3b, v22
	v_exp_f32_e32 v30, v30
	s_nop 0
	v_add_f32_e32 v30, 1.0, v30
	v_rcp_f32_e32 v30, v30
	s_nop 0
	v_mul_f32_e32 v22, v22, v30
	v_mul_f32_e32 v30, v22, v18
	v_mul_f32_e32 v18, 0xbfb8aa3b, v23
	v_exp_f32_e32 v18, v18
	s_nop 0
	v_add_f32_e32 v18, 1.0, v18
	v_rcp_f32_e32 v18, v18
	s_nop 0
	v_mul_f32_e32 v18, v23, v18
	v_mul_f32_e32 v31, v18, v19
	v_mul_f32_e32 v18, 0xbfb8aa3b, v24
	v_exp_f32_e32 v18, v18
	v_lshl_add_u64 v[22:23], v[34:35], 0, v[114:115]
	v_add_f32_e32 v18, 1.0, v18
	v_rcp_f32_e32 v18, v18
	s_nop 0
	v_mul_f32_e32 v18, v24, v18
	v_mul_f32_e32 v24, v18, v20
	v_mul_f32_e32 v18, 0xbfb8aa3b, v25
	v_exp_f32_e32 v18, v18
	s_nop 0
	v_add_f32_e32 v18, 1.0, v18
	v_rcp_f32_e32 v18, v18
	s_nop 0
	v_mul_f32_e32 v18, v25, v18
	v_mul_f32_e32 v21, v18, v21
	v_cvt_pk_bf16_f32 v18, v26, v27
	v_cvt_pk_bf16_f32 v19, v28, v29
	v_cvt_pk_bf16_f32 v20, v30, v31
	v_cvt_pk_bf16_f32 v21, v24, v21
	global_store_dwordx4 v[22:23], v[18:21], off
	s_nop 1
	v_mul_f32_e32 v20, 0xbfb8aa3b, v14
	v_exp_f32_e32 v20, v20
	v_add_u32_e32 v18, 0xb0, v139
	v_mad_i64_i32 v[18:19], s[6:7], v18, s74, v[134:135]
	v_add_f32_e32 v20, 1.0, v20
	v_rcp_f32_e32 v20, v20
	s_mov_b64 s[6:7], s[42:43]
	v_mul_f32_e32 v14, v14, v20
	v_mul_f32_e32 v10, v14, v10
	v_mul_f32_e32 v14, 0xbfb8aa3b, v15
	v_exp_f32_e32 v14, v14
	s_nop 0
	v_add_f32_e32 v14, 1.0, v14
	v_rcp_f32_e32 v14, v14
	s_nop 0
	v_mul_f32_e32 v14, v15, v14
	v_mul_f32_e32 v11, v14, v11
	v_mul_f32_e32 v14, 0xbfb8aa3b, v16
	v_exp_f32_e32 v14, v14
	s_nop 0
	v_add_f32_e32 v14, 1.0, v14
	v_rcp_f32_e32 v14, v14
	s_nop 0
	v_mul_f32_e32 v14, v16, v14
	v_mul_f32_e32 v12, v14, v12
	v_mul_f32_e32 v14, 0xbfb8aa3b, v17
	v_exp_f32_e32 v14, v14
	s_nop 0
	v_add_f32_e32 v14, 1.0, v14
	v_rcp_f32_e32 v14, v14
	s_nop 0
	v_mul_f32_e32 v14, v17, v14
	v_mul_f32_e32 v13, v14, v13
	v_mul_f32_e32 v14, 0xbfb8aa3b, v6
	v_exp_f32_e32 v14, v14
	s_nop 0
	v_add_f32_e32 v14, 1.0, v14
	v_rcp_f32_e32 v14, v14
	s_nop 0
	v_mul_f32_e32 v6, v6, v14
	v_mul_f32_e32 v14, v6, v2
	v_mul_f32_e32 v2, 0xbfb8aa3b, v7
	v_exp_f32_e32 v2, v2
	s_nop 0
	v_add_f32_e32 v2, 1.0, v2
	v_rcp_f32_e32 v2, v2
	s_nop 0
	v_mul_f32_e32 v2, v7, v2
	v_mul_f32_e32 v15, v2, v3
	v_mul_f32_e32 v2, 0xbfb8aa3b, v8
	v_exp_f32_e32 v2, v2
	v_lshl_add_u64 v[6:7], v[18:19], 0, v[114:115]
	v_add_f32_e32 v2, 1.0, v2
	v_rcp_f32_e32 v2, v2
	s_nop 0
	v_mul_f32_e32 v2, v8, v2
	v_mul_f32_e32 v8, v2, v4
	v_mul_f32_e32 v2, 0xbfb8aa3b, v9
	v_exp_f32_e32 v2, v2
	s_nop 0
	v_add_f32_e32 v2, 1.0, v2
	v_rcp_f32_e32 v2, v2
	s_nop 0
	v_mul_f32_e32 v2, v9, v2
	v_mul_f32_e32 v5, v2, v5
	v_cvt_pk_bf16_f32 v2, v10, v11
	v_cvt_pk_bf16_f32 v3, v12, v13
	v_cvt_pk_bf16_f32 v4, v14, v15
	v_cvt_pk_bf16_f32 v5, v8, v5
	global_store_dwordx4 v[6:7], v[2:5], off
	s_cbranch_vccz .LBB0_500
	s_waitcnt vmcnt(0)
	v_readlane_b32 s0, v255, 8
	v_readlane_b32 s62, v255, 10
	v_readlane_b32 s84, v255, 12
	s_cmpk_gt_u32 s22, 0xff
	v_readlane_b32 s1, v255, 9
	s_mov_b64 s[58:59], s[92:93]
	v_readlane_b32 s63, v255, 11
	v_readlane_b32 s85, v255, 13
	s_cbranch_scc1 .LBB0_507
	s_barrier

.LBB0_578:
	s_add_u32 s7, s40, 0xfff80080
	s_addc_u32 s11, s41, -1
	s_add_i32 s49, 0, 0x10000
	v_add_u32_e32 v142, s49, v158
	ds_read_b128 v[130:133], v142
	ds_read_b128 v[134:137], v142 offset:1024
	ds_read_b128 v[138:141], v142 offset:2048
	ds_read_b128 v[142:145], v142 offset:3072
	s_cmp_eq_u32 s6, 4
	s_cselect_b32 s95, s51, s11
	s_cselect_b32 s94, s50, s7
	s_cselect_b32 s97, s53, s9
	s_cselect_b32 s96, s52, s8
	v_lshl_add_u64 v[156:157], s[40:41], 0, v[150:151]
	s_add_i32 m0, s55, 0xc000
	ds_read_b128 v[152:155], v159
	ds_read_b128 v[160:163], v159 offset:1024
	ds_read_b128 v[164:167], v159 offset:2048
	ds_read_b128 v[168:171], v159 offset:3072
	ds_read_b128 v[172:175], v159 offset:4096
	ds_read_b128 v[176:179], v159 offset:5120
	ds_read_b128 v[180:183], v159 offset:6144
	ds_read_b128 v[184:187], v159 offset:7168
	global_load_lds_dwordx4 v[156:157], off
	v_lshl_add_u64 v[156:157], v[156:157], 0, s[60:61]
	s_add_i32 m0, s55, 0xe000
	s_nop 0
	global_load_lds_dwordx4 v[156:157], off
	s_waitcnt lgkmcnt(8)
	s_setprio 1
	s_barrier
	s_waitcnt lgkmcnt(0)
	v_mfma_f32_16x16x32_bf16 v[126:129], v[130:133], v[152:155], v[126:129]
	v_mfma_f32_16x16x32_bf16 v[122:125], v[138:141], v[152:155], v[122:125]
	v_mfma_f32_16x16x32_bf16 v[114:117], v[130:133], v[164:167], v[114:117]
	v_mfma_f32_16x16x32_bf16 v[110:113], v[138:141], v[164:167], v[110:113]
	v_mfma_f32_16x16x32_bf16 v[102:105], v[130:133], v[172:175], v[102:105]
	v_mfma_f32_16x16x32_bf16 v[94:97], v[138:141], v[172:175], v[94:97]
	v_mfma_f32_16x16x32_bf16 v[86:89], v[130:133], v[180:183], v[86:89]
	v_mfma_f32_16x16x32_bf16 v[78:81], v[138:141], v[180:183], v[78:81]
	v_mfma_f32_16x16x32_bf16 v[126:129], v[134:137], v[160:163], v[126:129]
	v_mfma_f32_16x16x32_bf16 v[122:125], v[142:145], v[160:163], v[122:125]
	v_mfma_f32_16x16x32_bf16 v[114:117], v[134:137], v[168:171], v[114:117]
	v_mfma_f32_16x16x32_bf16 v[110:113], v[142:145], v[168:171], v[110:113]
	v_mfma_f32_16x16x32_bf16 v[102:105], v[134:137], v[176:179], v[102:105]
	v_mfma_f32_16x16x32_bf16 v[94:97], v[142:145], v[176:179], v[94:97]
	v_mfma_f32_16x16x32_bf16 v[86:89], v[134:137], v[184:187], v[86:89]
	v_mfma_f32_16x16x32_bf16 v[78:81], v[142:145], v[184:187], v[78:81]
	s_barrier
	s_setprio 0
	s_add_i32 s7, 0, 0x14000
	v_add_u32_e32 v156, s7, v158
	s_add_i32 s11, s49, s63
	ds_read_b128 v[188:191], v156
	ds_read_b128 v[192:195], v156 offset:1024
	ds_read_b128 v[196:199], v156 offset:2048
	ds_read_b128 v[200:203], v156 offset:3072
	v_lshl_add_u64 v[156:157], s[96:97], 0, v[0:1]
	s_mov_b32 m0, s11
	v_lshl_add_u64 v[204:205], v[156:157], 0, s[68:69]
	global_load_lds_dwordx4 v[156:157], off
	s_add_i32 m0, s11, 0x2000
	s_nop 0
	global_load_lds_dwordx4 v[204:205], off
	s_setprio 1
	s_barrier
	s_waitcnt lgkmcnt(0)
	v_mfma_f32_16x16x32_bf16 v[118:121], v[188:191], v[152:155], v[118:121]
	v_mfma_f32_16x16x32_bf16 v[106:109], v[196:199], v[152:155], v[106:109]
	v_mfma_f32_16x16x32_bf16 v[98:101], v[188:191], v[164:167], v[98:101]
	v_mfma_f32_16x16x32_bf16 v[90:93], v[196:199], v[164:167], v[90:93]
	v_mfma_f32_16x16x32_bf16 v[82:85], v[188:191], v[172:175], v[82:85]
	v_mfma_f32_16x16x32_bf16 v[74:77], v[196:199], v[172:175], v[74:77]
	v_mfma_f32_16x16x32_bf16 v[70:73], v[188:191], v[180:183], v[70:73]
	v_mfma_f32_16x16x32_bf16 v[66:69], v[196:199], v[180:183], v[66:69]
	v_mfma_f32_16x16x32_bf16 v[118:121], v[192:195], v[160:163], v[118:121]
	v_mfma_f32_16x16x32_bf16 v[106:109], v[200:203], v[160:163], v[106:109]
	v_mfma_f32_16x16x32_bf16 v[98:101], v[192:195], v[168:171], v[98:101]
	v_mfma_f32_16x16x32_bf16 v[90:93], v[200:203], v[168:171], v[90:93]
	v_mfma_f32_16x16x32_bf16 v[82:85], v[192:195], v[176:179], v[82:85]
	v_mfma_f32_16x16x32_bf16 v[74:77], v[200:203], v[176:179], v[74:77]
	v_mfma_f32_16x16x32_bf16 v[70:73], v[192:195], v[184:187], v[70:73]
	v_mfma_f32_16x16x32_bf16 v[66:69], v[200:203], v[184:187], v[66:69]
	s_barrier
	s_setprio 0
	s_mov_b32 m0, s55
	v_lshl_add_u64 v[204:205], s[94:95], 0, v[148:149]
	ds_read_b128 v[152:155], v159 offset:16384
	ds_read_b128 v[160:163], v159 offset:17408
	ds_read_b128 v[164:167], v159 offset:18432
	ds_read_b128 v[168:171], v159 offset:19456
	ds_read_b128 v[172:175], v159 offset:20480
	ds_read_b128 v[176:179], v159 offset:21504
	ds_read_b128 v[180:183], v159 offset:22528
	ds_read_b128 v[184:187], v159 offset:23552
	global_load_lds_dwordx4 v[204:205], off
	v_lshl_add_u64 v[206:207], v[204:205], 0, s[60:61]
	s_mov_b32 m0, s84
	s_nop 0
	global_load_lds_dwordx4 v[206:207], off
	s_setprio 1
	s_barrier
	s_waitcnt lgkmcnt(0)
	v_mfma_f32_16x16x32_bf16 v[62:65], v[130:133], v[152:155], v[62:65]
	v_mfma_f32_16x16x32_bf16 v[58:61], v[138:141], v[152:155], v[58:61]
	v_mfma_f32_16x16x32_bf16 v[54:57], v[130:133], v[164:167], v[54:57]
	v_mfma_f32_16x16x32_bf16 v[46:49], v[138:141], v[164:167], v[46:49]
	v_mfma_f32_16x16x32_bf16 v[38:41], v[130:133], v[172:175], v[38:41]
	v_mfma_f32_16x16x32_bf16 v[30:33], v[138:141], v[172:175], v[30:33]
	v_mfma_f32_16x16x32_bf16 v[22:25], v[130:133], v[180:183], v[22:25]
	v_mfma_f32_16x16x32_bf16 v[14:17], v[138:141], v[180:183], v[14:17]
	v_mfma_f32_16x16x32_bf16 v[62:65], v[134:137], v[160:163], v[62:65]
	v_mfma_f32_16x16x32_bf16 v[58:61], v[142:145], v[160:163], v[58:61]
	v_mfma_f32_16x16x32_bf16 v[54:57], v[134:137], v[168:171], v[54:57]
	v_mfma_f32_16x16x32_bf16 v[46:49], v[142:145], v[168:171], v[46:49]
	v_mfma_f32_16x16x32_bf16 v[38:41], v[134:137], v[176:179], v[38:41]
	v_mfma_f32_16x16x32_bf16 v[30:33], v[142:145], v[176:179], v[30:33]
	v_mfma_f32_16x16x32_bf16 v[22:25], v[134:137], v[184:187], v[22:25]
	v_mfma_f32_16x16x32_bf16 v[14:17], v[142:145], v[184:187], v[14:17]
	s_barrier
	s_setprio 0
	s_add_i32 s7, s7, s63
	v_lshl_add_u64 v[130:131], v[156:157], 0, vcc
	s_mov_b32 m0, s7
	s_nop 0
	global_load_lds_dwordx4 v[130:131], off
	v_lshl_add_u64 v[130:131], v[156:157], 0, s[78:79]
	s_add_i32 m0, s7, 0x2000
	s_nop 0
	global_load_lds_dwordx4 v[130:131], off
	s_waitcnt vmcnt(6)
	s_setprio 1
	s_barrier
	v_mfma_f32_16x16x32_bf16 v[50:53], v[188:191], v[152:155], v[50:53]
	v_mfma_f32_16x16x32_bf16 v[42:45], v[196:199], v[152:155], v[42:45]
	v_mfma_f32_16x16x32_bf16 v[34:37], v[188:191], v[164:167], v[34:37]
	v_mfma_f32_16x16x32_bf16 v[26:29], v[196:199], v[164:167], v[26:29]
	v_mfma_f32_16x16x32_bf16 v[18:21], v[188:191], v[172:175], v[18:21]
	v_mfma_f32_16x16x32_bf16 v[10:13], v[196:199], v[172:175], v[10:13]
	v_mfma_f32_16x16x32_bf16 v[6:9], v[188:191], v[180:183], v[6:9]
	v_mfma_f32_16x16x32_bf16 v[2:5], v[196:199], v[180:183], v[2:5]
	v_mfma_f32_16x16x32_bf16 v[50:53], v[192:195], v[160:163], v[50:53]
	v_mfma_f32_16x16x32_bf16 v[42:45], v[200:203], v[160:163], v[42:45]
	v_mfma_f32_16x16x32_bf16 v[34:37], v[192:195], v[168:171], v[34:37]
	v_mfma_f32_16x16x32_bf16 v[26:29], v[200:203], v[168:171], v[26:29]
	v_mfma_f32_16x16x32_bf16 v[18:21], v[192:195], v[176:179], v[18:21]
	v_mfma_f32_16x16x32_bf16 v[10:13], v[200:203], v[176:179], v[10:13]
	v_mfma_f32_16x16x32_bf16 v[6:9], v[192:195], v[184:187], v[6:9]
	v_mfma_f32_16x16x32_bf16 v[2:5], v[200:203], v[184:187], v[2:5]
	s_barrier
	s_setprio 0
	s_add_i32 s7, 0, 0x18000
	v_add_u32_e32 v142, s7, v158
	ds_read_b128 v[130:133], v142
	ds_read_b128 v[134:137], v142 offset:1024
	ds_read_b128 v[138:141], v142 offset:2048
	ds_read_b128 v[142:145], v142 offset:3072
	s_mov_b32 m0, s85
	v_lshl_add_u64 v[188:189], v[204:205], 0, s[20:21]
	ds_read_b128 v[152:155], v159 offset:32768
	ds_read_b128 v[160:163], v159 offset:33792
	ds_read_b128 v[164:167], v159 offset:34816
	ds_read_b128 v[168:171], v159 offset:35840
	ds_read_b128 v[172:175], v159 offset:36864
	ds_read_b128 v[176:179], v159 offset:37888
	ds_read_b128 v[180:183], v159 offset:38912
	ds_read_b128 v[184:187], v159 offset:39936
	global_load_lds_dwordx4 v[188:189], off
	v_lshl_add_u64 v[188:189], v[204:205], 0, s[64:65]
	s_mov_b32 m0, s86
	s_nop 0
	global_load_lds_dwordx4 v[188:189], off
	s_waitcnt lgkmcnt(8)
	s_setprio 1
	s_barrier
	s_waitcnt lgkmcnt(0)
	v_mfma_f32_16x16x32_bf16 v[126:129], v[130:133], v[152:155], v[126:129]
	v_mfma_f32_16x16x32_bf16 v[122:125], v[138:141], v[152:155], v[122:125]
	v_mfma_f32_16x16x32_bf16 v[114:117], v[130:133], v[164:167], v[114:117]
	v_mfma_f32_16x16x32_bf16 v[110:113], v[138:141], v[164:167], v[110:113]
	v_mfma_f32_16x16x32_bf16 v[102:105], v[130:133], v[172:175], v[102:105]
	v_mfma_f32_16x16x32_bf16 v[94:97], v[138:141], v[172:175], v[94:97]
	v_mfma_f32_16x16x32_bf16 v[86:89], v[130:133], v[180:183], v[86:89]
	v_mfma_f32_16x16x32_bf16 v[78:81], v[138:141], v[180:183], v[78:81]
	v_mfma_f32_16x16x32_bf16 v[126:129], v[134:137], v[160:163], v[126:129]
	v_mfma_f32_16x16x32_bf16 v[122:125], v[142:145], v[160:163], v[122:125]
	v_mfma_f32_16x16x32_bf16 v[114:117], v[134:137], v[168:171], v[114:117]
	v_mfma_f32_16x16x32_bf16 v[110:113], v[142:145], v[168:171], v[110:113]
	v_mfma_f32_16x16x32_bf16 v[102:105], v[134:137], v[176:179], v[102:105]
	v_mfma_f32_16x16x32_bf16 v[94:97], v[142:145], v[176:179], v[94:97]
	v_mfma_f32_16x16x32_bf16 v[86:89], v[134:137], v[184:187], v[86:89]
	v_mfma_f32_16x16x32_bf16 v[78:81], v[142:145], v[184:187], v[78:81]
	s_barrier
	s_setprio 0
	s_add_i32 s11, 0, 0x1c000
	s_add_i32 s7, s7, s63
	v_add_u32_e32 v200, s11, v158
	v_lshl_add_u64 v[206:207], v[156:157], 0, s[34:35]
	s_mov_b32 m0, s7
	ds_read_b128 v[188:191], v200
	ds_read_b128 v[192:195], v200 offset:1024
	ds_read_b128 v[196:199], v200 offset:2048
	ds_read_b128 v[200:203], v200 offset:3072
	global_load_lds_dwordx4 v[206:207], off
	v_lshl_add_u64 v[206:207], v[156:157], 0, s[38:39]
	s_add_i32 m0, s7, 0x2000
	s_nop 0
	global_load_lds_dwordx4 v[206:207], off
	s_setprio 1
	s_barrier
	s_waitcnt lgkmcnt(0)
	v_mfma_f32_16x16x32_bf16 v[118:121], v[188:191], v[152:155], v[118:121]
	v_mfma_f32_16x16x32_bf16 v[106:109], v[196:199], v[152:155], v[106:109]
	v_mfma_f32_16x16x32_bf16 v[98:101], v[188:191], v[164:167], v[98:101]
	v_mfma_f32_16x16x32_bf16 v[90:93], v[196:199], v[164:167], v[90:93]
	v_mfma_f32_16x16x32_bf16 v[82:85], v[188:191], v[172:175], v[82:85]
	v_mfma_f32_16x16x32_bf16 v[74:77], v[196:199], v[172:175], v[74:77]
	v_mfma_f32_16x16x32_bf16 v[70:73], v[188:191], v[180:183], v[70:73]
	v_mfma_f32_16x16x32_bf16 v[66:69], v[196:199], v[180:183], v[66:69]
	v_mfma_f32_16x16x32_bf16 v[118:121], v[192:195], v[160:163], v[118:121]
	v_mfma_f32_16x16x32_bf16 v[106:109], v[200:203], v[160:163], v[106:109]
	v_mfma_f32_16x16x32_bf16 v[98:101], v[192:195], v[168:171], v[98:101]
	v_mfma_f32_16x16x32_bf16 v[90:93], v[200:203], v[168:171], v[90:93]
	v_mfma_f32_16x16x32_bf16 v[82:85], v[192:195], v[176:179], v[82:85]
	v_mfma_f32_16x16x32_bf16 v[74:77], v[200:203], v[176:179], v[74:77]
	v_mfma_f32_16x16x32_bf16 v[70:73], v[192:195], v[184:187], v[70:73]
	v_mfma_f32_16x16x32_bf16 v[66:69], v[200:203], v[184:187], v[66:69]
	s_barrier
	s_setprio 0
	s_mov_b32 m0, s89
	v_lshl_add_u64 v[206:207], v[204:205], 0, s[34:35]
	ds_read_b128 v[152:155], v159 offset:49152
	ds_read_b128 v[160:163], v159 offset:50176
	ds_read_b128 v[164:167], v159 offset:51200
	ds_read_b128 v[168:171], v159 offset:52224
	ds_read_b128 v[172:175], v159 offset:53248
	ds_read_b128 v[176:179], v159 offset:54272
	ds_read_b128 v[180:183], v159 offset:55296
	ds_read_b128 v[184:187], v159 offset:56320
	global_load_lds_dwordx4 v[206:207], off
	v_lshl_add_u64 v[204:205], v[204:205], 0, s[66:67]
	s_mov_b32 m0, s90
	s_nop 0
	global_load_lds_dwordx4 v[204:205], off
	s_setprio 1
	s_barrier
	s_waitcnt lgkmcnt(0)
	v_mfma_f32_16x16x32_bf16 v[62:65], v[130:133], v[152:155], v[62:65]
	v_mfma_f32_16x16x32_bf16 v[58:61], v[138:141], v[152:155], v[58:61]
	v_mfma_f32_16x16x32_bf16 v[54:57], v[130:133], v[164:167], v[54:57]
	v_mfma_f32_16x16x32_bf16 v[46:49], v[138:141], v[164:167], v[46:49]
	v_mfma_f32_16x16x32_bf16 v[38:41], v[130:133], v[172:175], v[38:41]
	v_mfma_f32_16x16x32_bf16 v[30:33], v[138:141], v[172:175], v[30:33]
	v_mfma_f32_16x16x32_bf16 v[22:25], v[130:133], v[180:183], v[22:25]
	v_mfma_f32_16x16x32_bf16 v[14:17], v[138:141], v[180:183], v[14:17]
	v_mfma_f32_16x16x32_bf16 v[62:65], v[134:137], v[160:163], v[62:65]
	v_mfma_f32_16x16x32_bf16 v[58:61], v[142:145], v[160:163], v[58:61]
	v_mfma_f32_16x16x32_bf16 v[54:57], v[134:137], v[168:171], v[54:57]
	v_mfma_f32_16x16x32_bf16 v[46:49], v[142:145], v[168:171], v[46:49]
	v_mfma_f32_16x16x32_bf16 v[38:41], v[134:137], v[176:179], v[38:41]
	v_mfma_f32_16x16x32_bf16 v[30:33], v[142:145], v[176:179], v[30:33]
	v_mfma_f32_16x16x32_bf16 v[22:25], v[134:137], v[184:187], v[22:25]
	v_mfma_f32_16x16x32_bf16 v[14:17], v[142:145], v[184:187], v[14:17]
	s_barrier
	s_setprio 0
	s_add_i32 s7, s11, s63
	v_lshl_add_u64 v[130:131], v[156:157], 0, s[72:73]
	s_mov_b32 m0, s7
	s_nop 0
	global_load_lds_dwordx4 v[130:131], off
	v_lshl_add_u64 v[130:131], v[156:157], 0, s[56:57]
	s_add_i32 m0, s7, 0x2000
	s_nop 0
	global_load_lds_dwordx4 v[130:131], off
	s_waitcnt vmcnt(6)
	s_setprio 1
	s_barrier
	v_mfma_f32_16x16x32_bf16 v[50:53], v[188:191], v[152:155], v[50:53]
	v_mfma_f32_16x16x32_bf16 v[42:45], v[196:199], v[152:155], v[42:45]
	v_mfma_f32_16x16x32_bf16 v[34:37], v[188:191], v[164:167], v[34:37]
	v_mfma_f32_16x16x32_bf16 v[26:29], v[196:199], v[164:167], v[26:29]
	v_mfma_f32_16x16x32_bf16 v[18:21], v[188:191], v[172:175], v[18:21]
	v_mfma_f32_16x16x32_bf16 v[10:13], v[196:199], v[172:175], v[10:13]
	v_mfma_f32_16x16x32_bf16 v[6:9], v[188:191], v[180:183], v[6:9]
	v_mfma_f32_16x16x32_bf16 v[2:5], v[196:199], v[180:183], v[2:5]
	v_mfma_f32_16x16x32_bf16 v[50:53], v[192:195], v[160:163], v[50:53]
	v_mfma_f32_16x16x32_bf16 v[42:45], v[200:203], v[160:163], v[42:45]
	v_mfma_f32_16x16x32_bf16 v[34:37], v[192:195], v[168:171], v[34:37]
	v_mfma_f32_16x16x32_bf16 v[26:29], v[200:203], v[168:171], v[26:29]
	v_mfma_f32_16x16x32_bf16 v[18:21], v[192:195], v[176:179], v[18:21]
	v_mfma_f32_16x16x32_bf16 v[10:13], v[200:203], v[176:179], v[10:13]
	v_mfma_f32_16x16x32_bf16 v[6:9], v[192:195], v[184:187], v[6:9]
	v_mfma_f32_16x16x32_bf16 v[2:5], v[200:203], v[184:187], v[2:5]
	s_barrier
	s_setprio 0
	s_add_i32 s6, s6, 2
	s_add_u32 s8, s8, 0x100
	s_addc_u32 s9, s9, 0
	s_add_u32 s40, s40, 0x100
	s_addc_u32 s41, s41, 0
	s_cmp_gt_u32 s6, 5
	s_cbranch_scc0 .LBB0_578
	v_mov_b32_e32 v156, v146
	s_lshl_b32 s6, s92, 8
	v_ashrrev_i32_e32 v130, 2, v156
	s_or_b32 s6, s6, s88
	v_and_b32_e32 v130, -4, v130
	v_add_u32_e32 v152, s6, v130
	v_ashrrev_i32_e32 v153, 31, v152
	v_cndmask_b32_e64 v131, 0, 1, s[44:45]
	v_lshl_add_u64 v[154:155], v[152:153], 2, s[42:43]
	v_mov_b32_e32 v130, 1.0
	v_cmp_ne_u32_e64 s[40:41], 1, v131
	s_andn2_b64 vcc, exec, s[44:45]
	v_mov_b32_e32 v134, 1.0
	v_mov_b32_e32 v135, 1.0
	v_mov_b32_e32 v136, 1.0
	v_mov_b32_e32 v137, 1.0
	s_cbranch_vccnz .LBB0_581
	global_load_dwordx4 v[134:137], v[154:155], off

.LBB0_679:
	s_add_u32 s7, s48, 0xffea0080
	s_addc_u32 s78, s49, -1
	s_add_i32 s79, 0, 0x10000
	v_add_u32_e32 v132, s79, v135
	ds_read_b128 v[138:141], v132
	ds_read_b128 v[142:145], v132 offset:1024
	ds_read_b128 v[148:151], v132 offset:2048
	ds_read_b128 v[152:155], v132 offset:3072
	s_cmpk_eq_i32 s6, 0x54
	s_cselect_b32 s91, s45, s78
	s_cselect_b32 s90, s44, s7
	s_cselect_b32 s93, s47, s9
	s_cselect_b32 s92, s46, s8
	v_lshl_add_u64 v[132:133], s[48:49], 0, v[130:131]
	s_add_i32 m0, s56, 0xc000
	ds_read_b128 v[156:159], v136
	ds_read_b128 v[160:163], v136 offset:1024
	ds_read_b128 v[164:167], v136 offset:2048
	ds_read_b128 v[168:171], v136 offset:3072
	ds_read_b128 v[172:175], v136 offset:4096
	ds_read_b128 v[176:179], v136 offset:5120
	ds_read_b128 v[180:183], v136 offset:6144
	ds_read_b128 v[184:187], v136 offset:7168
	global_load_lds_dwordx4 v[132:133], off
	v_lshl_add_u64 v[132:133], v[132:133], 0, s[26:27]
	s_add_i32 m0, s56, 0xe000
	s_nop 0
	global_load_lds_dwordx4 v[132:133], off
	s_waitcnt lgkmcnt(8)
	s_setprio 1
	s_barrier
	s_waitcnt lgkmcnt(0)
	v_mfma_f32_16x16x32_bf16 v[126:129], v[138:141], v[156:159], v[126:129]
	v_mfma_f32_16x16x32_bf16 v[122:125], v[148:151], v[156:159], v[122:125]
	v_mfma_f32_16x16x32_bf16 v[118:121], v[138:141], v[164:167], v[118:121]
	v_mfma_f32_16x16x32_bf16 v[110:113], v[148:151], v[164:167], v[110:113]
	v_mfma_f32_16x16x32_bf16 v[102:105], v[138:141], v[172:175], v[102:105]
	v_mfma_f32_16x16x32_bf16 v[94:97], v[148:151], v[172:175], v[94:97]
	v_mfma_f32_16x16x32_bf16 v[86:89], v[138:141], v[180:183], v[86:89]
	v_mfma_f32_16x16x32_bf16 v[78:81], v[148:151], v[180:183], v[78:81]
	v_mfma_f32_16x16x32_bf16 v[126:129], v[142:145], v[160:163], v[126:129]
	v_mfma_f32_16x16x32_bf16 v[122:125], v[152:155], v[160:163], v[122:125]
	v_mfma_f32_16x16x32_bf16 v[118:121], v[142:145], v[168:171], v[118:121]
	v_mfma_f32_16x16x32_bf16 v[110:113], v[152:155], v[168:171], v[110:113]
	v_mfma_f32_16x16x32_bf16 v[102:105], v[142:145], v[176:179], v[102:105]
	v_mfma_f32_16x16x32_bf16 v[94:97], v[152:155], v[176:179], v[94:97]
	v_mfma_f32_16x16x32_bf16 v[86:89], v[142:145], v[184:187], v[86:89]
	v_mfma_f32_16x16x32_bf16 v[78:81], v[152:155], v[184:187], v[78:81]
	s_barrier
	s_setprio 0
	s_add_i32 s7, 0, 0x14000
	v_add_u32_e32 v132, s7, v135
	s_add_i32 s78, s79, s55
	ds_read_b128 v[188:191], v132
	ds_read_b128 v[192:195], v132 offset:1024
	ds_read_b128 v[196:199], v132 offset:2048
	ds_read_b128 v[200:203], v132 offset:3072
	v_lshl_add_u64 v[132:133], s[92:93], 0, v[0:1]
	s_mov_b32 m0, s78
	v_lshl_add_u64 v[204:205], v[132:133], 0, s[26:27]
	global_load_lds_dwordx4 v[132:133], off
	s_add_i32 m0, s78, 0x2000
	s_nop 0
	global_load_lds_dwordx4 v[204:205], off
	s_setprio 1
	s_barrier
	s_waitcnt lgkmcnt(0)
	v_mfma_f32_16x16x32_bf16 v[114:117], v[188:191], v[156:159], v[114:117]
	v_mfma_f32_16x16x32_bf16 v[106:109], v[196:199], v[156:159], v[106:109]
	v_mfma_f32_16x16x32_bf16 v[98:101], v[188:191], v[164:167], v[98:101]
	v_mfma_f32_16x16x32_bf16 v[90:93], v[196:199], v[164:167], v[90:93]
	v_mfma_f32_16x16x32_bf16 v[82:85], v[188:191], v[172:175], v[82:85]
	v_mfma_f32_16x16x32_bf16 v[74:77], v[196:199], v[172:175], v[74:77]
	v_mfma_f32_16x16x32_bf16 v[70:73], v[188:191], v[180:183], v[70:73]
	v_mfma_f32_16x16x32_bf16 v[66:69], v[196:199], v[180:183], v[66:69]
	v_mfma_f32_16x16x32_bf16 v[114:117], v[192:195], v[160:163], v[114:117]
	v_mfma_f32_16x16x32_bf16 v[106:109], v[200:203], v[160:163], v[106:109]
	v_mfma_f32_16x16x32_bf16 v[98:101], v[192:195], v[168:171], v[98:101]
	v_mfma_f32_16x16x32_bf16 v[90:93], v[200:203], v[168:171], v[90:93]
	v_mfma_f32_16x16x32_bf16 v[82:85], v[192:195], v[176:179], v[82:85]
	v_mfma_f32_16x16x32_bf16 v[74:77], v[200:203], v[176:179], v[74:77]
	v_mfma_f32_16x16x32_bf16 v[70:73], v[192:195], v[184:187], v[70:73]
	v_mfma_f32_16x16x32_bf16 v[66:69], v[200:203], v[184:187], v[66:69]
	s_barrier
	s_setprio 0
	s_mov_b32 m0, s56
	v_lshl_add_u64 v[204:205], s[90:91], 0, v[0:1]
	ds_read_b128 v[156:159], v136 offset:16384
	ds_read_b128 v[160:163], v136 offset:17408
	ds_read_b128 v[164:167], v136 offset:18432
	ds_read_b128 v[168:171], v136 offset:19456
	ds_read_b128 v[172:175], v136 offset:20480
	ds_read_b128 v[176:179], v136 offset:21504
	ds_read_b128 v[180:183], v136 offset:22528
	ds_read_b128 v[184:187], v136 offset:23552
	global_load_lds_dwordx4 v[204:205], off
	v_lshl_add_u64 v[206:207], v[204:205], 0, s[26:27]
	s_mov_b32 m0, s57
	s_nop 0
	global_load_lds_dwordx4 v[206:207], off
	s_setprio 1
	s_barrier
	s_waitcnt lgkmcnt(0)
	v_mfma_f32_16x16x32_bf16 v[62:65], v[138:141], v[156:159], v[62:65]
	v_mfma_f32_16x16x32_bf16 v[58:61], v[148:151], v[156:159], v[58:61]
	v_mfma_f32_16x16x32_bf16 v[54:57], v[138:141], v[164:167], v[54:57]
	v_mfma_f32_16x16x32_bf16 v[46:49], v[148:151], v[164:167], v[46:49]
	v_mfma_f32_16x16x32_bf16 v[38:41], v[138:141], v[172:175], v[38:41]
	v_mfma_f32_16x16x32_bf16 v[30:33], v[148:151], v[172:175], v[30:33]
	v_mfma_f32_16x16x32_bf16 v[22:25], v[138:141], v[180:183], v[22:25]
	v_mfma_f32_16x16x32_bf16 v[14:17], v[148:151], v[180:183], v[14:17]
	v_mfma_f32_16x16x32_bf16 v[62:65], v[142:145], v[160:163], v[62:65]
	v_mfma_f32_16x16x32_bf16 v[58:61], v[152:155], v[160:163], v[58:61]
	v_mfma_f32_16x16x32_bf16 v[54:57], v[142:145], v[168:171], v[54:57]
	v_mfma_f32_16x16x32_bf16 v[46:49], v[152:155], v[168:171], v[46:49]
	v_mfma_f32_16x16x32_bf16 v[38:41], v[142:145], v[176:179], v[38:41]
	v_mfma_f32_16x16x32_bf16 v[30:33], v[152:155], v[176:179], v[30:33]
	v_mfma_f32_16x16x32_bf16 v[22:25], v[142:145], v[184:187], v[22:25]
	v_mfma_f32_16x16x32_bf16 v[14:17], v[152:155], v[184:187], v[14:17]
	s_barrier
	s_setprio 0
	s_add_i32 s7, s7, s55
	v_lshl_add_u64 v[138:139], v[132:133], 0, s[28:29]
	s_mov_b32 m0, s7
	s_nop 0
	global_load_lds_dwordx4 v[138:139], off
	v_lshl_add_u64 v[138:139], v[132:133], 0, s[30:31]
	s_add_i32 m0, s7, 0x2000
	s_nop 0
	global_load_lds_dwordx4 v[138:139], off
	s_waitcnt vmcnt(6)
	s_setprio 1
	s_barrier
	v_mfma_f32_16x16x32_bf16 v[50:53], v[188:191], v[156:159], v[50:53]
	v_mfma_f32_16x16x32_bf16 v[42:45], v[196:199], v[156:159], v[42:45]
	v_mfma_f32_16x16x32_bf16 v[34:37], v[188:191], v[164:167], v[34:37]
	v_mfma_f32_16x16x32_bf16 v[26:29], v[196:199], v[164:167], v[26:29]
	v_mfma_f32_16x16x32_bf16 v[18:21], v[188:191], v[172:175], v[18:21]
	v_mfma_f32_16x16x32_bf16 v[10:13], v[196:199], v[172:175], v[10:13]
	v_mfma_f32_16x16x32_bf16 v[6:9], v[188:191], v[180:183], v[6:9]
	v_mfma_f32_16x16x32_bf16 v[2:5], v[196:199], v[180:183], v[2:5]
	v_mfma_f32_16x16x32_bf16 v[50:53], v[192:195], v[160:163], v[50:53]
	v_mfma_f32_16x16x32_bf16 v[42:45], v[200:203], v[160:163], v[42:45]
	v_mfma_f32_16x16x32_bf16 v[34:37], v[192:195], v[168:171], v[34:37]
	v_mfma_f32_16x16x32_bf16 v[26:29], v[200:203], v[168:171], v[26:29]
	v_mfma_f32_16x16x32_bf16 v[18:21], v[192:195], v[176:179], v[18:21]
	v_mfma_f32_16x16x32_bf16 v[10:13], v[200:203], v[176:179], v[10:13]
	v_mfma_f32_16x16x32_bf16 v[6:9], v[192:195], v[184:187], v[6:9]
	v_mfma_f32_16x16x32_bf16 v[2:5], v[200:203], v[184:187], v[2:5]
	s_barrier
	s_setprio 0
	s_add_i32 s7, 0, 0x18000
	v_add_u32_e32 v137, s7, v135
	ds_read_b128 v[138:141], v137
	ds_read_b128 v[142:145], v137 offset:1024
	ds_read_b128 v[148:151], v137 offset:2048
	ds_read_b128 v[152:155], v137 offset:3072
	s_mov_b32 m0, s58
	v_lshl_add_u64 v[188:189], v[204:205], 0, s[28:29]
	ds_read_b128 v[156:159], v136 offset:32768
	ds_read_b128 v[160:163], v136 offset:33792
	ds_read_b128 v[164:167], v136 offset:34816
	ds_read_b128 v[168:171], v136 offset:35840
	ds_read_b128 v[172:175], v136 offset:36864
	ds_read_b128 v[176:179], v136 offset:37888
	ds_read_b128 v[180:183], v136 offset:38912
	ds_read_b128 v[184:187], v136 offset:39936
	global_load_lds_dwordx4 v[188:189], off
	v_lshl_add_u64 v[188:189], v[204:205], 0, s[30:31]
	s_mov_b32 m0, s59
	s_nop 0
	global_load_lds_dwordx4 v[188:189], off
	s_waitcnt lgkmcnt(8)
	s_setprio 1
	s_barrier
	s_waitcnt lgkmcnt(0)
	v_mfma_f32_16x16x32_bf16 v[126:129], v[138:141], v[156:159], v[126:129]
	v_mfma_f32_16x16x32_bf16 v[122:125], v[148:151], v[156:159], v[122:125]
	v_mfma_f32_16x16x32_bf16 v[118:121], v[138:141], v[164:167], v[118:121]
	v_mfma_f32_16x16x32_bf16 v[110:113], v[148:151], v[164:167], v[110:113]
	v_mfma_f32_16x16x32_bf16 v[102:105], v[138:141], v[172:175], v[102:105]
	v_mfma_f32_16x16x32_bf16 v[94:97], v[148:151], v[172:175], v[94:97]
	v_mfma_f32_16x16x32_bf16 v[86:89], v[138:141], v[180:183], v[86:89]
	v_mfma_f32_16x16x32_bf16 v[78:81], v[148:151], v[180:183], v[78:81]
	v_mfma_f32_16x16x32_bf16 v[126:129], v[142:145], v[160:163], v[126:129]
	v_mfma_f32_16x16x32_bf16 v[122:125], v[152:155], v[160:163], v[122:125]
	v_mfma_f32_16x16x32_bf16 v[118:121], v[142:145], v[168:171], v[118:121]
	v_mfma_f32_16x16x32_bf16 v[110:113], v[152:155], v[168:171], v[110:113]
	v_mfma_f32_16x16x32_bf16 v[102:105], v[142:145], v[176:179], v[102:105]
	v_mfma_f32_16x16x32_bf16 v[94:97], v[152:155], v[176:179], v[94:97]
	v_mfma_f32_16x16x32_bf16 v[86:89], v[142:145], v[184:187], v[86:89]
	v_mfma_f32_16x16x32_bf16 v[78:81], v[152:155], v[184:187], v[78:81]
	s_barrier
	s_setprio 0
	s_add_i32 s78, 0, 0x1c000
	s_add_i32 s7, s7, s55
	v_add_u32_e32 v137, s78, v135
	v_lshl_add_u64 v[206:207], v[132:133], 0, s[34:35]
	s_mov_b32 m0, s7
	ds_read_b128 v[188:191], v137
	ds_read_b128 v[192:195], v137 offset:1024
	ds_read_b128 v[196:199], v137 offset:2048
	ds_read_b128 v[200:203], v137 offset:3072
	global_load_lds_dwordx4 v[206:207], off
	v_lshl_add_u64 v[206:207], v[132:133], 0, s[36:37]
	s_add_i32 m0, s7, 0x2000
	s_nop 0
	global_load_lds_dwordx4 v[206:207], off
	s_setprio 1
	s_barrier
	s_waitcnt lgkmcnt(0)
	v_mfma_f32_16x16x32_bf16 v[114:117], v[188:191], v[156:159], v[114:117]
	v_mfma_f32_16x16x32_bf16 v[106:109], v[196:199], v[156:159], v[106:109]
	v_mfma_f32_16x16x32_bf16 v[98:101], v[188:191], v[164:167], v[98:101]
	v_mfma_f32_16x16x32_bf16 v[90:93], v[196:199], v[164:167], v[90:93]
	v_mfma_f32_16x16x32_bf16 v[82:85], v[188:191], v[172:175], v[82:85]
	v_mfma_f32_16x16x32_bf16 v[74:77], v[196:199], v[172:175], v[74:77]
	v_mfma_f32_16x16x32_bf16 v[70:73], v[188:191], v[180:183], v[70:73]
	v_mfma_f32_16x16x32_bf16 v[66:69], v[196:199], v[180:183], v[66:69]
	v_mfma_f32_16x16x32_bf16 v[114:117], v[192:195], v[160:163], v[114:117]
	v_mfma_f32_16x16x32_bf16 v[106:109], v[200:203], v[160:163], v[106:109]
	v_mfma_f32_16x16x32_bf16 v[98:101], v[192:195], v[168:171], v[98:101]
	v_mfma_f32_16x16x32_bf16 v[90:93], v[200:203], v[168:171], v[90:93]
	v_mfma_f32_16x16x32_bf16 v[82:85], v[192:195], v[176:179], v[82:85]
	v_mfma_f32_16x16x32_bf16 v[74:77], v[200:203], v[176:179], v[74:77]
	v_mfma_f32_16x16x32_bf16 v[70:73], v[192:195], v[184:187], v[70:73]
	v_mfma_f32_16x16x32_bf16 v[66:69], v[200:203], v[184:187], v[66:69]
	s_barrier
	s_setprio 0
	s_mov_b32 m0, s84
	v_lshl_add_u64 v[206:207], v[204:205], 0, s[34:35]
	ds_read_b128 v[156:159], v136 offset:49152
	ds_read_b128 v[160:163], v136 offset:50176
	ds_read_b128 v[164:167], v136 offset:51200
	ds_read_b128 v[168:171], v136 offset:52224
	ds_read_b128 v[172:175], v136 offset:53248
	ds_read_b128 v[176:179], v136 offset:54272
	ds_read_b128 v[180:183], v136 offset:55296
	ds_read_b128 v[184:187], v136 offset:56320
	global_load_lds_dwordx4 v[206:207], off
	v_lshl_add_u64 v[204:205], v[204:205], 0, s[36:37]
	s_mov_b32 m0, s85
	s_nop 0
	global_load_lds_dwordx4 v[204:205], off
	s_setprio 1
	s_barrier
	s_waitcnt lgkmcnt(0)
	v_mfma_f32_16x16x32_bf16 v[62:65], v[138:141], v[156:159], v[62:65]
	v_mfma_f32_16x16x32_bf16 v[58:61], v[148:151], v[156:159], v[58:61]
	v_mfma_f32_16x16x32_bf16 v[54:57], v[138:141], v[164:167], v[54:57]
	v_mfma_f32_16x16x32_bf16 v[46:49], v[148:151], v[164:167], v[46:49]
	v_mfma_f32_16x16x32_bf16 v[38:41], v[138:141], v[172:175], v[38:41]
	v_mfma_f32_16x16x32_bf16 v[30:33], v[148:151], v[172:175], v[30:33]
	v_mfma_f32_16x16x32_bf16 v[22:25], v[138:141], v[180:183], v[22:25]
	v_mfma_f32_16x16x32_bf16 v[14:17], v[148:151], v[180:183], v[14:17]
	v_mfma_f32_16x16x32_bf16 v[62:65], v[142:145], v[160:163], v[62:65]
	v_mfma_f32_16x16x32_bf16 v[58:61], v[152:155], v[160:163], v[58:61]
	v_mfma_f32_16x16x32_bf16 v[54:57], v[142:145], v[168:171], v[54:57]
	v_mfma_f32_16x16x32_bf16 v[46:49], v[152:155], v[168:171], v[46:49]
	v_mfma_f32_16x16x32_bf16 v[38:41], v[142:145], v[176:179], v[38:41]
	v_mfma_f32_16x16x32_bf16 v[30:33], v[152:155], v[176:179], v[30:33]
	v_mfma_f32_16x16x32_bf16 v[22:25], v[142:145], v[184:187], v[22:25]
	v_mfma_f32_16x16x32_bf16 v[14:17], v[152:155], v[184:187], v[14:17]
	s_barrier
	s_setprio 0
	s_add_i32 s7, s78, s55
	v_lshl_add_u64 v[138:139], v[132:133], 0, s[18:19]
	s_mov_b32 m0, s7
	v_lshl_add_u64 v[132:133], v[132:133], 0, s[14:15]
	global_load_lds_dwordx4 v[138:139], off
	s_add_i32 m0, s7, 0x2000
	s_nop 0
	global_load_lds_dwordx4 v[132:133], off
	s_waitcnt vmcnt(6)
	s_setprio 1
	s_barrier
	v_mfma_f32_16x16x32_bf16 v[50:53], v[188:191], v[156:159], v[50:53]
	v_mfma_f32_16x16x32_bf16 v[42:45], v[196:199], v[156:159], v[42:45]
	v_mfma_f32_16x16x32_bf16 v[34:37], v[188:191], v[164:167], v[34:37]
	v_mfma_f32_16x16x32_bf16 v[26:29], v[196:199], v[164:167], v[26:29]
	v_mfma_f32_16x16x32_bf16 v[18:21], v[188:191], v[172:175], v[18:21]
	v_mfma_f32_16x16x32_bf16 v[10:13], v[196:199], v[172:175], v[10:13]
	v_mfma_f32_16x16x32_bf16 v[6:9], v[188:191], v[180:183], v[6:9]
	v_mfma_f32_16x16x32_bf16 v[2:5], v[196:199], v[180:183], v[2:5]
	v_mfma_f32_16x16x32_bf16 v[50:53], v[192:195], v[160:163], v[50:53]
	v_mfma_f32_16x16x32_bf16 v[42:45], v[200:203], v[160:163], v[42:45]
	v_mfma_f32_16x16x32_bf16 v[34:37], v[192:195], v[168:171], v[34:37]
	v_mfma_f32_16x16x32_bf16 v[26:29], v[200:203], v[168:171], v[26:29]
	v_mfma_f32_16x16x32_bf16 v[18:21], v[192:195], v[176:179], v[18:21]
	v_mfma_f32_16x16x32_bf16 v[10:13], v[200:203], v[176:179], v[10:13]
	v_mfma_f32_16x16x32_bf16 v[6:9], v[192:195], v[184:187], v[6:9]
	v_mfma_f32_16x16x32_bf16 v[2:5], v[200:203], v[184:187], v[2:5]
	s_barrier
	s_setprio 0
	s_add_i32 s6, s6, 2
	s_add_u32 s8, s8, 0x100
	s_addc_u32 s9, s9, 0
	s_add_u32 s48, s48, 0x100
	s_addc_u32 s49, s49, 0
	s_cmpk_gt_u32 s6, 0x55
	s_cbranch_scc0 .LBB0_679
	v_mov_b32_e32 v137, v134
	s_lshl_b32 s6, s88, 8
	v_ashrrev_i32_e32 v132, 2, v137
	s_or_b32 s6, s6, s63
	v_and_b32_e32 v132, -4, v132
	v_add_u32_e32 v132, s6, v132
	s_lshl_b32 s6, s87, 8
	s_add_i32 s6, s6, s62
	v_and_or_b32 v188, v137, 15, s6
	v_ashrrev_i32_e32 v189, 31, v188
	v_ashrrev_i32_e32 v133, 31, v132
	v_lshlrev_b64 v[206:207], 13, v[188:189]
	v_or_b32_e32 v156, 16, v188
	v_or_b32_e32 v172, 32, v188
	v_or_b32_e32 v188, 48, v188
	v_lshlrev_b64 v[132:133], 2, v[132:133]
	v_ashrrev_i32_e32 v157, 31, v156
	v_ashrrev_i32_e32 v173, 31, v172
	v_ashrrev_i32_e32 v189, 31, v188
	v_lshl_add_u64 v[204:205], s[40:41], 0, v[132:133]
	v_lshlrev_b64 v[208:209], 13, v[156:157]
	v_lshlrev_b64 v[210:211], 13, v[172:173]
	v_lshlrev_b64 v[212:213], 13, v[188:189]
	v_lshl_add_u64 v[152:153], v[204:205], 0, v[206:207]
	v_lshl_add_u64 v[168:169], v[204:205], 0, v[208:209]
	v_lshl_add_u64 v[184:185], v[204:205], 0, v[210:211]
	v_lshl_add_u64 v[200:201], v[204:205], 0, v[212:213]
	global_load_dwordx4 v[138:141], v[152:153], off
	global_load_dwordx4 v[142:145], v[152:153], off offset:64
	global_load_dwordx4 v[148:151], v[152:153], off offset:512
	s_nop 0
	global_load_dwordx4 v[152:155], v[152:153], off offset:576
	s_nop 0
	global_load_dwordx4 v[156:159], v[168:169], off
	global_load_dwordx4 v[160:163], v[168:169], off offset:64
	global_load_dwordx4 v[164:167], v[168:169], off offset:512
	s_nop 0
	global_load_dwordx4 v[168:171], v[168:169], off offset:576
	s_nop 0
	global_load_dwordx4 v[172:175], v[184:185], off
	global_load_dwordx4 v[176:179], v[184:185], off offset:64
	global_load_dwordx4 v[180:183], v[184:185], off offset:512
	s_nop 0
	global_load_dwordx4 v[184:187], v[184:185], off offset:576
	s_nop 0
	global_load_dwordx4 v[188:191], v[200:201], off
	global_load_dwordx4 v[192:195], v[200:201], off offset:64
	global_load_dwordx4 v[196:199], v[200:201], off offset:512
	s_nop 0
	global_load_dwordx4 v[200:203], v[200:201], off offset:576
	s_waitcnt vmcnt(0)
	v_pk_fma_f32 v[126:127], v[126:127], 0.5, v[138:139] op_sel_hi:[1,0,1]
	v_lshl_add_u64 v[138:139], s[4:5], 0, v[206:207]
	v_lshl_add_u64 v[138:139], v[138:139], 0, v[132:133]
	v_pk_fma_f32 v[116:117], v[116:117], 0.5, v[150:151] op_sel_hi:[1,0,1]
	v_pk_fma_f32 v[114:115], v[114:115], 0.5, v[148:149] op_sel_hi:[1,0,1]
	global_store_dwordx4 v[138:139], v[114:117], off offset:512
	v_pk_fma_f32 v[100:101], v[100:101], 0.5, v[166:167] op_sel_hi:[1,0,1]
	v_pk_fma_f32 v[98:99], v[98:99], 0.5, v[164:165] op_sel_hi:[1,0,1]
	v_lshl_add_u64 v[114:115], s[4:5], 0, v[208:209]
	v_lshl_add_u64 v[114:115], v[114:115], 0, v[132:133]
	global_store_dwordx4 v[114:115], v[98:101], off offset:512
	v_pk_fma_f32 v[84:85], v[84:85], 0.5, v[182:183] op_sel_hi:[1,0,1]
	v_pk_fma_f32 v[82:83], v[82:83], 0.5, v[180:181] op_sel_hi:[1,0,1]
	v_lshl_add_u64 v[98:99], s[4:5], 0, v[210:211]
	v_lshl_add_u64 v[98:99], v[98:99], 0, v[132:133]
	v_pk_fma_f32 v[108:109], v[108:109], 0.5, v[154:155] op_sel_hi:[1,0,1]
	v_pk_fma_f32 v[106:107], v[106:107], 0.5, v[152:153] op_sel_hi:[1,0,1]
	v_pk_fma_f32 v[92:93], v[92:93], 0.5, v[170:171] op_sel_hi:[1,0,1]
	v_pk_fma_f32 v[90:91], v[90:91], 0.5, v[168:169] op_sel_hi:[1,0,1]
	global_store_dwordx4 v[98:99], v[82:85], off offset:512
	v_pk_fma_f32 v[76:77], v[76:77], 0.5, v[186:187] op_sel_hi:[1,0,1]
	v_pk_fma_f32 v[74:75], v[74:75], 0.5, v[184:185] op_sel_hi:[1,0,1]
	v_lshl_add_u64 v[82:83], s[4:5], 0, v[212:213]
	global_store_dwordx4 v[138:139], v[106:109], off offset:576
	global_store_dwordx4 v[114:115], v[90:93], off offset:576
	global_store_dwordx4 v[98:99], v[74:77], off offset:576
	v_pk_fma_f32 v[108:109], v[120:121], 0.5, v[158:159] op_sel_hi:[1,0,1]
	v_pk_fma_f32 v[106:107], v[118:119], 0.5, v[156:157] op_sel_hi:[1,0,1]
	v_pk_fma_f32 v[92:93], v[104:105], 0.5, v[174:175] op_sel_hi:[1,0,1]
	v_pk_fma_f32 v[90:91], v[102:103], 0.5, v[172:173] op_sel_hi:[1,0,1]
	v_pk_fma_f32 v[76:77], v[88:89], 0.5, v[190:191] op_sel_hi:[1,0,1]
	v_pk_fma_f32 v[74:75], v[86:87], 0.5, v[188:189] op_sel_hi:[1,0,1]
	v_lshl_add_u64 v[82:83], v[82:83], 0, v[132:133]
	v_pk_fma_f32 v[128:129], v[128:129], 0.5, v[140:141] op_sel_hi:[1,0,1]
	v_pk_fma_f32 v[124:125], v[124:125], 0.5, v[144:145] op_sel_hi:[1,0,1]
	v_pk_fma_f32 v[122:123], v[122:123], 0.5, v[142:143] op_sel_hi:[1,0,1]
	global_store_dwordx4 v[114:115], v[106:109], off
	global_store_dwordx4 v[98:99], v[90:93], off
	global_store_dwordx4 v[82:83], v[74:77], off
	v_pk_fma_f32 v[108:109], v[112:113], 0.5, v[162:163] op_sel_hi:[1,0,1]
	v_pk_fma_f32 v[106:107], v[110:111], 0.5, v[160:161] op_sel_hi:[1,0,1]
	v_pk_fma_f32 v[92:93], v[96:97], 0.5, v[178:179] op_sel_hi:[1,0,1]
	v_pk_fma_f32 v[90:91], v[94:95], 0.5, v[176:177] op_sel_hi:[1,0,1]
	v_pk_fma_f32 v[76:77], v[80:81], 0.5, v[194:195] op_sel_hi:[1,0,1]
	v_pk_fma_f32 v[74:75], v[78:79], 0.5, v[192:193] op_sel_hi:[1,0,1]
	v_pk_fma_f32 v[72:73], v[72:73], 0.5, v[198:199] op_sel_hi:[1,0,1]
	v_pk_fma_f32 v[70:71], v[70:71], 0.5, v[196:197] op_sel_hi:[1,0,1]
	v_pk_fma_f32 v[68:69], v[68:69], 0.5, v[202:203] op_sel_hi:[1,0,1]
	v_pk_fma_f32 v[66:67], v[66:67], 0.5, v[200:201] op_sel_hi:[1,0,1]
	global_store_dwordx4 v[138:139], v[126:129], off
	global_store_dwordx4 v[138:139], v[122:125], off offset:64
	global_store_dwordx4 v[114:115], v[106:109], off offset:64
	global_store_dwordx4 v[98:99], v[90:93], off offset:64
	global_store_dwordx4 v[82:83], v[74:77], off offset:64
	global_store_dwordx4 v[82:83], v[70:73], off offset:512
	global_store_dwordx4 v[82:83], v[66:69], off offset:576
	s_mov_b64 s[6:7], 0x120000
	v_lshl_add_u64 v[140:141], v[206:207], 0, s[6:7]
	s_mov_b64 s[6:7], 0x140000
	v_lshl_add_u64 v[138:139], v[206:207], 0, s[0:1]
	v_lshl_add_u64 v[142:143], v[206:207], 0, s[6:7]
	v_lshl_add_u64 v[144:145], v[206:207], 0, s[28:29]
	v_lshl_add_u64 v[78:79], v[204:205], 0, v[138:139]
	v_lshl_add_u64 v[94:95], v[204:205], 0, v[140:141]
	v_lshl_add_u64 v[110:111], v[204:205], 0, v[142:143]
	v_lshl_add_u64 v[126:127], v[204:205], 0, v[144:145]
	global_load_dwordx4 v[66:69], v[78:79], off
	global_load_dwordx4 v[70:73], v[78:79], off offset:64
	global_load_dwordx4 v[74:77], v[78:79], off offset:512
	s_nop 0
	global_load_dwordx4 v[78:81], v[78:79], off offset:576
	s_nop 0
	global_load_dwordx4 v[82:85], v[94:95], off
	global_load_dwordx4 v[86:89], v[94:95], off offset:64
	global_load_dwordx4 v[90:93], v[94:95], off offset:512
	s_nop 0
	global_load_dwordx4 v[94:97], v[94:95], off offset:576
	s_nop 0
	global_load_dwordx4 v[98:101], v[110:111], off
	global_load_dwordx4 v[102:105], v[110:111], off offset:64
	global_load_dwordx4 v[106:109], v[110:111], off offset:512
	s_nop 0
	global_load_dwordx4 v[110:113], v[110:111], off offset:576
	s_nop 0
	global_load_dwordx4 v[114:117], v[126:127], off
	global_load_dwordx4 v[118:121], v[126:127], off offset:64
	global_load_dwordx4 v[122:125], v[126:127], off offset:512
	s_nop 0
	global_load_dwordx4 v[126:129], v[126:127], off offset:576
	s_waitcnt vmcnt(0)
	v_pk_fma_f32 v[62:63], v[62:63], 0.5, v[66:67] op_sel_hi:[1,0,1]
	v_lshl_add_u64 v[66:67], s[4:5], 0, v[138:139]
	v_lshl_add_u64 v[66:67], v[66:67], 0, v[132:133]
	v_pk_fma_f32 v[52:53], v[52:53], 0.5, v[76:77] op_sel_hi:[1,0,1]
	v_pk_fma_f32 v[50:51], v[50:51], 0.5, v[74:75] op_sel_hi:[1,0,1]
	global_store_dwordx4 v[66:67], v[50:53], off offset:512
	v_pk_fma_f32 v[36:37], v[36:37], 0.5, v[92:93] op_sel_hi:[1,0,1]
	v_pk_fma_f32 v[34:35], v[34:35], 0.5, v[90:91] op_sel_hi:[1,0,1]
	v_lshl_add_u64 v[50:51], s[4:5], 0, v[140:141]
	v_lshl_add_u64 v[50:51], v[50:51], 0, v[132:133]
	global_store_dwordx4 v[50:51], v[34:37], off offset:512
	v_pk_fma_f32 v[20:21], v[20:21], 0.5, v[108:109] op_sel_hi:[1,0,1]
	v_pk_fma_f32 v[18:19], v[18:19], 0.5, v[106:107] op_sel_hi:[1,0,1]
	v_lshl_add_u64 v[34:35], s[4:5], 0, v[142:143]
	v_lshl_add_u64 v[34:35], v[34:35], 0, v[132:133]
	v_pk_fma_f32 v[44:45], v[44:45], 0.5, v[80:81] op_sel_hi:[1,0,1]
	v_pk_fma_f32 v[42:43], v[42:43], 0.5, v[78:79] op_sel_hi:[1,0,1]
	v_pk_fma_f32 v[28:29], v[28:29], 0.5, v[96:97] op_sel_hi:[1,0,1]
	v_pk_fma_f32 v[26:27], v[26:27], 0.5, v[94:95] op_sel_hi:[1,0,1]
	global_store_dwordx4 v[34:35], v[18:21], off offset:512
	v_pk_fma_f32 v[12:13], v[12:13], 0.5, v[112:113] op_sel_hi:[1,0,1]
	v_pk_fma_f32 v[10:11], v[10:11], 0.5, v[110:111] op_sel_hi:[1,0,1]
	v_lshl_add_u64 v[18:19], s[4:5], 0, v[144:145]
	global_store_dwordx4 v[66:67], v[42:45], off offset:576
	global_store_dwordx4 v[50:51], v[26:29], off offset:576
	global_store_dwordx4 v[34:35], v[10:13], off offset:576
	v_pk_fma_f32 v[44:45], v[56:57], 0.5, v[84:85] op_sel_hi:[1,0,1]
	v_pk_fma_f32 v[42:43], v[54:55], 0.5, v[82:83] op_sel_hi:[1,0,1]
	v_pk_fma_f32 v[28:29], v[40:41], 0.5, v[100:101] op_sel_hi:[1,0,1]
	v_pk_fma_f32 v[26:27], v[38:39], 0.5, v[98:99] op_sel_hi:[1,0,1]
	v_pk_fma_f32 v[12:13], v[24:25], 0.5, v[116:117] op_sel_hi:[1,0,1]
	v_pk_fma_f32 v[10:11], v[22:23], 0.5, v[114:115] op_sel_hi:[1,0,1]
	v_lshl_add_u64 v[18:19], v[18:19], 0, v[132:133]
	v_pk_fma_f32 v[64:65], v[64:65], 0.5, v[68:69] op_sel_hi:[1,0,1]
	v_pk_fma_f32 v[60:61], v[60:61], 0.5, v[72:73] op_sel_hi:[1,0,1]
	v_pk_fma_f32 v[58:59], v[58:59], 0.5, v[70:71] op_sel_hi:[1,0,1]
	global_store_dwordx4 v[50:51], v[42:45], off
	global_store_dwordx4 v[34:35], v[26:29], off
	global_store_dwordx4 v[18:19], v[10:13], off
	v_pk_fma_f32 v[44:45], v[48:49], 0.5, v[88:89] op_sel_hi:[1,0,1]
	v_pk_fma_f32 v[42:43], v[46:47], 0.5, v[86:87] op_sel_hi:[1,0,1]
	v_pk_fma_f32 v[28:29], v[32:33], 0.5, v[104:105] op_sel_hi:[1,0,1]
	v_pk_fma_f32 v[26:27], v[30:31], 0.5, v[102:103] op_sel_hi:[1,0,1]
	v_pk_fma_f32 v[12:13], v[16:17], 0.5, v[120:121] op_sel_hi:[1,0,1]
	v_pk_fma_f32 v[10:11], v[14:15], 0.5, v[118:119] op_sel_hi:[1,0,1]
	v_pk_fma_f32 v[8:9], v[8:9], 0.5, v[124:125] op_sel_hi:[1,0,1]
	v_pk_fma_f32 v[6:7], v[6:7], 0.5, v[122:123] op_sel_hi:[1,0,1]
	v_pk_fma_f32 v[4:5], v[4:5], 0.5, v[128:129] op_sel_hi:[1,0,1]
	v_pk_fma_f32 v[2:3], v[2:3], 0.5, v[126:127] op_sel_hi:[1,0,1]
	global_store_dwordx4 v[66:67], v[62:65], off
	global_store_dwordx4 v[66:67], v[58:61], off offset:64
	global_store_dwordx4 v[50:51], v[42:45], off offset:64
	global_store_dwordx4 v[34:35], v[26:29], off offset:64
	global_store_dwordx4 v[18:19], v[10:13], off offset:64
	global_store_dwordx4 v[18:19], v[6:9], off offset:512
	global_store_dwordx4 v[18:19], v[2:5], off offset:576
	s_and_b64 vcc, exec, s[42:43]
	s_mov_b32 s87, s10
	s_mov_b32 s88, s11
	s_mov_b64 s[8:9], s[46:47]
	s_mov_b64 s[6:7], s[44:45]
	s_movk_i32 s92, 0x4000
	s_movk_i32 s93, 0xf800
	s_movk_i32 s91, 0x60
	s_mov_b32 s78, 0x2a000000
	s_mov_b32 s79, 0x3fffe
	s_mov_b32 s90, 0xc0000
	s_cbranch_vccz .LBB0_672
	s_waitcnt vmcnt(0)
	s_cmpk_gt_u32 s50, 0xff
	s_cbranch_scc1 .LBB0_683
	s_barrier

.LBB0_694:
	s_add_u32 s8, s6, 0x100
	s_addc_u32 s9, s7, 0
	s_add_i32 s78, 0, 0x10000
	v_add_u32_e32 v134, s78, v137
	ds_read_b128 v[140:143], v134
	ds_read_b128 v[148:151], v134 offset:1024
	ds_read_b128 v[152:155], v134 offset:2048
	ds_read_b128 v[156:159], v134 offset:3072
	s_cmp_eq_u32 s87, 28
	s_cselect_b32 s89, s45, s9
	s_cselect_b32 s88, s44, s8
	s_cselect_b32 s91, s47, s86
	s_cselect_b32 s90, s46, s41
	v_lshl_add_u64 v[134:135], s[6:7], 0, v[132:133]
	v_lshl_add_u64 v[144:145], v[134:135], 0, s[16:17]
	s_add_i32 m0, s49, 0xc000
	ds_read_b128 v[160:163], v138
	ds_read_b128 v[164:167], v138 offset:1024
	ds_read_b128 v[168:171], v138 offset:2048
	ds_read_b128 v[172:175], v138 offset:3072
	ds_read_b128 v[176:179], v138 offset:4096
	ds_read_b128 v[180:183], v138 offset:5120
	ds_read_b128 v[184:187], v138 offset:6144
	ds_read_b128 v[188:191], v138 offset:7168
	global_load_lds_dwordx4 v[144:145], off
	v_lshl_add_u64 v[134:135], v[134:135], 0, s[80:81]
	s_add_i32 m0, s49, 0xe000
	s_nop 0
	global_load_lds_dwordx4 v[134:135], off
	s_waitcnt lgkmcnt(8)
	s_setprio 1
	s_barrier
	s_waitcnt lgkmcnt(0)
	v_mfma_f32_16x16x32_bf16 v[126:129], v[140:143], v[160:163], v[126:129]
	v_mfma_f32_16x16x32_bf16 v[122:125], v[152:155], v[160:163], v[122:125]
	v_mfma_f32_16x16x32_bf16 v[110:113], v[140:143], v[168:171], v[110:113]
	v_mfma_f32_16x16x32_bf16 v[106:109], v[152:155], v[168:171], v[106:109]
	v_mfma_f32_16x16x32_bf16 v[94:97], v[140:143], v[176:179], v[94:97]
	v_mfma_f32_16x16x32_bf16 v[90:93], v[152:155], v[176:179], v[90:93]
	v_mfma_f32_16x16x32_bf16 v[78:81], v[140:143], v[184:187], v[78:81]
	v_mfma_f32_16x16x32_bf16 v[74:77], v[152:155], v[184:187], v[74:77]
	v_mfma_f32_16x16x32_bf16 v[126:129], v[148:151], v[164:167], v[126:129]
	v_mfma_f32_16x16x32_bf16 v[122:125], v[156:159], v[164:167], v[122:125]
	v_mfma_f32_16x16x32_bf16 v[110:113], v[148:151], v[172:175], v[110:113]
	v_mfma_f32_16x16x32_bf16 v[106:109], v[156:159], v[172:175], v[106:109]
	v_mfma_f32_16x16x32_bf16 v[94:97], v[148:151], v[180:183], v[94:97]
	v_mfma_f32_16x16x32_bf16 v[90:93], v[156:159], v[180:183], v[90:93]
	v_mfma_f32_16x16x32_bf16 v[78:81], v[148:151], v[188:191], v[78:81]
	v_mfma_f32_16x16x32_bf16 v[74:77], v[156:159], v[188:191], v[74:77]
	s_barrier
	s_setprio 0
	s_add_i32 s6, 0, 0x14000
	v_add_u32_e32 v134, s6, v137
	s_add_i32 s7, s78, s54
	ds_read_b128 v[192:195], v134
	ds_read_b128 v[196:199], v134 offset:1024
	ds_read_b128 v[200:203], v134 offset:2048
	ds_read_b128 v[204:207], v134 offset:3072
	v_lshl_add_u64 v[134:135], s[90:91], 0, v[0:1]
	s_mov_b32 m0, s7
	v_lshl_add_u64 v[144:145], v[134:135], 0, s[60:61]
	global_load_lds_dwordx4 v[134:135], off
	s_add_i32 m0, s7, 0x2000
	s_nop 0
	global_load_lds_dwordx4 v[144:145], off
	s_setprio 1
	s_barrier
	s_waitcnt lgkmcnt(0)
	v_mfma_f32_16x16x32_bf16 v[118:121], v[192:195], v[160:163], v[118:121]
	v_mfma_f32_16x16x32_bf16 v[114:117], v[200:203], v[160:163], v[114:117]
	v_mfma_f32_16x16x32_bf16 v[102:105], v[192:195], v[168:171], v[102:105]
	v_mfma_f32_16x16x32_bf16 v[98:101], v[200:203], v[168:171], v[98:101]
	v_mfma_f32_16x16x32_bf16 v[86:89], v[192:195], v[176:179], v[86:89]
	v_mfma_f32_16x16x32_bf16 v[82:85], v[200:203], v[176:179], v[82:85]
	v_mfma_f32_16x16x32_bf16 v[70:73], v[192:195], v[184:187], v[70:73]
	v_mfma_f32_16x16x32_bf16 v[66:69], v[200:203], v[184:187], v[66:69]
	v_mfma_f32_16x16x32_bf16 v[118:121], v[196:199], v[164:167], v[118:121]
	v_mfma_f32_16x16x32_bf16 v[114:117], v[204:207], v[164:167], v[114:117]
	v_mfma_f32_16x16x32_bf16 v[102:105], v[196:199], v[172:175], v[102:105]
	v_mfma_f32_16x16x32_bf16 v[98:101], v[204:207], v[172:175], v[98:101]
	v_mfma_f32_16x16x32_bf16 v[86:89], v[196:199], v[180:183], v[86:89]
	v_mfma_f32_16x16x32_bf16 v[82:85], v[204:207], v[180:183], v[82:85]
	v_mfma_f32_16x16x32_bf16 v[70:73], v[196:199], v[188:191], v[70:73]
	v_mfma_f32_16x16x32_bf16 v[66:69], v[204:207], v[188:191], v[66:69]
	s_barrier
	s_setprio 0
	s_mov_b32 m0, s49
	v_lshl_add_u64 v[144:145], s[88:89], 0, v[130:131]
	ds_read_b128 v[160:163], v138 offset:16384
	ds_read_b128 v[164:167], v138 offset:17408
	ds_read_b128 v[168:171], v138 offset:18432
	ds_read_b128 v[172:175], v138 offset:19456
	ds_read_b128 v[176:179], v138 offset:20480
	ds_read_b128 v[180:183], v138 offset:21504
	ds_read_b128 v[184:187], v138 offset:22528
	ds_read_b128 v[188:191], v138 offset:23552
	global_load_lds_dwordx4 v[144:145], off
	v_lshl_add_u64 v[208:209], v[144:145], 0, s[60:61]
	s_mov_b32 m0, s55
	s_nop 0
	global_load_lds_dwordx4 v[208:209], off
	s_setprio 1
	s_barrier
	s_waitcnt lgkmcnt(0)
	v_mfma_f32_16x16x32_bf16 v[62:65], v[140:143], v[160:163], v[62:65]
	v_mfma_f32_16x16x32_bf16 v[58:61], v[152:155], v[160:163], v[58:61]
	v_mfma_f32_16x16x32_bf16 v[46:49], v[140:143], v[168:171], v[46:49]
	v_mfma_f32_16x16x32_bf16 v[42:45], v[152:155], v[168:171], v[42:45]
	v_mfma_f32_16x16x32_bf16 v[30:33], v[140:143], v[176:179], v[30:33]
	v_mfma_f32_16x16x32_bf16 v[26:29], v[152:155], v[176:179], v[26:29]
	v_mfma_f32_16x16x32_bf16 v[14:17], v[140:143], v[184:187], v[14:17]
	v_mfma_f32_16x16x32_bf16 v[10:13], v[152:155], v[184:187], v[10:13]
	v_mfma_f32_16x16x32_bf16 v[62:65], v[148:151], v[164:167], v[62:65]
	v_mfma_f32_16x16x32_bf16 v[58:61], v[156:159], v[164:167], v[58:61]
	v_mfma_f32_16x16x32_bf16 v[46:49], v[148:151], v[172:175], v[46:49]
	v_mfma_f32_16x16x32_bf16 v[42:45], v[156:159], v[172:175], v[42:45]
	v_mfma_f32_16x16x32_bf16 v[30:33], v[148:151], v[180:183], v[30:33]
	v_mfma_f32_16x16x32_bf16 v[26:29], v[156:159], v[180:183], v[26:29]
	v_mfma_f32_16x16x32_bf16 v[14:17], v[148:151], v[188:191], v[14:17]
	v_mfma_f32_16x16x32_bf16 v[10:13], v[156:159], v[188:191], v[10:13]
	s_barrier
	s_setprio 0
	s_add_i32 s6, s6, s54
	v_lshl_add_u64 v[140:141], v[134:135], 0, s[20:21]
	s_mov_b32 m0, s6
	s_nop 0
	global_load_lds_dwordx4 v[140:141], off
	v_lshl_add_u64 v[140:141], v[134:135], 0, s[64:65]
	s_add_i32 m0, s6, 0x2000
	s_nop 0
	global_load_lds_dwordx4 v[140:141], off
	s_waitcnt vmcnt(6)
	s_setprio 1
	s_barrier
	v_mfma_f32_16x16x32_bf16 v[54:57], v[192:195], v[160:163], v[54:57]
	v_mfma_f32_16x16x32_bf16 v[50:53], v[200:203], v[160:163], v[50:53]
	v_mfma_f32_16x16x32_bf16 v[38:41], v[192:195], v[168:171], v[38:41]
	v_mfma_f32_16x16x32_bf16 v[34:37], v[200:203], v[168:171], v[34:37]
	v_mfma_f32_16x16x32_bf16 v[22:25], v[192:195], v[176:179], v[22:25]
	v_mfma_f32_16x16x32_bf16 v[18:21], v[200:203], v[176:179], v[18:21]
	v_mfma_f32_16x16x32_bf16 v[6:9], v[192:195], v[184:187], v[6:9]
	v_mfma_f32_16x16x32_bf16 v[2:5], v[200:203], v[184:187], v[2:5]
	v_mfma_f32_16x16x32_bf16 v[54:57], v[196:199], v[164:167], v[54:57]
	v_mfma_f32_16x16x32_bf16 v[50:53], v[204:207], v[164:167], v[50:53]
	v_mfma_f32_16x16x32_bf16 v[38:41], v[196:199], v[172:175], v[38:41]
	v_mfma_f32_16x16x32_bf16 v[34:37], v[204:207], v[172:175], v[34:37]
	v_mfma_f32_16x16x32_bf16 v[22:25], v[196:199], v[180:183], v[22:25]
	v_mfma_f32_16x16x32_bf16 v[18:21], v[204:207], v[180:183], v[18:21]
	v_mfma_f32_16x16x32_bf16 v[6:9], v[196:199], v[188:191], v[6:9]
	v_mfma_f32_16x16x32_bf16 v[2:5], v[204:207], v[188:191], v[2:5]
	s_barrier
	s_setprio 0
	s_add_i32 s6, 0, 0x18000
	v_add_u32_e32 v139, s6, v137
	ds_read_b128 v[140:143], v139
	ds_read_b128 v[148:151], v139 offset:1024
	ds_read_b128 v[152:155], v139 offset:2048
	ds_read_b128 v[156:159], v139 offset:3072
	s_mov_b32 m0, s56
	v_lshl_add_u64 v[192:193], v[144:145], 0, s[20:21]
	ds_read_b128 v[160:163], v138 offset:32768
	ds_read_b128 v[164:167], v138 offset:33792
	ds_read_b128 v[168:171], v138 offset:34816
	ds_read_b128 v[172:175], v138 offset:35840
	ds_read_b128 v[176:179], v138 offset:36864
	ds_read_b128 v[180:183], v138 offset:37888
	ds_read_b128 v[184:187], v138 offset:38912
	ds_read_b128 v[188:191], v138 offset:39936
	global_load_lds_dwordx4 v[192:193], off
	v_lshl_add_u64 v[192:193], v[144:145], 0, s[64:65]
	s_mov_b32 m0, s57
	s_nop 0
	global_load_lds_dwordx4 v[192:193], off
	s_waitcnt lgkmcnt(8)
	s_setprio 1
	s_barrier
	s_waitcnt lgkmcnt(0)
	v_mfma_f32_16x16x32_bf16 v[126:129], v[140:143], v[160:163], v[126:129]
	v_mfma_f32_16x16x32_bf16 v[122:125], v[152:155], v[160:163], v[122:125]
	v_mfma_f32_16x16x32_bf16 v[110:113], v[140:143], v[168:171], v[110:113]
	v_mfma_f32_16x16x32_bf16 v[106:109], v[152:155], v[168:171], v[106:109]
	v_mfma_f32_16x16x32_bf16 v[94:97], v[140:143], v[176:179], v[94:97]
	v_mfma_f32_16x16x32_bf16 v[90:93], v[152:155], v[176:179], v[90:93]
	v_mfma_f32_16x16x32_bf16 v[78:81], v[140:143], v[184:187], v[78:81]
	v_mfma_f32_16x16x32_bf16 v[74:77], v[152:155], v[184:187], v[74:77]
	v_mfma_f32_16x16x32_bf16 v[126:129], v[148:151], v[164:167], v[126:129]
	v_mfma_f32_16x16x32_bf16 v[122:125], v[156:159], v[164:167], v[122:125]
	v_mfma_f32_16x16x32_bf16 v[110:113], v[148:151], v[172:175], v[110:113]
	v_mfma_f32_16x16x32_bf16 v[106:109], v[156:159], v[172:175], v[106:109]
	v_mfma_f32_16x16x32_bf16 v[94:97], v[148:151], v[180:183], v[94:97]
	v_mfma_f32_16x16x32_bf16 v[90:93], v[156:159], v[180:183], v[90:93]
	v_mfma_f32_16x16x32_bf16 v[78:81], v[148:151], v[188:191], v[78:81]
	v_mfma_f32_16x16x32_bf16 v[74:77], v[156:159], v[188:191], v[74:77]
	s_barrier
	s_setprio 0
	s_add_i32 s7, 0, 0x1c000
	s_add_i32 s6, s6, s54
	v_add_u32_e32 v139, s7, v137
	v_lshl_add_u64 v[208:209], v[134:135], 0, s[34:35]
	s_mov_b32 m0, s6
	ds_read_b128 v[192:195], v139
	ds_read_b128 v[196:199], v139 offset:1024
	ds_read_b128 v[200:203], v139 offset:2048
	ds_read_b128 v[204:207], v139 offset:3072
	global_load_lds_dwordx4 v[208:209], off
	v_lshl_add_u64 v[208:209], v[134:135], 0, s[66:67]
	s_add_i32 m0, s6, 0x2000
	s_nop 0
	global_load_lds_dwordx4 v[208:209], off
	s_setprio 1
	s_barrier
	s_waitcnt lgkmcnt(0)
	v_mfma_f32_16x16x32_bf16 v[118:121], v[192:195], v[160:163], v[118:121]
	v_mfma_f32_16x16x32_bf16 v[114:117], v[200:203], v[160:163], v[114:117]
	v_mfma_f32_16x16x32_bf16 v[102:105], v[192:195], v[168:171], v[102:105]
	v_mfma_f32_16x16x32_bf16 v[98:101], v[200:203], v[168:171], v[98:101]
	v_mfma_f32_16x16x32_bf16 v[86:89], v[192:195], v[176:179], v[86:89]
	v_mfma_f32_16x16x32_bf16 v[82:85], v[200:203], v[176:179], v[82:85]
	v_mfma_f32_16x16x32_bf16 v[70:73], v[192:195], v[184:187], v[70:73]
	v_mfma_f32_16x16x32_bf16 v[66:69], v[200:203], v[184:187], v[66:69]
	v_mfma_f32_16x16x32_bf16 v[118:121], v[196:199], v[164:167], v[118:121]
	v_mfma_f32_16x16x32_bf16 v[114:117], v[204:207], v[164:167], v[114:117]
	v_mfma_f32_16x16x32_bf16 v[102:105], v[196:199], v[172:175], v[102:105]
	v_mfma_f32_16x16x32_bf16 v[98:101], v[204:207], v[172:175], v[98:101]
	v_mfma_f32_16x16x32_bf16 v[86:89], v[196:199], v[180:183], v[86:89]
	v_mfma_f32_16x16x32_bf16 v[82:85], v[204:207], v[180:183], v[82:85]
	v_mfma_f32_16x16x32_bf16 v[70:73], v[196:199], v[188:191], v[70:73]
	v_mfma_f32_16x16x32_bf16 v[66:69], v[204:207], v[188:191], v[66:69]
	s_barrier
	s_setprio 0
	s_mov_b32 m0, s58
	v_lshl_add_u64 v[208:209], v[144:145], 0, s[34:35]
	ds_read_b128 v[160:163], v138 offset:49152
	ds_read_b128 v[164:167], v138 offset:50176
	ds_read_b128 v[168:171], v138 offset:51200
	ds_read_b128 v[172:175], v138 offset:52224
	ds_read_b128 v[176:179], v138 offset:53248
	ds_read_b128 v[180:183], v138 offset:54272
	ds_read_b128 v[184:187], v138 offset:55296
	ds_read_b128 v[188:191], v138 offset:56320
	global_load_lds_dwordx4 v[208:209], off
	v_lshl_add_u64 v[144:145], v[144:145], 0, s[66:67]
	s_mov_b32 m0, s59
	s_nop 0
	global_load_lds_dwordx4 v[144:145], off
	s_setprio 1
	s_barrier
	s_waitcnt lgkmcnt(0)
	v_mfma_f32_16x16x32_bf16 v[62:65], v[140:143], v[160:163], v[62:65]
	v_mfma_f32_16x16x32_bf16 v[58:61], v[152:155], v[160:163], v[58:61]
	v_mfma_f32_16x16x32_bf16 v[46:49], v[140:143], v[168:171], v[46:49]
	v_mfma_f32_16x16x32_bf16 v[42:45], v[152:155], v[168:171], v[42:45]
	v_mfma_f32_16x16x32_bf16 v[30:33], v[140:143], v[176:179], v[30:33]
	v_mfma_f32_16x16x32_bf16 v[26:29], v[152:155], v[176:179], v[26:29]
	v_mfma_f32_16x16x32_bf16 v[14:17], v[140:143], v[184:187], v[14:17]
	v_mfma_f32_16x16x32_bf16 v[10:13], v[152:155], v[184:187], v[10:13]
	v_mfma_f32_16x16x32_bf16 v[62:65], v[148:151], v[164:167], v[62:65]
	v_mfma_f32_16x16x32_bf16 v[58:61], v[156:159], v[164:167], v[58:61]
	v_mfma_f32_16x16x32_bf16 v[46:49], v[148:151], v[172:175], v[46:49]
	v_mfma_f32_16x16x32_bf16 v[42:45], v[156:159], v[172:175], v[42:45]
	v_mfma_f32_16x16x32_bf16 v[30:33], v[148:151], v[180:183], v[30:33]
	v_mfma_f32_16x16x32_bf16 v[26:29], v[156:159], v[180:183], v[26:29]
	v_mfma_f32_16x16x32_bf16 v[14:17], v[148:151], v[188:191], v[14:17]
	v_mfma_f32_16x16x32_bf16 v[10:13], v[156:159], v[188:191], v[10:13]
	s_barrier
	s_setprio 0
	s_add_i32 s6, s7, s54
	v_lshl_add_u64 v[140:141], v[134:135], 0, s[16:17]
	s_mov_b32 m0, s6
	v_lshl_add_u64 v[134:135], v[134:135], 0, s[80:81]
	global_load_lds_dwordx4 v[140:141], off
	s_add_i32 m0, s6, 0x2000
	s_nop 0
	global_load_lds_dwordx4 v[134:135], off
	s_waitcnt vmcnt(6)
	s_setprio 1
	s_barrier
	v_mfma_f32_16x16x32_bf16 v[54:57], v[192:195], v[160:163], v[54:57]
	v_mfma_f32_16x16x32_bf16 v[50:53], v[200:203], v[160:163], v[50:53]
	v_mfma_f32_16x16x32_bf16 v[38:41], v[192:195], v[168:171], v[38:41]
	v_mfma_f32_16x16x32_bf16 v[34:37], v[200:203], v[168:171], v[34:37]
	v_mfma_f32_16x16x32_bf16 v[22:25], v[192:195], v[176:179], v[22:25]
	v_mfma_f32_16x16x32_bf16 v[18:21], v[200:203], v[176:179], v[18:21]
	v_mfma_f32_16x16x32_bf16 v[6:9], v[192:195], v[184:187], v[6:9]
	v_mfma_f32_16x16x32_bf16 v[2:5], v[200:203], v[184:187], v[2:5]
	v_mfma_f32_16x16x32_bf16 v[54:57], v[196:199], v[164:167], v[54:57]
	v_mfma_f32_16x16x32_bf16 v[50:53], v[204:207], v[164:167], v[50:53]
	v_mfma_f32_16x16x32_bf16 v[38:41], v[196:199], v[172:175], v[38:41]
	v_mfma_f32_16x16x32_bf16 v[34:37], v[204:207], v[172:175], v[34:37]
	v_mfma_f32_16x16x32_bf16 v[22:25], v[196:199], v[180:183], v[22:25]
	v_mfma_f32_16x16x32_bf16 v[18:21], v[204:207], v[180:183], v[18:21]
	v_mfma_f32_16x16x32_bf16 v[6:9], v[196:199], v[188:191], v[6:9]
	v_mfma_f32_16x16x32_bf16 v[2:5], v[204:207], v[188:191], v[2:5]
	s_barrier
	s_setprio 0
	s_add_i32 s87, s87, 2
	s_add_u32 s41, s41, 0x100
	s_addc_u32 s86, s86, 0
	s_cmp_gt_u32 s87, 29
	s_mov_b64 s[6:7], s[8:9]
	s_cbranch_scc0 .LBB0_694
	v_mov_b32_e32 v134, v136
	s_lshl_b32 s6, s48, 8
	s_add_i32 s6, s6, s10
	v_and_or_b32 v139, v134, 15, s6
	s_lshl_b32 s6, s85, 7
	v_ashrrev_i32_e32 v134, 1, v134
	s_or_b32 s6, s6, s62
	v_and_b32_e32 v134, -8, v134
	v_add_u32_e32 v140, s6, v134
	v_mul_f32_e32 v134, 0xbfb8aa3b, v126
	v_exp_f32_e32 v142, v134
	v_mul_f32_e32 v134, 0xbfb8aa3b, v127
	v_exp_f32_e32 v143, v134
	v_ashrrev_i32_e32 v141, 31, v140
	v_add_f32_e32 v142, 1.0, v142
	v_rcp_f32_e32 v144, v142
	v_add_f32_e32 v142, 1.0, v143
	v_rcp_f32_e32 v145, v142
	v_mov_b64_e32 v[134:135], s[4:5]
	v_mul_f32_e32 v126, v126, v144
	v_mul_f32_e32 v118, v126, v118
	v_mul_f32_e32 v126, v127, v145
	v_mul_f32_e32 v127, 0xbfb8aa3b, v128
	v_exp_f32_e32 v127, v127
	v_mul_f32_e32 v144, 0xbfb8aa3b, v129
	v_exp_f32_e32 v144, v144
	v_mul_f32_e32 v119, v126, v119
	v_add_f32_e32 v126, 1.0, v127
	v_rcp_f32_e32 v126, v126
	v_add_f32_e32 v127, 1.0, v144
	v_mul_f32_e32 v144, 0xbfb8aa3b, v122
	v_rcp_f32_e32 v127, v127
	v_exp_f32_e32 v144, v144
	v_mul_f32_e32 v126, v128, v126
	v_mul_f32_e32 v126, v126, v120
	v_mul_f32_e32 v120, v129, v127
	v_add_f32_e32 v127, 1.0, v144
	v_rcp_f32_e32 v127, v127
	v_mul_f32_e32 v128, 0xbfb8aa3b, v123
	v_mul_f32_e32 v129, v120, v121
	v_exp_f32_e32 v128, v128
	v_mul_f32_e32 v120, v122, v127
	v_mul_f32_e32 v122, v120, v114
	v_mul_f32_e32 v120, 0xbfb8aa3b, v124
	v_exp_f32_e32 v120, v120
	v_mul_f32_e32 v121, 0xbfb8aa3b, v125
	v_exp_f32_e32 v121, v121
	v_add_f32_e32 v114, 1.0, v128
	v_rcp_f32_e32 v114, v114
	v_add_f32_e32 v120, 1.0, v120
	v_rcp_f32_e32 v120, v120
	v_add_f32_e32 v121, 1.0, v121
	v_rcp_f32_e32 v121, v121
	v_mul_f32_e32 v114, v123, v114
	v_mul_f32_e32 v123, v114, v115
	v_mul_f32_e32 v114, v124, v120
	v_mul_f32_e32 v124, v114, v116
	v_mul_f32_e32 v114, v125, v121
	v_mad_i64_i32 v[142:143], s[6:7], v139, s74, v[134:135]
	v_mul_f32_e32 v125, v114, v117
	v_lshlrev_b64 v[114:115], 1, v[140:141]
	v_lshl_add_u64 v[120:121], v[142:143], 0, v[114:115]
	v_cvt_pk_bf16_f32 v116, v118, v119
	v_cvt_pk_bf16_f32 v117, v126, v129
	v_cvt_pk_bf16_f32 v118, v122, v123
	v_cvt_pk_bf16_f32 v119, v124, v125
	global_store_dwordx4 v[120:121], v[116:119], off
	s_and_b64 vcc, exec, s[42:43]
	s_mov_b32 s48, s40
	v_mul_f32_e32 v116, 0xbfb8aa3b, v110
	v_exp_f32_e32 v116, v116
	v_mul_f32_e32 v117, 0xbfb8aa3b, v111
	v_exp_f32_e32 v117, v117
	v_or_b32_e32 v118, 16, v139
	v_add_f32_e32 v116, 1.0, v116
	v_rcp_f32_e32 v119, v116
	v_add_f32_e32 v116, 1.0, v117
	v_rcp_f32_e32 v120, v116
	v_mad_i64_i32 v[116:117], s[6:7], v118, s74, v[134:135]
	v_mul_f32_e32 v110, v110, v119
	v_mul_f32_e32 v110, v110, v102
	v_mul_f32_e32 v102, v111, v120
	v_mul_f32_e32 v111, 0xbfb8aa3b, v112
	v_exp_f32_e32 v111, v111
	v_mul_f32_e32 v118, 0xbfb8aa3b, v113
	v_exp_f32_e32 v118, v118
	v_mul_f32_e32 v119, v102, v103
	v_add_f32_e32 v102, 1.0, v111
	v_rcp_f32_e32 v102, v102
	v_add_f32_e32 v103, 1.0, v118
	v_mul_f32_e32 v111, 0xbfb8aa3b, v106
	v_rcp_f32_e32 v103, v103
	v_exp_f32_e32 v111, v111
	v_mul_f32_e32 v102, v112, v102
	v_mul_f32_e32 v104, v102, v104
	v_mul_f32_e32 v102, v113, v103
	v_add_f32_e32 v103, 1.0, v111
	v_rcp_f32_e32 v103, v103
	v_mul_f32_e32 v111, 0xbfb8aa3b, v107
	v_mul_f32_e32 v105, v102, v105
	v_exp_f32_e32 v111, v111
	v_mul_f32_e32 v102, v106, v103
	v_mul_f32_e32 v106, v102, v98
	v_mul_f32_e32 v102, 0xbfb8aa3b, v108
	v_exp_f32_e32 v102, v102
	v_mul_f32_e32 v103, 0xbfb8aa3b, v109
	v_exp_f32_e32 v103, v103
	v_add_f32_e32 v98, 1.0, v111
	v_rcp_f32_e32 v98, v98
	v_add_f32_e32 v102, 1.0, v102
	v_rcp_f32_e32 v102, v102
	v_add_f32_e32 v103, 1.0, v103
	v_rcp_f32_e32 v103, v103
	v_mul_f32_e32 v98, v107, v98
	v_mul_f32_e32 v107, v98, v99
	v_mul_f32_e32 v98, v108, v102
	v_mul_f32_e32 v108, v98, v100
	v_mul_f32_e32 v98, v109, v103
	v_mul_f32_e32 v101, v98, v101
	v_lshl_add_u64 v[102:103], v[116:117], 0, v[114:115]
	v_cvt_pk_bf16_f32 v98, v110, v119
	v_cvt_pk_bf16_f32 v99, v104, v105
	v_cvt_pk_bf16_f32 v100, v106, v107
	v_cvt_pk_bf16_f32 v101, v108, v101
	global_store_dwordx4 v[102:103], v[98:101], off
	s_mov_b32 s85, s84
	s_mov_b64 s[8:9], s[46:47]
	v_mul_f32_e32 v98, 0xbfb8aa3b, v94
	v_exp_f32_e32 v98, v98
	v_mul_f32_e32 v99, 0xbfb8aa3b, v95
	v_exp_f32_e32 v99, v99
	v_or_b32_e32 v100, 32, v139
	v_add_f32_e32 v98, 1.0, v98
	v_rcp_f32_e32 v101, v98
	v_add_f32_e32 v98, 1.0, v99
	v_rcp_f32_e32 v102, v98
	v_mad_i64_i32 v[98:99], s[6:7], v100, s74, v[134:135]
	v_mul_f32_e32 v94, v94, v101
	v_mul_f32_e32 v94, v94, v86
	v_mul_f32_e32 v86, v95, v102
	v_mul_f32_e32 v95, 0xbfb8aa3b, v96
	v_exp_f32_e32 v95, v95
	v_mul_f32_e32 v100, 0xbfb8aa3b, v97
	v_exp_f32_e32 v100, v100
	v_mul_f32_e32 v101, v86, v87
	v_add_f32_e32 v86, 1.0, v95
	v_rcp_f32_e32 v86, v86
	v_add_f32_e32 v87, 1.0, v100
	v_mul_f32_e32 v95, 0xbfb8aa3b, v90
	v_rcp_f32_e32 v87, v87
	v_exp_f32_e32 v95, v95
	v_mul_f32_e32 v86, v96, v86
	v_mul_f32_e32 v88, v86, v88
	v_mul_f32_e32 v86, v97, v87
	v_add_f32_e32 v87, 1.0, v95
	v_rcp_f32_e32 v87, v87
	v_mul_f32_e32 v95, 0xbfb8aa3b, v91
	v_mul_f32_e32 v89, v86, v89
	v_exp_f32_e32 v95, v95
	v_mul_f32_e32 v86, v90, v87
	v_mul_f32_e32 v90, v86, v82
	v_mul_f32_e32 v86, 0xbfb8aa3b, v92
	v_exp_f32_e32 v86, v86
	v_mul_f32_e32 v87, 0xbfb8aa3b, v93
	v_exp_f32_e32 v87, v87
	v_add_f32_e32 v82, 1.0, v95
	v_rcp_f32_e32 v82, v82
	v_add_f32_e32 v86, 1.0, v86
	v_rcp_f32_e32 v86, v86
	v_add_f32_e32 v87, 1.0, v87
	v_rcp_f32_e32 v87, v87
	v_mul_f32_e32 v82, v91, v82
	v_mul_f32_e32 v91, v82, v83
	v_mul_f32_e32 v82, v92, v86
	v_mul_f32_e32 v92, v82, v84
	v_mul_f32_e32 v82, v93, v87
	v_mul_f32_e32 v85, v82, v85
	v_lshl_add_u64 v[86:87], v[98:99], 0, v[114:115]
	v_cvt_pk_bf16_f32 v82, v94, v101
	v_cvt_pk_bf16_f32 v83, v88, v89
	v_cvt_pk_bf16_f32 v84, v90, v91
	v_cvt_pk_bf16_f32 v85, v92, v85
	global_store_dwordx4 v[86:87], v[82:85], off
	s_nop 1
	v_mul_f32_e32 v82, 0xbfb8aa3b, v78
	v_exp_f32_e32 v82, v82
	v_mul_f32_e32 v83, 0xbfb8aa3b, v79
	v_exp_f32_e32 v83, v83
	v_or_b32_e32 v84, 48, v139
	v_add_f32_e32 v82, 1.0, v82
	v_rcp_f32_e32 v85, v82
	v_add_f32_e32 v82, 1.0, v83
	v_rcp_f32_e32 v86, v82
	v_mad_i64_i32 v[82:83], s[6:7], v84, s74, v[134:135]
	v_mul_f32_e32 v78, v78, v85
	v_mul_f32_e32 v78, v78, v70
	v_mul_f32_e32 v70, v79, v86
	v_mul_f32_e32 v79, 0xbfb8aa3b, v80
	v_exp_f32_e32 v79, v79
	v_mul_f32_e32 v84, 0xbfb8aa3b, v81
	v_exp_f32_e32 v84, v84
	v_mul_f32_e32 v85, v70, v71
	v_add_f32_e32 v70, 1.0, v79
	v_rcp_f32_e32 v70, v70
	v_add_f32_e32 v71, 1.0, v84
	v_mul_f32_e32 v79, 0xbfb8aa3b, v74
	v_rcp_f32_e32 v71, v71
	v_exp_f32_e32 v79, v79
	v_mul_f32_e32 v70, v80, v70
	v_mul_f32_e32 v72, v70, v72
	v_mul_f32_e32 v70, v81, v71
	v_add_f32_e32 v71, 1.0, v79
	v_rcp_f32_e32 v71, v71
	v_mul_f32_e32 v79, 0xbfb8aa3b, v75
	v_mul_f32_e32 v73, v70, v73
	v_exp_f32_e32 v79, v79
	v_mul_f32_e32 v70, v74, v71
	v_mul_f32_e32 v74, v70, v66
	v_mul_f32_e32 v70, 0xbfb8aa3b, v76
	v_exp_f32_e32 v70, v70
	v_mul_f32_e32 v71, 0xbfb8aa3b, v77
	v_exp_f32_e32 v71, v71
	v_add_f32_e32 v66, 1.0, v79
	v_rcp_f32_e32 v66, v66
	v_add_f32_e32 v70, 1.0, v70
	v_rcp_f32_e32 v70, v70
	v_add_f32_e32 v71, 1.0, v71
	v_rcp_f32_e32 v71, v71
	v_mul_f32_e32 v66, v75, v66
	v_mul_f32_e32 v75, v66, v67
	v_mul_f32_e32 v66, v76, v70
	v_mul_f32_e32 v76, v66, v68
	v_mul_f32_e32 v66, v77, v71
	v_mul_f32_e32 v69, v66, v69
	v_lshl_add_u64 v[70:71], v[82:83], 0, v[114:115]
	v_cvt_pk_bf16_f32 v66, v78, v85
	v_cvt_pk_bf16_f32 v67, v72, v73
	v_cvt_pk_bf16_f32 v68, v74, v75
	v_cvt_pk_bf16_f32 v69, v76, v69
	global_store_dwordx4 v[70:71], v[66:69], off
	s_nop 1
	v_mul_f32_e32 v66, 0xbfb8aa3b, v62
	v_exp_f32_e32 v66, v66
	v_mul_f32_e32 v67, 0xbfb8aa3b, v63
	v_exp_f32_e32 v67, v67
	v_add_u32_e32 v68, 0x80, v139
	v_add_f32_e32 v66, 1.0, v66
	v_rcp_f32_e32 v69, v66
	v_add_f32_e32 v66, 1.0, v67
	v_rcp_f32_e32 v70, v66
	v_mad_i64_i32 v[66:67], s[6:7], v68, s74, v[134:135]
	v_mul_f32_e32 v62, v62, v69
	v_mul_f32_e32 v62, v62, v54
	v_mul_f32_e32 v54, v63, v70
	v_mul_f32_e32 v63, 0xbfb8aa3b, v64
	v_exp_f32_e32 v63, v63
	v_mul_f32_e32 v68, 0xbfb8aa3b, v65
	v_exp_f32_e32 v68, v68
	v_mul_f32_e32 v69, v54, v55
	v_add_f32_e32 v54, 1.0, v63
	v_rcp_f32_e32 v54, v54
	v_add_f32_e32 v55, 1.0, v68
	v_mul_f32_e32 v63, 0xbfb8aa3b, v58
	v_rcp_f32_e32 v55, v55
	v_exp_f32_e32 v63, v63
	v_mul_f32_e32 v54, v64, v54
	v_mul_f32_e32 v56, v54, v56
	v_mul_f32_e32 v54, v65, v55
	v_add_f32_e32 v55, 1.0, v63
	v_rcp_f32_e32 v55, v55
	v_mul_f32_e32 v63, 0xbfb8aa3b, v59
	v_mul_f32_e32 v57, v54, v57
	v_exp_f32_e32 v63, v63
	v_mul_f32_e32 v54, v58, v55
	v_mul_f32_e32 v58, v54, v50
	v_mul_f32_e32 v54, 0xbfb8aa3b, v60
	v_exp_f32_e32 v54, v54
	v_mul_f32_e32 v55, 0xbfb8aa3b, v61
	v_exp_f32_e32 v55, v55
	v_add_f32_e32 v50, 1.0, v63
	v_rcp_f32_e32 v50, v50
	v_add_f32_e32 v54, 1.0, v54
	v_rcp_f32_e32 v54, v54
	v_add_f32_e32 v55, 1.0, v55
	v_rcp_f32_e32 v55, v55
	v_mul_f32_e32 v50, v59, v50
	v_mul_f32_e32 v59, v50, v51
	v_mul_f32_e32 v50, v60, v54
	v_mul_f32_e32 v60, v50, v52
	v_mul_f32_e32 v50, v61, v55
	v_mul_f32_e32 v53, v50, v53
	v_lshl_add_u64 v[54:55], v[66:67], 0, v[114:115]
	v_cvt_pk_bf16_f32 v50, v62, v69
	v_cvt_pk_bf16_f32 v51, v56, v57
	v_cvt_pk_bf16_f32 v52, v58, v59
	v_cvt_pk_bf16_f32 v53, v60, v53
	global_store_dwordx4 v[54:55], v[50:53], off
	s_nop 1
	v_mul_f32_e32 v50, 0xbfb8aa3b, v46
	v_exp_f32_e32 v50, v50
	v_mul_f32_e32 v51, 0xbfb8aa3b, v47
	v_exp_f32_e32 v51, v51
	v_add_u32_e32 v52, 0x90, v139
	v_add_f32_e32 v50, 1.0, v50
	v_rcp_f32_e32 v53, v50
	v_add_f32_e32 v50, 1.0, v51
	v_rcp_f32_e32 v54, v50
	v_mad_i64_i32 v[50:51], s[6:7], v52, s74, v[134:135]
	v_mul_f32_e32 v46, v46, v53
	v_mul_f32_e32 v46, v46, v38
	v_mul_f32_e32 v38, v47, v54
	v_mul_f32_e32 v47, 0xbfb8aa3b, v48
	v_exp_f32_e32 v47, v47
	v_mul_f32_e32 v52, 0xbfb8aa3b, v49
	v_exp_f32_e32 v52, v52
	v_mul_f32_e32 v53, v38, v39
	v_add_f32_e32 v38, 1.0, v47
	v_rcp_f32_e32 v38, v38
	v_add_f32_e32 v39, 1.0, v52
	v_mul_f32_e32 v47, 0xbfb8aa3b, v42
	v_rcp_f32_e32 v39, v39
	v_exp_f32_e32 v47, v47
	v_mul_f32_e32 v38, v48, v38
	v_mul_f32_e32 v40, v38, v40
	v_mul_f32_e32 v38, v49, v39
	v_add_f32_e32 v39, 1.0, v47
	v_rcp_f32_e32 v39, v39
	v_mul_f32_e32 v47, 0xbfb8aa3b, v43
	v_mul_f32_e32 v41, v38, v41
	v_exp_f32_e32 v47, v47
	v_mul_f32_e32 v38, v42, v39
	v_mul_f32_e32 v42, v38, v34
	v_mul_f32_e32 v38, 0xbfb8aa3b, v44
	v_exp_f32_e32 v38, v38
	v_mul_f32_e32 v39, 0xbfb8aa3b, v45
	v_exp_f32_e32 v39, v39
	v_add_f32_e32 v34, 1.0, v47
	v_rcp_f32_e32 v34, v34
	v_add_f32_e32 v38, 1.0, v38
	v_rcp_f32_e32 v38, v38
	v_add_f32_e32 v39, 1.0, v39
	v_rcp_f32_e32 v39, v39
	v_mul_f32_e32 v34, v43, v34
	v_mul_f32_e32 v43, v34, v35
	v_mul_f32_e32 v34, v44, v38
	v_mul_f32_e32 v44, v34, v36
	v_mul_f32_e32 v34, v45, v39
	v_mul_f32_e32 v37, v34, v37
	v_lshl_add_u64 v[38:39], v[50:51], 0, v[114:115]
	v_cvt_pk_bf16_f32 v34, v46, v53
	v_cvt_pk_bf16_f32 v35, v40, v41
	v_cvt_pk_bf16_f32 v36, v42, v43
	v_cvt_pk_bf16_f32 v37, v44, v37
	global_store_dwordx4 v[38:39], v[34:37], off
	s_nop 1
	v_mul_f32_e32 v34, 0xbfb8aa3b, v30
	v_exp_f32_e32 v34, v34
	v_mul_f32_e32 v35, 0xbfb8aa3b, v31
	v_exp_f32_e32 v35, v35
	v_add_u32_e32 v36, 0xa0, v139
	v_add_f32_e32 v34, 1.0, v34
	v_rcp_f32_e32 v37, v34
	v_add_f32_e32 v34, 1.0, v35
	v_rcp_f32_e32 v38, v34
	v_mad_i64_i32 v[34:35], s[6:7], v36, s74, v[134:135]
	v_mul_f32_e32 v30, v30, v37
	v_mul_f32_e32 v30, v30, v22
	v_mul_f32_e32 v22, v31, v38
	v_mul_f32_e32 v31, 0xbfb8aa3b, v32
	v_exp_f32_e32 v31, v31
	v_mul_f32_e32 v36, 0xbfb8aa3b, v33
	v_exp_f32_e32 v36, v36
	v_mul_f32_e32 v37, v22, v23
	v_add_f32_e32 v22, 1.0, v31
	v_rcp_f32_e32 v22, v22
	v_add_f32_e32 v23, 1.0, v36
	v_mul_f32_e32 v31, 0xbfb8aa3b, v26
	v_rcp_f32_e32 v23, v23
	v_exp_f32_e32 v31, v31
	v_mul_f32_e32 v22, v32, v22
	v_mul_f32_e32 v24, v22, v24
	v_mul_f32_e32 v22, v33, v23
	v_add_f32_e32 v23, 1.0, v31
	v_rcp_f32_e32 v23, v23
	v_mul_f32_e32 v31, 0xbfb8aa3b, v27
	v_mul_f32_e32 v25, v22, v25
	v_exp_f32_e32 v31, v31
	v_mul_f32_e32 v22, v26, v23
	v_mul_f32_e32 v26, v22, v18
	v_mul_f32_e32 v22, 0xbfb8aa3b, v28
	v_exp_f32_e32 v22, v22
	v_mul_f32_e32 v23, 0xbfb8aa3b, v29
	v_exp_f32_e32 v23, v23
	v_add_f32_e32 v18, 1.0, v31
	v_rcp_f32_e32 v18, v18
	v_add_f32_e32 v22, 1.0, v22
	v_rcp_f32_e32 v22, v22
	v_add_f32_e32 v23, 1.0, v23
	v_rcp_f32_e32 v23, v23
	v_mul_f32_e32 v18, v27, v18
	v_mul_f32_e32 v27, v18, v19
	v_mul_f32_e32 v18, v28, v22
	v_mul_f32_e32 v28, v18, v20
	v_mul_f32_e32 v18, v29, v23
	v_mul_f32_e32 v21, v18, v21
	v_lshl_add_u64 v[22:23], v[34:35], 0, v[114:115]
	v_cvt_pk_bf16_f32 v18, v30, v37
	v_cvt_pk_bf16_f32 v19, v24, v25
	v_cvt_pk_bf16_f32 v20, v26, v27
	v_cvt_pk_bf16_f32 v21, v28, v21
	global_store_dwordx4 v[22:23], v[18:21], off
	s_nop 1
	v_mul_f32_e32 v18, 0xbfb8aa3b, v14
	v_exp_f32_e32 v18, v18
	v_mul_f32_e32 v19, 0xbfb8aa3b, v15
	v_exp_f32_e32 v19, v19
	v_add_u32_e32 v20, 0xb0, v139
	v_add_f32_e32 v18, 1.0, v18
	v_rcp_f32_e32 v21, v18
	v_add_f32_e32 v18, 1.0, v19
	v_rcp_f32_e32 v22, v18
	v_mad_i64_i32 v[18:19], s[6:7], v20, s74, v[134:135]
	v_mul_f32_e32 v14, v14, v21
	v_mul_f32_e32 v14, v14, v6
	v_mul_f32_e32 v6, v15, v22
	v_mul_f32_e32 v15, 0xbfb8aa3b, v16
	v_exp_f32_e32 v15, v15
	v_mul_f32_e32 v20, 0xbfb8aa3b, v17
	v_exp_f32_e32 v20, v20
	v_mul_f32_e32 v21, v6, v7
	v_add_f32_e32 v6, 1.0, v15
	v_rcp_f32_e32 v6, v6
	v_add_f32_e32 v7, 1.0, v20
	v_mul_f32_e32 v15, 0xbfb8aa3b, v10
	v_rcp_f32_e32 v7, v7
	v_exp_f32_e32 v15, v15
	v_mul_f32_e32 v6, v16, v6
	v_mul_f32_e32 v8, v6, v8
	v_mul_f32_e32 v6, v17, v7
	v_add_f32_e32 v7, 1.0, v15
	v_rcp_f32_e32 v7, v7
	v_mul_f32_e32 v15, 0xbfb8aa3b, v11
	v_mul_f32_e32 v9, v6, v9
	v_exp_f32_e32 v15, v15
	v_mul_f32_e32 v6, v10, v7
	v_mul_f32_e32 v10, v6, v2
	v_mul_f32_e32 v6, 0xbfb8aa3b, v12
	v_exp_f32_e32 v6, v6
	v_mul_f32_e32 v7, 0xbfb8aa3b, v13
	v_exp_f32_e32 v7, v7
	v_add_f32_e32 v2, 1.0, v15
	v_rcp_f32_e32 v2, v2
	v_add_f32_e32 v6, 1.0, v6
	v_rcp_f32_e32 v6, v6
	v_add_f32_e32 v7, 1.0, v7
	v_rcp_f32_e32 v7, v7
	v_mul_f32_e32 v2, v11, v2
	v_mul_f32_e32 v11, v2, v3
	v_mul_f32_e32 v2, v12, v6
	v_mul_f32_e32 v12, v2, v4
	v_mul_f32_e32 v2, v13, v7
	v_mul_f32_e32 v5, v2, v5
	v_lshl_add_u64 v[6:7], v[18:19], 0, v[114:115]
	s_mov_b64 s[6:7], s[44:45]
	v_cvt_pk_bf16_f32 v2, v14, v21
	v_cvt_pk_bf16_f32 v3, v8, v9
	v_cvt_pk_bf16_f32 v4, v10, v11
	v_cvt_pk_bf16_f32 v5, v12, v5
	global_store_dwordx4 v[6:7], v[2:5], off
	s_cbranch_vccz .LBB0_691
	s_waitcnt vmcnt(0)
	v_readlane_b32 s0, v255, 8
	v_readlane_b32 s62, v255, 10
	v_readlane_b32 s84, v255, 12
	v_readlane_b32 s44, v255, 26
	s_cmpk_gt_u32 s22, 0xff
	v_readlane_b32 s1, v255, 9
	s_mov_b64 s[58:59], s[92:93]
	v_readlane_b32 s63, v255, 11
	v_readlane_b32 s85, v255, 13
	v_readlane_b32 s45, v255, 27
	s_cbranch_scc1 .LBB0_698
	s_barrier
